# P1 prenorm rows unrolled over a 4-deep ring of row buffers (3-4 rows of loads in flight instead of 1)
# baseline (speedup 1.0000x reference)
; DI unsigned pk2(float lo, float hi) { return pg8::cvt_pk_bf16(lo, hi); }
; DI void prenorm_rows(const float* X, const float* gvec, const float* ada, int sh_off, int sc_off, bf16* U, int row_lo, int row_hi, int gw, int ngw, int lane) {
;     const int nrows = row_hi - row_lo, rpw = (nrows + ngw - 1) / ngw; const int m0 = row_lo + gw * rpw; int m1 = m0 + rpw; if (m1 > row_hi) m1 = row_hi;
;     int curb = -1; f32x4 mul[4], add[4], nx[4];
;     if (m0 < m1) {
; #pragma unroll
;         for (int j = 0; j < 4; ++j) nx[j] = *(const f32x4*)(X + (size_t)m0 * 1024 + 4 * lane + 256 * j);
;     }
;     for (int m = m0; m < m1; ++m) {
;         const int b = m >> 11;
;         f32x4 v[4]; float ss = 0.f;
; #pragma unroll
;         for (int j = 0; j < 4; ++j) v[j] = nx[j];
;         if (m + 1 < m1) {
; #pragma unroll
;             for (int j = 0; j < 4; ++j) nx[j] = *(const f32x4*)(X + (size_t)(m + 1) * 1024 + 4 * lane + 256 * j);
;         }
;         if (b != curb) { curb = b;
; #pragma unroll
;             for (int j = 0; j < 4; ++j) { const int col = 4 * lane + 256 * j; const f32x4 g = *(const f32x4*)(gvec + col), sc = *(const f32x4*)(ada + (size_t)b * 6144 + sc_off + col);
;                 mul[j] = g * (sc + 1.0f); add[j] = *(const f32x4*)(ada + (size_t)b * 6144 + sh_off + col); } }
; #pragma unroll
;         for (int j = 0; j < 4; ++j) ss += (v[j][0] * v[j][0] + v[j][1] * v[j][1]) + (v[j][2] * v[j][2] + v[j][3] * v[j][3]);
;         const float rstd = rsqrtf(wave_sum(ss) * (1.0f / 1024.0f) + 1e-6f);
; #pragma unroll
;         for (int j = 0; j < 4; ++j) { const f32x4 o = (v[j] * rstd) * mul[j] + add[j]; v2u w; w.x = pk2(o[0], o[1]); w.y = pk2(o[2], o[3]);
;             *(v2u*)(U + (size_t)m * 1024 + 4 * lane + 256 * j) = w; }
.Lpn_start:
	global_load_dwordx4 v[164:167], v[68:69], off
	global_load_dwordx4 v[160:163], v[68:69], off offset:1024
	global_load_dwordx4 v[156:159], v[68:69], off offset:2048
	global_load_dwordx4 v[152:155], v[68:69], off offset:3072
	v_lshl_add_u64 v[68:69], v[68:69], 0, s[0:1]
	global_load_dwordx4 v[180:183], v[68:69], off
	global_load_dwordx4 v[176:179], v[68:69], off offset:1024
	global_load_dwordx4 v[172:175], v[68:69], off offset:2048
	global_load_dwordx4 v[168:171], v[68:69], off offset:3072
	v_lshl_add_u64 v[68:69], v[68:69], 0, s[0:1]
	global_load_dwordx4 v[44:47], v[68:69], off
	global_load_dwordx4 v[40:43], v[68:69], off offset:1024
	global_load_dwordx4 v[36:39], v[68:69], off offset:2048
	global_load_dwordx4 v[32:35], v[68:69], off offset:3072
	v_lshl_add_u64 v[68:69], v[68:69], 0, s[0:1]
	s_ashr_i32 s6, s6, 11
	s_mul_i32 s11, s6, 0x6000
	v_readlane_b32 s12, v251, 8
	s_mul_hi_i32 s9, s6, 0x6000
	v_readlane_b32 s13, v251, 9
	s_add_u32 s12, s12, s11
	v_readlane_b32 s14, v251, 10
	s_addc_u32 s13, s13, s9
	v_readlane_b32 s15, v251, 11
	s_add_u32 s14, s12, 0x1000
	s_addc_u32 s15, s13, 0
	s_nop 2
	global_load_dwordx4 v[48:51], v77, s[14:15]
	global_load_dwordx4 v[52:55], v78, s[14:15]
	global_load_dwordx4 v[56:59], v79, s[14:15]
	global_load_dwordx4 v[60:63], v80, s[14:15]
	global_load_dwordx4 v[82:85], v[64:65], off
	global_load_dwordx4 v[86:89], v[64:65], off offset:1024
	global_load_dwordx4 v[90:93], v[64:65], off offset:2048
	global_load_dwordx4 v[94:97], v[64:65], off offset:3072
	global_load_dwordx4 v[28:31], v77, s[12:13]
	global_load_dwordx4 v[24:27], v77, s[12:13] offset:1024
	global_load_dwordx4 v[20:23], v77, s[12:13] offset:2048
	global_load_dwordx4 v[16:19], v77, s[12:13] offset:3072
	s_waitcnt vmcnt(11)
	v_pk_add_f32 v[50:51], v[50:51], 1.0 op_sel_hi:[1,0]
	v_pk_add_f32 v[48:49], v[48:49], 1.0 op_sel_hi:[1,0]
	s_waitcnt vmcnt(10)
	v_pk_add_f32 v[54:55], v[54:55], 1.0 op_sel_hi:[1,0]
	v_pk_add_f32 v[52:53], v[52:53], 1.0 op_sel_hi:[1,0]
	s_waitcnt vmcnt(9)
	v_pk_add_f32 v[58:59], v[58:59], 1.0 op_sel_hi:[1,0]
	v_pk_add_f32 v[56:57], v[56:57], 1.0 op_sel_hi:[1,0]
	s_waitcnt vmcnt(8)
	v_pk_add_f32 v[62:63], v[62:63], 1.0 op_sel_hi:[1,0]
	v_pk_add_f32 v[60:61], v[60:61], 1.0 op_sel_hi:[1,0]
	s_waitcnt vmcnt(7)
	v_pk_mul_f32 v[50:51], v[84:85], v[50:51]
	v_pk_mul_f32 v[48:49], v[82:83], v[48:49]
	s_waitcnt vmcnt(6)
	v_pk_mul_f32 v[54:55], v[88:89], v[54:55]
	v_pk_mul_f32 v[52:53], v[86:87], v[52:53]
	s_waitcnt vmcnt(5)
	v_pk_mul_f32 v[58:59], v[92:93], v[58:59]
	v_pk_mul_f32 v[56:57], v[90:91], v[56:57]
	s_waitcnt vmcnt(4)
	v_pk_mul_f32 v[62:63], v[96:97], v[62:63]
	v_pk_mul_f32 v[60:61], v[94:95], v[60:61]
	s_waitcnt vmcnt(0)
	v_pk_mul_f32 v[82:83], v[8:9], v[8:9]
	v_pk_mul_f32 v[84:85], v[10:11], v[10:11]
	v_pk_mul_f32 v[86:87], v[12:13], v[12:13]
	v_pk_mul_f32 v[88:89], v[14:15], v[14:15]
	v_mov_b32_e32 v90, v86
	v_mov_b32_e32 v91, v89
	v_pk_mov_b32 v[86:87], v[86:87], v[88:89] op_sel:[1,0]
	v_mov_b32_e32 v88, v82
	v_mov_b32_e32 v89, v85
	v_pk_mov_b32 v[82:83], v[82:83], v[84:85] op_sel:[1,0]
	v_pk_add_f32 v[86:87], v[86:87], v[90:91]
	v_pk_add_f32 v[82:83], v[82:83], v[88:89]
	v_pk_add_f32 v[86:87], v[86:87], v[86:87] op_sel_hi:[0,1]
	v_pk_add_f32 v[82:83], v[82:83], v[82:83] op_sel_hi:[0,1]
	v_mul_f32_e32 v82, v4, v4
	v_pk_fma_f32 v[84:85], v[4:5], v[4:5], v[82:83] op_sel_hi:[1,1,0]
	v_mul_f32_e32 v82, v6, v6
	v_pk_fma_f32 v[88:89], v[6:7], v[6:7], v[82:83] op_sel_hi:[1,1,0]
	v_mul_f32_e32 v84, v0, v0
	v_mul_f32_e32 v88, v1, v1
	v_mul_f32_e32 v86, v2, v2
	v_mul_f32_e32 v82, v3, v3
	v_pk_add_f32 v[84:85], v[84:85], v[88:89]
	v_pk_add_f32 v[82:83], v[86:87], v[82:83]
	v_pk_add_f32 v[82:83], v[84:85], v[82:83]
	v_add_f32_e32 v82, v82, v83
	ds_bpermute_b32 v83, v71, v82
	s_waitcnt lgkmcnt(0)
	v_add_f32_e32 v82, v82, v83
	ds_bpermute_b32 v83, v72, v82
	s_waitcnt lgkmcnt(0)
	v_add_f32_e32 v82, v82, v83
	ds_bpermute_b32 v83, v73, v82
	s_waitcnt lgkmcnt(0)
	v_add_f32_e32 v82, v82, v83
	ds_bpermute_b32 v83, v74, v82
	s_waitcnt lgkmcnt(0)
	v_add_f32_e32 v82, v82, v83
	ds_bpermute_b32 v83, v75, v82
	s_waitcnt lgkmcnt(0)
	v_add_f32_e32 v82, v82, v83
	ds_bpermute_b32 v83, v76, v82
	s_waitcnt lgkmcnt(0)
	v_add_f32_e32 v82, v82, v83
	v_fmamk_f32 v82, v82, 0x3a800000, v81
	v_mul_f32_e32 v83, 0x4b800000, v82
	v_cmp_gt_f32_e32 vcc, s7, v82
	s_nop 1
	v_cndmask_b32_e32 v82, v82, v83, vcc
	v_rsq_f32_e32 v82, v82
	s_nop 0
	v_mul_f32_e32 v83, 0x45800000, v82
	v_cndmask_b32_e32 v82, v82, v83, vcc
	v_pk_mul_f32 v[12:13], v[12:13], v[82:83] op_sel_hi:[1,0]
	v_pk_mul_f32 v[8:9], v[8:9], v[82:83] op_sel_hi:[1,0]
	v_pk_mul_f32 v[4:5], v[4:5], v[82:83] op_sel_hi:[1,0]
	v_pk_mul_f32 v[0:1], v[0:1], v[82:83] op_sel_hi:[1,0]
	v_pk_mul_f32 v[14:15], v[14:15], v[82:83] op_sel_hi:[1,0]
	v_pk_mul_f32 v[10:11], v[10:11], v[82:83] op_sel_hi:[1,0]
	v_pk_fma_f32 v[12:13], v[48:49], v[12:13], v[28:29]
	v_pk_fma_f32 v[8:9], v[52:53], v[8:9], v[24:25]
	v_pk_mul_f32 v[6:7], v[6:7], v[82:83] op_sel_hi:[1,0]
	v_pk_fma_f32 v[4:5], v[56:57], v[4:5], v[20:21]
	v_pk_mul_f32 v[2:3], v[2:3], v[82:83] op_sel_hi:[1,0]
	v_pk_fma_f32 v[0:1], v[60:61], v[0:1], v[16:17]
	v_pk_fma_f32 v[14:15], v[50:51], v[14:15], v[30:31]
	v_pk_fma_f32 v[10:11], v[54:55], v[10:11], v[26:27]
	v_cvt_pk_bf16_f32 v12, v12, v13
	v_cvt_pk_bf16_f32 v13, v14, v15
	global_store_dwordx2 v[66:67], v[12:13], off
	v_cvt_pk_bf16_f32 v8, v8, v9
	v_cvt_pk_bf16_f32 v9, v10, v11
	global_store_dwordx2 v[66:67], v[8:9], off offset:512
	v_pk_fma_f32 v[6:7], v[58:59], v[6:7], v[22:23]
	v_cvt_pk_bf16_f32 v4, v4, v5
	v_pk_fma_f32 v[2:3], v[62:63], v[2:3], v[18:19]
	v_cvt_pk_bf16_f32 v5, v6, v7
	global_store_dwordx2 v[66:67], v[4:5], off offset:1024
	v_cvt_pk_bf16_f32 v0, v0, v1
	v_cvt_pk_bf16_f32 v1, v2, v3
	global_store_dwordx2 v[66:67], v[0:1], off offset:1536
	v_lshl_add_u64 v[66:67], v[66:67], 0, s[2:3]
	global_load_dwordx4 v[12:15], v[68:69], off
	global_load_dwordx4 v[8:11], v[68:69], off offset:1024
	global_load_dwordx4 v[4:7], v[68:69], off offset:2048
	global_load_dwordx4 v[0:3], v[68:69], off offset:3072
	v_lshl_add_u64 v[68:69], v[68:69], 0, s[0:1]
	s_waitcnt vmcnt(28)
; DI unsigned pk2(float lo, float hi) { return pg8::cvt_pk_bf16(lo, hi); }
; DI void prenorm_rows(const float* X, const float* gvec, const float* ada, int sh_off, int sc_off, bf16* U, int row_lo, int row_hi, int gw, int ngw, int lane) {
;     ...
;         f32x4 v[4]; float ss = 0.f;
; #pragma unroll
;         for (int j = 0; j < 4; ++j) v[j] = nx[j];
;         if (m + 1 < m1) {
; #pragma unroll
;             for (int j = 0; j < 4; ++j) nx[j] = *(const f32x4*)(X + (size_t)(m + 1) * 1024 + 4 * lane + 256 * j);
;         }
;         if (b != curb) { curb = b;
; #pragma unroll
;             for (int j = 0; j < 4; ++j) { const int col = 4 * lane + 256 * j; const f32x4 g = *(const f32x4*)(gvec + col), sc = *(const f32x4*)(ada + (size_t)b * 6144 + sc_off + col);
;                 mul[j] = g * (sc + 1.0f); add[j] = *(const f32x4*)(ada + (size_t)b * 6144 + sh_off + col); } }
; #pragma unroll
;         for (int j = 0; j < 4; ++j) ss += (v[j][0] * v[j][0] + v[j][1] * v[j][1]) + (v[j][2] * v[j][2] + v[j][3] * v[j][3]);
;         const float rstd = rsqrtf(wave_sum(ss) * (1.0f / 1024.0f) + 1e-6f);
; #pragma unroll
;         for (int j = 0; j < 4; ++j) { const f32x4 o = (v[j] * rstd) * mul[j] + add[j]; v2u w; w.x = pk2(o[0], o[1]); w.y = pk2(o[2], o[3]);
;             *(v2u*)(U + (size_t)m * 1024 + 4 * lane + 256 * j) = w; }
	v_pk_mul_f32 v[82:83], v[160:161], v[160:161]
	v_pk_mul_f32 v[84:85], v[162:163], v[162:163]
	v_pk_mul_f32 v[86:87], v[164:165], v[164:165]
	v_pk_mul_f32 v[88:89], v[166:167], v[166:167]
	v_mov_b32_e32 v90, v86
	v_mov_b32_e32 v91, v89
	v_pk_mov_b32 v[86:87], v[86:87], v[88:89] op_sel:[1,0]
	v_mov_b32_e32 v88, v82
	v_mov_b32_e32 v89, v85
	v_pk_mov_b32 v[82:83], v[82:83], v[84:85] op_sel:[1,0]
	v_pk_add_f32 v[86:87], v[86:87], v[90:91]
	v_pk_add_f32 v[82:83], v[82:83], v[88:89]
	v_pk_add_f32 v[86:87], v[86:87], v[86:87] op_sel_hi:[0,1]
	v_pk_add_f32 v[82:83], v[82:83], v[82:83] op_sel_hi:[0,1]
	v_mul_f32_e32 v82, v156, v156
	v_pk_fma_f32 v[84:85], v[156:157], v[156:157], v[82:83] op_sel_hi:[1,1,0]
	v_mul_f32_e32 v82, v158, v158
	v_pk_fma_f32 v[88:89], v[158:159], v[158:159], v[82:83] op_sel_hi:[1,1,0]
	v_mul_f32_e32 v84, v152, v152
	v_mul_f32_e32 v88, v153, v153
	v_mul_f32_e32 v86, v154, v154
	v_mul_f32_e32 v82, v155, v155
	v_pk_add_f32 v[84:85], v[84:85], v[88:89]
	v_pk_add_f32 v[82:83], v[86:87], v[82:83]
	v_pk_add_f32 v[82:83], v[84:85], v[82:83]
	v_add_f32_e32 v82, v82, v83
	ds_bpermute_b32 v83, v71, v82
	s_waitcnt lgkmcnt(0)
	v_add_f32_e32 v82, v82, v83
	ds_bpermute_b32 v83, v72, v82
	s_waitcnt lgkmcnt(0)
	v_add_f32_e32 v82, v82, v83
	ds_bpermute_b32 v83, v73, v82
	s_waitcnt lgkmcnt(0)
	v_add_f32_e32 v82, v82, v83
	ds_bpermute_b32 v83, v74, v82
	s_waitcnt lgkmcnt(0)
	v_add_f32_e32 v82, v82, v83
	ds_bpermute_b32 v83, v75, v82
	s_waitcnt lgkmcnt(0)
	v_add_f32_e32 v82, v82, v83
	ds_bpermute_b32 v83, v76, v82
	s_waitcnt lgkmcnt(0)
	v_add_f32_e32 v82, v82, v83
	v_fmamk_f32 v82, v82, 0x3a800000, v81
	v_mul_f32_e32 v83, 0x4b800000, v82
	v_cmp_gt_f32_e32 vcc, s7, v82
	s_nop 1
	v_cndmask_b32_e32 v82, v82, v83, vcc
	v_rsq_f32_e32 v82, v82
	s_nop 0
	v_mul_f32_e32 v83, 0x45800000, v82
	v_cndmask_b32_e32 v82, v82, v83, vcc
	v_pk_mul_f32 v[164:165], v[164:165], v[82:83] op_sel_hi:[1,0]
	v_pk_mul_f32 v[160:161], v[160:161], v[82:83] op_sel_hi:[1,0]
	v_pk_mul_f32 v[156:157], v[156:157], v[82:83] op_sel_hi:[1,0]
	v_pk_mul_f32 v[152:153], v[152:153], v[82:83] op_sel_hi:[1,0]
	v_pk_mul_f32 v[166:167], v[166:167], v[82:83] op_sel_hi:[1,0]
	v_pk_mul_f32 v[162:163], v[162:163], v[82:83] op_sel_hi:[1,0]
	v_pk_fma_f32 v[164:165], v[48:49], v[164:165], v[28:29]
	v_pk_fma_f32 v[160:161], v[52:53], v[160:161], v[24:25]
	v_pk_mul_f32 v[158:159], v[158:159], v[82:83] op_sel_hi:[1,0]
	v_pk_fma_f32 v[156:157], v[56:57], v[156:157], v[20:21]
	v_pk_mul_f32 v[154:155], v[154:155], v[82:83] op_sel_hi:[1,0]
	v_pk_fma_f32 v[152:153], v[60:61], v[152:153], v[16:17]
	v_pk_fma_f32 v[166:167], v[50:51], v[166:167], v[30:31]
	v_pk_fma_f32 v[162:163], v[54:55], v[162:163], v[26:27]
	v_cvt_pk_bf16_f32 v164, v164, v165
	v_cvt_pk_bf16_f32 v165, v166, v167
	global_store_dwordx2 v[66:67], v[164:165], off
	v_cvt_pk_bf16_f32 v160, v160, v161
	v_cvt_pk_bf16_f32 v161, v162, v163
	global_store_dwordx2 v[66:67], v[160:161], off offset:512
	v_pk_fma_f32 v[158:159], v[58:59], v[158:159], v[22:23]
	v_cvt_pk_bf16_f32 v156, v156, v157
	v_pk_fma_f32 v[154:155], v[62:63], v[154:155], v[18:19]
	v_cvt_pk_bf16_f32 v157, v158, v159
	global_store_dwordx2 v[66:67], v[156:157], off offset:1024
	v_cvt_pk_bf16_f32 v152, v152, v153
	v_cvt_pk_bf16_f32 v153, v154, v155
	global_store_dwordx2 v[66:67], v[152:153], off offset:1536
	v_lshl_add_u64 v[66:67], v[66:67], 0, s[2:3]
	global_load_dwordx4 v[164:167], v[68:69], off
	global_load_dwordx4 v[160:163], v[68:69], off offset:1024
	global_load_dwordx4 v[156:159], v[68:69], off offset:2048
	global_load_dwordx4 v[152:155], v[68:69], off offset:3072
	v_lshl_add_u64 v[68:69], v[68:69], 0, s[0:1]
	s_waitcnt vmcnt(32)
	v_pk_mul_f32 v[82:83], v[176:177], v[176:177]
	v_pk_mul_f32 v[84:85], v[178:179], v[178:179]
	v_pk_mul_f32 v[86:87], v[180:181], v[180:181]
	v_pk_mul_f32 v[88:89], v[182:183], v[182:183]
	v_mov_b32_e32 v90, v86
	v_mov_b32_e32 v91, v89
	v_pk_mov_b32 v[86:87], v[86:87], v[88:89] op_sel:[1,0]
	v_mov_b32_e32 v88, v82
	v_mov_b32_e32 v89, v85
	v_pk_mov_b32 v[82:83], v[82:83], v[84:85] op_sel:[1,0]
	v_pk_add_f32 v[86:87], v[86:87], v[90:91]
	v_pk_add_f32 v[82:83], v[82:83], v[88:89]
	v_pk_add_f32 v[86:87], v[86:87], v[86:87] op_sel_hi:[0,1]
	v_pk_add_f32 v[82:83], v[82:83], v[82:83] op_sel_hi:[0,1]
	v_mul_f32_e32 v82, v172, v172
	v_pk_fma_f32 v[84:85], v[172:173], v[172:173], v[82:83] op_sel_hi:[1,1,0]
	v_mul_f32_e32 v82, v174, v174
	v_pk_fma_f32 v[88:89], v[174:175], v[174:175], v[82:83] op_sel_hi:[1,1,0]
	v_mul_f32_e32 v84, v168, v168
	v_mul_f32_e32 v88, v169, v169
	v_mul_f32_e32 v86, v170, v170
	v_mul_f32_e32 v82, v171, v171
	v_pk_add_f32 v[84:85], v[84:85], v[88:89]
	v_pk_add_f32 v[82:83], v[86:87], v[82:83]
	v_pk_add_f32 v[82:83], v[84:85], v[82:83]
	v_add_f32_e32 v82, v82, v83
	ds_bpermute_b32 v83, v71, v82
	s_waitcnt lgkmcnt(0)
	v_add_f32_e32 v82, v82, v83
	ds_bpermute_b32 v83, v72, v82
	s_waitcnt lgkmcnt(0)
	v_add_f32_e32 v82, v82, v83
	ds_bpermute_b32 v83, v73, v82
	s_waitcnt lgkmcnt(0)
	v_add_f32_e32 v82, v82, v83
	ds_bpermute_b32 v83, v74, v82
	s_waitcnt lgkmcnt(0)
	v_add_f32_e32 v82, v82, v83
	ds_bpermute_b32 v83, v75, v82
	s_waitcnt lgkmcnt(0)
	v_add_f32_e32 v82, v82, v83
	ds_bpermute_b32 v83, v76, v82
	s_waitcnt lgkmcnt(0)
; DI unsigned pk2(float lo, float hi) { return pg8::cvt_pk_bf16(lo, hi); }
; DI void prenorm_rows(const float* X, const float* gvec, const float* ada, int sh_off, int sc_off, bf16* U, int row_lo, int row_hi, int gw, int ngw, int lane) {
;     ...
;         f32x4 v[4]; float ss = 0.f;
; #pragma unroll
;         for (int j = 0; j < 4; ++j) v[j] = nx[j];
;         if (m + 1 < m1) {
; #pragma unroll
;             for (int j = 0; j < 4; ++j) nx[j] = *(const f32x4*)(X + (size_t)(m + 1) * 1024 + 4 * lane + 256 * j);
;         }
;         if (b != curb) { curb = b;
; #pragma unroll
;             for (int j = 0; j < 4; ++j) { const int col = 4 * lane + 256 * j; const f32x4 g = *(const f32x4*)(gvec + col), sc = *(const f32x4*)(ada + (size_t)b * 6144 + sc_off + col);
;                 mul[j] = g * (sc + 1.0f); add[j] = *(const f32x4*)(ada + (size_t)b * 6144 + sh_off + col); } }
; #pragma unroll
;         for (int j = 0; j < 4; ++j) ss += (v[j][0] * v[j][0] + v[j][1] * v[j][1]) + (v[j][2] * v[j][2] + v[j][3] * v[j][3]);
;         const float rstd = rsqrtf(wave_sum(ss) * (1.0f / 1024.0f) + 1e-6f);
; #pragma unroll
;         for (int j = 0; j < 4; ++j) { const f32x4 o = (v[j] * rstd) * mul[j] + add[j]; v2u w; w.x = pk2(o[0], o[1]); w.y = pk2(o[2], o[3]);
;             *(v2u*)(U + (size_t)m * 1024 + 4 * lane + 256 * j) = w; }
	v_add_f32_e32 v82, v82, v83
	v_fmamk_f32 v82, v82, 0x3a800000, v81
	v_mul_f32_e32 v83, 0x4b800000, v82
	v_cmp_gt_f32_e32 vcc, s7, v82
	s_nop 1
	v_cndmask_b32_e32 v82, v82, v83, vcc
	v_rsq_f32_e32 v82, v82
	s_nop 0
	v_mul_f32_e32 v83, 0x45800000, v82
	v_cndmask_b32_e32 v82, v82, v83, vcc
	v_pk_mul_f32 v[180:181], v[180:181], v[82:83] op_sel_hi:[1,0]
	v_pk_mul_f32 v[176:177], v[176:177], v[82:83] op_sel_hi:[1,0]
	v_pk_mul_f32 v[172:173], v[172:173], v[82:83] op_sel_hi:[1,0]
	v_pk_mul_f32 v[168:169], v[168:169], v[82:83] op_sel_hi:[1,0]
	v_pk_mul_f32 v[182:183], v[182:183], v[82:83] op_sel_hi:[1,0]
	v_pk_mul_f32 v[178:179], v[178:179], v[82:83] op_sel_hi:[1,0]
	v_pk_fma_f32 v[180:181], v[48:49], v[180:181], v[28:29]
	v_pk_fma_f32 v[176:177], v[52:53], v[176:177], v[24:25]
	v_pk_mul_f32 v[174:175], v[174:175], v[82:83] op_sel_hi:[1,0]
	v_pk_fma_f32 v[172:173], v[56:57], v[172:173], v[20:21]
	v_pk_mul_f32 v[170:171], v[170:171], v[82:83] op_sel_hi:[1,0]
	v_pk_fma_f32 v[168:169], v[60:61], v[168:169], v[16:17]
	v_pk_fma_f32 v[182:183], v[50:51], v[182:183], v[30:31]
	v_pk_fma_f32 v[178:179], v[54:55], v[178:179], v[26:27]
	v_cvt_pk_bf16_f32 v180, v180, v181
	v_cvt_pk_bf16_f32 v181, v182, v183
	global_store_dwordx2 v[66:67], v[180:181], off
	v_cvt_pk_bf16_f32 v176, v176, v177
	v_cvt_pk_bf16_f32 v177, v178, v179
	global_store_dwordx2 v[66:67], v[176:177], off offset:512
	v_pk_fma_f32 v[174:175], v[58:59], v[174:175], v[22:23]
	v_cvt_pk_bf16_f32 v172, v172, v173
	v_pk_fma_f32 v[170:171], v[62:63], v[170:171], v[18:19]
	v_cvt_pk_bf16_f32 v173, v174, v175
	global_store_dwordx2 v[66:67], v[172:173], off offset:1024
	v_cvt_pk_bf16_f32 v168, v168, v169
	v_cvt_pk_bf16_f32 v169, v170, v171
	global_store_dwordx2 v[66:67], v[168:169], off offset:1536
	v_lshl_add_u64 v[66:67], v[66:67], 0, s[2:3]
	global_load_dwordx4 v[180:183], v[68:69], off
	global_load_dwordx4 v[176:179], v[68:69], off offset:1024
	global_load_dwordx4 v[172:175], v[68:69], off offset:2048
	global_load_dwordx4 v[168:171], v[68:69], off offset:3072
	v_lshl_add_u64 v[68:69], v[68:69], 0, s[0:1]
	s_waitcnt vmcnt(36)
	v_pk_mul_f32 v[82:83], v[40:41], v[40:41]
	v_pk_mul_f32 v[84:85], v[42:43], v[42:43]
	v_pk_mul_f32 v[86:87], v[44:45], v[44:45]
	v_pk_mul_f32 v[88:89], v[46:47], v[46:47]
	v_mov_b32_e32 v90, v86
	v_mov_b32_e32 v91, v89
	v_pk_mov_b32 v[86:87], v[86:87], v[88:89] op_sel:[1,0]
	v_mov_b32_e32 v88, v82
	v_mov_b32_e32 v89, v85
	v_pk_mov_b32 v[82:83], v[82:83], v[84:85] op_sel:[1,0]
	v_pk_add_f32 v[86:87], v[86:87], v[90:91]
	v_pk_add_f32 v[82:83], v[82:83], v[88:89]
	v_pk_add_f32 v[86:87], v[86:87], v[86:87] op_sel_hi:[0,1]
	v_pk_add_f32 v[82:83], v[82:83], v[82:83] op_sel_hi:[0,1]
	v_mul_f32_e32 v82, v36, v36
	v_pk_fma_f32 v[84:85], v[36:37], v[36:37], v[82:83] op_sel_hi:[1,1,0]
	v_mul_f32_e32 v82, v38, v38
	v_pk_fma_f32 v[88:89], v[38:39], v[38:39], v[82:83] op_sel_hi:[1,1,0]
	v_mul_f32_e32 v84, v32, v32
	v_mul_f32_e32 v88, v33, v33
	v_mul_f32_e32 v86, v34, v34
	v_mul_f32_e32 v82, v35, v35
	v_pk_add_f32 v[84:85], v[84:85], v[88:89]
	v_pk_add_f32 v[82:83], v[86:87], v[82:83]
	v_pk_add_f32 v[82:83], v[84:85], v[82:83]
	v_add_f32_e32 v82, v82, v83
	ds_bpermute_b32 v83, v71, v82
	s_waitcnt lgkmcnt(0)
	v_add_f32_e32 v82, v82, v83
	ds_bpermute_b32 v83, v72, v82
	s_waitcnt lgkmcnt(0)
	v_add_f32_e32 v82, v82, v83
	ds_bpermute_b32 v83, v73, v82
	s_waitcnt lgkmcnt(0)
	v_add_f32_e32 v82, v82, v83
	ds_bpermute_b32 v83, v74, v82
	s_waitcnt lgkmcnt(0)
	v_add_f32_e32 v82, v82, v83
	ds_bpermute_b32 v83, v75, v82
	s_waitcnt lgkmcnt(0)
	v_add_f32_e32 v82, v82, v83
	ds_bpermute_b32 v83, v76, v82
	s_waitcnt lgkmcnt(0)
	v_add_f32_e32 v82, v82, v83
	v_fmamk_f32 v82, v82, 0x3a800000, v81
	v_mul_f32_e32 v83, 0x4b800000, v82
	v_cmp_gt_f32_e32 vcc, s7, v82
	s_nop 1
	v_cndmask_b32_e32 v82, v82, v83, vcc
	v_rsq_f32_e32 v82, v82
	s_nop 0
	v_mul_f32_e32 v83, 0x45800000, v82
	v_cndmask_b32_e32 v82, v82, v83, vcc
	v_pk_mul_f32 v[44:45], v[44:45], v[82:83] op_sel_hi:[1,0]
	v_pk_mul_f32 v[40:41], v[40:41], v[82:83] op_sel_hi:[1,0]
	v_pk_mul_f32 v[36:37], v[36:37], v[82:83] op_sel_hi:[1,0]
	v_pk_mul_f32 v[32:33], v[32:33], v[82:83] op_sel_hi:[1,0]
	v_pk_mul_f32 v[46:47], v[46:47], v[82:83] op_sel_hi:[1,0]
	v_pk_mul_f32 v[42:43], v[42:43], v[82:83] op_sel_hi:[1,0]
	v_pk_fma_f32 v[44:45], v[48:49], v[44:45], v[28:29]
	v_pk_fma_f32 v[40:41], v[52:53], v[40:41], v[24:25]
	v_pk_mul_f32 v[38:39], v[38:39], v[82:83] op_sel_hi:[1,0]
	v_pk_fma_f32 v[36:37], v[56:57], v[36:37], v[20:21]
	v_pk_mul_f32 v[34:35], v[34:35], v[82:83] op_sel_hi:[1,0]
	v_pk_fma_f32 v[32:33], v[60:61], v[32:33], v[16:17]
	v_pk_fma_f32 v[46:47], v[50:51], v[46:47], v[30:31]
	v_pk_fma_f32 v[42:43], v[54:55], v[42:43], v[26:27]
	v_cvt_pk_bf16_f32 v44, v44, v45
	v_cvt_pk_bf16_f32 v45, v46, v47
	global_store_dwordx2 v[66:67], v[44:45], off
	v_cvt_pk_bf16_f32 v40, v40, v41
	v_cvt_pk_bf16_f32 v41, v42, v43
	global_store_dwordx2 v[66:67], v[40:41], off offset:512
	v_pk_fma_f32 v[38:39], v[58:59], v[38:39], v[22:23]
	v_cvt_pk_bf16_f32 v36, v36, v37
	v_pk_fma_f32 v[34:35], v[62:63], v[34:35], v[18:19]
	v_cvt_pk_bf16_f32 v37, v38, v39
	global_store_dwordx2 v[66:67], v[36:37], off offset:1024
	v_cvt_pk_bf16_f32 v32, v32, v33
	v_cvt_pk_bf16_f32 v33, v34, v35
	global_store_dwordx2 v[66:67], v[32:33], off offset:1536
	v_lshl_add_u64 v[66:67], v[66:67], 0, s[2:3]
	global_load_dwordx4 v[44:47], v[68:69], off
	global_load_dwordx4 v[40:43], v[68:69], off offset:1024
	global_load_dwordx4 v[36:39], v[68:69], off offset:2048
	global_load_dwordx4 v[32:35], v[68:69], off offset:3072
	v_lshl_add_u64 v[68:69], v[68:69], 0, s[0:1]
	s_waitcnt vmcnt(24)
; DI unsigned pk2(float lo, float hi) { return pg8::cvt_pk_bf16(lo, hi); }
; DI void prenorm_rows(const float* X, const float* gvec, const float* ada, int sh_off, int sc_off, bf16* U, int row_lo, int row_hi, int gw, int ngw, int lane) {
;     ...
;         f32x4 v[4]; float ss = 0.f;
; #pragma unroll
;         for (int j = 0; j < 4; ++j) v[j] = nx[j];
;         if (m + 1 < m1) {
; #pragma unroll
;             for (int j = 0; j < 4; ++j) nx[j] = *(const f32x4*)(X + (size_t)(m + 1) * 1024 + 4 * lane + 256 * j);
;         }
;         if (b != curb) { curb = b;
; #pragma unroll
;             for (int j = 0; j < 4; ++j) { const int col = 4 * lane + 256 * j; const f32x4 g = *(const f32x4*)(gvec + col), sc = *(const f32x4*)(ada + (size_t)b * 6144 + sc_off + col);
;                 mul[j] = g * (sc + 1.0f); add[j] = *(const f32x4*)(ada + (size_t)b * 6144 + sh_off + col); } }
; #pragma unroll
;         for (int j = 0; j < 4; ++j) ss += (v[j][0] * v[j][0] + v[j][1] * v[j][1]) + (v[j][2] * v[j][2] + v[j][3] * v[j][3]);
;         const float rstd = rsqrtf(wave_sum(ss) * (1.0f / 1024.0f) + 1e-6f);
; #pragma unroll
;         for (int j = 0; j < 4; ++j) { const f32x4 o = (v[j] * rstd) * mul[j] + add[j]; v2u w; w.x = pk2(o[0], o[1]); w.y = pk2(o[2], o[3]);
;             *(v2u*)(U + (size_t)m * 1024 + 4 * lane + 256 * j) = w; }
	v_pk_mul_f32 v[82:83], v[8:9], v[8:9]
	v_pk_mul_f32 v[84:85], v[10:11], v[10:11]
	v_pk_mul_f32 v[86:87], v[12:13], v[12:13]
	v_pk_mul_f32 v[88:89], v[14:15], v[14:15]
	v_mov_b32_e32 v90, v86
	v_mov_b32_e32 v91, v89
	v_pk_mov_b32 v[86:87], v[86:87], v[88:89] op_sel:[1,0]
	v_mov_b32_e32 v88, v82
	v_mov_b32_e32 v89, v85
	v_pk_mov_b32 v[82:83], v[82:83], v[84:85] op_sel:[1,0]
	v_pk_add_f32 v[86:87], v[86:87], v[90:91]
	v_pk_add_f32 v[82:83], v[82:83], v[88:89]
	v_pk_add_f32 v[86:87], v[86:87], v[86:87] op_sel_hi:[0,1]
	v_pk_add_f32 v[82:83], v[82:83], v[82:83] op_sel_hi:[0,1]
	v_mul_f32_e32 v82, v4, v4
	v_pk_fma_f32 v[84:85], v[4:5], v[4:5], v[82:83] op_sel_hi:[1,1,0]
	v_mul_f32_e32 v82, v6, v6
	v_pk_fma_f32 v[88:89], v[6:7], v[6:7], v[82:83] op_sel_hi:[1,1,0]
	v_mul_f32_e32 v84, v0, v0
	v_mul_f32_e32 v88, v1, v1
	v_mul_f32_e32 v86, v2, v2
	v_mul_f32_e32 v82, v3, v3
	v_pk_add_f32 v[84:85], v[84:85], v[88:89]
	v_pk_add_f32 v[82:83], v[86:87], v[82:83]
	v_pk_add_f32 v[82:83], v[84:85], v[82:83]
	v_add_f32_e32 v82, v82, v83
	ds_bpermute_b32 v83, v71, v82
	s_waitcnt lgkmcnt(0)
	v_add_f32_e32 v82, v82, v83
	ds_bpermute_b32 v83, v72, v82
	s_waitcnt lgkmcnt(0)
	v_add_f32_e32 v82, v82, v83
	ds_bpermute_b32 v83, v73, v82
	s_waitcnt lgkmcnt(0)
	v_add_f32_e32 v82, v82, v83
	ds_bpermute_b32 v83, v74, v82
	s_waitcnt lgkmcnt(0)
	v_add_f32_e32 v82, v82, v83
	ds_bpermute_b32 v83, v75, v82
	s_waitcnt lgkmcnt(0)
	v_add_f32_e32 v82, v82, v83
	ds_bpermute_b32 v83, v76, v82
	s_waitcnt lgkmcnt(0)
	v_add_f32_e32 v82, v82, v83
	v_fmamk_f32 v82, v82, 0x3a800000, v81
	v_mul_f32_e32 v83, 0x4b800000, v82
	v_cmp_gt_f32_e32 vcc, s7, v82
	s_nop 1
	v_cndmask_b32_e32 v82, v82, v83, vcc
	v_rsq_f32_e32 v82, v82
	s_nop 0
	v_mul_f32_e32 v83, 0x45800000, v82
	v_cndmask_b32_e32 v82, v82, v83, vcc
	v_pk_mul_f32 v[12:13], v[12:13], v[82:83] op_sel_hi:[1,0]
	v_pk_mul_f32 v[8:9], v[8:9], v[82:83] op_sel_hi:[1,0]
	v_pk_mul_f32 v[4:5], v[4:5], v[82:83] op_sel_hi:[1,0]
	v_pk_mul_f32 v[0:1], v[0:1], v[82:83] op_sel_hi:[1,0]
	v_pk_mul_f32 v[14:15], v[14:15], v[82:83] op_sel_hi:[1,0]
	v_pk_mul_f32 v[10:11], v[10:11], v[82:83] op_sel_hi:[1,0]
	v_pk_fma_f32 v[12:13], v[48:49], v[12:13], v[28:29]
	v_pk_fma_f32 v[8:9], v[52:53], v[8:9], v[24:25]
	v_pk_mul_f32 v[6:7], v[6:7], v[82:83] op_sel_hi:[1,0]
	v_pk_fma_f32 v[4:5], v[56:57], v[4:5], v[20:21]
	v_pk_mul_f32 v[2:3], v[2:3], v[82:83] op_sel_hi:[1,0]
	v_pk_fma_f32 v[0:1], v[60:61], v[0:1], v[16:17]
	v_pk_fma_f32 v[14:15], v[50:51], v[14:15], v[30:31]
	v_pk_fma_f32 v[10:11], v[54:55], v[10:11], v[26:27]
	v_cvt_pk_bf16_f32 v12, v12, v13
	v_cvt_pk_bf16_f32 v13, v14, v15
	global_store_dwordx2 v[66:67], v[12:13], off
	v_cvt_pk_bf16_f32 v8, v8, v9
	v_cvt_pk_bf16_f32 v9, v10, v11
	global_store_dwordx2 v[66:67], v[8:9], off offset:512
	v_pk_fma_f32 v[6:7], v[58:59], v[6:7], v[22:23]
	v_cvt_pk_bf16_f32 v4, v4, v5
	v_pk_fma_f32 v[2:3], v[62:63], v[2:3], v[18:19]
	v_cvt_pk_bf16_f32 v5, v6, v7
	global_store_dwordx2 v[66:67], v[4:5], off offset:1024
	v_cvt_pk_bf16_f32 v0, v0, v1
	v_cvt_pk_bf16_f32 v1, v2, v3
	global_store_dwordx2 v[66:67], v[0:1], off offset:1536
	v_lshl_add_u64 v[66:67], v[66:67], 0, s[2:3]
	global_load_dwordx4 v[12:15], v[68:69], off
	global_load_dwordx4 v[8:11], v[68:69], off offset:1024
	global_load_dwordx4 v[4:7], v[68:69], off offset:2048
	global_load_dwordx4 v[0:3], v[68:69], off offset:3072
	v_lshl_add_u64 v[68:69], v[68:69], 0, s[0:1]
	s_waitcnt vmcnt(24)
	v_pk_mul_f32 v[82:83], v[160:161], v[160:161]
	v_pk_mul_f32 v[84:85], v[162:163], v[162:163]
	v_pk_mul_f32 v[86:87], v[164:165], v[164:165]
	v_pk_mul_f32 v[88:89], v[166:167], v[166:167]
	v_mov_b32_e32 v90, v86
	v_mov_b32_e32 v91, v89
	v_pk_mov_b32 v[86:87], v[86:87], v[88:89] op_sel:[1,0]
	v_mov_b32_e32 v88, v82
	v_mov_b32_e32 v89, v85
	v_pk_mov_b32 v[82:83], v[82:83], v[84:85] op_sel:[1,0]
	v_pk_add_f32 v[86:87], v[86:87], v[90:91]
	v_pk_add_f32 v[82:83], v[82:83], v[88:89]
	v_pk_add_f32 v[86:87], v[86:87], v[86:87] op_sel_hi:[0,1]
	v_pk_add_f32 v[82:83], v[82:83], v[82:83] op_sel_hi:[0,1]
	v_mul_f32_e32 v82, v156, v156
	v_pk_fma_f32 v[84:85], v[156:157], v[156:157], v[82:83] op_sel_hi:[1,1,0]
	v_mul_f32_e32 v82, v158, v158
	v_pk_fma_f32 v[88:89], v[158:159], v[158:159], v[82:83] op_sel_hi:[1,1,0]
	v_mul_f32_e32 v84, v152, v152
	v_mul_f32_e32 v88, v153, v153
	v_mul_f32_e32 v86, v154, v154
	v_mul_f32_e32 v82, v155, v155
	v_pk_add_f32 v[84:85], v[84:85], v[88:89]
	v_pk_add_f32 v[82:83], v[86:87], v[82:83]
	v_pk_add_f32 v[82:83], v[84:85], v[82:83]
	v_add_f32_e32 v82, v82, v83
	ds_bpermute_b32 v83, v71, v82
	s_waitcnt lgkmcnt(0)
	v_add_f32_e32 v82, v82, v83
	ds_bpermute_b32 v83, v72, v82
	s_waitcnt lgkmcnt(0)
	v_add_f32_e32 v82, v82, v83
	ds_bpermute_b32 v83, v73, v82
	s_waitcnt lgkmcnt(0)
	v_add_f32_e32 v82, v82, v83
	ds_bpermute_b32 v83, v74, v82
	s_waitcnt lgkmcnt(0)
	v_add_f32_e32 v82, v82, v83
	ds_bpermute_b32 v83, v75, v82
	s_waitcnt lgkmcnt(0)
	v_add_f32_e32 v82, v82, v83
	ds_bpermute_b32 v83, v76, v82
	s_waitcnt lgkmcnt(0)
; DI unsigned pk2(float lo, float hi) { return pg8::cvt_pk_bf16(lo, hi); }
; DI void prenorm_rows(const float* X, const float* gvec, const float* ada, int sh_off, int sc_off, bf16* U, int row_lo, int row_hi, int gw, int ngw, int lane) {
;     ...
;         f32x4 v[4]; float ss = 0.f;
; #pragma unroll
;         for (int j = 0; j < 4; ++j) v[j] = nx[j];
;         if (m + 1 < m1) {
; #pragma unroll
;             for (int j = 0; j < 4; ++j) nx[j] = *(const f32x4*)(X + (size_t)(m + 1) * 1024 + 4 * lane + 256 * j);
;         }
;         if (b != curb) { curb = b;
; #pragma unroll
;             for (int j = 0; j < 4; ++j) { const int col = 4 * lane + 256 * j; const f32x4 g = *(const f32x4*)(gvec + col), sc = *(const f32x4*)(ada + (size_t)b * 6144 + sc_off + col);
;                 mul[j] = g * (sc + 1.0f); add[j] = *(const f32x4*)(ada + (size_t)b * 6144 + sh_off + col); } }
; #pragma unroll
;         for (int j = 0; j < 4; ++j) ss += (v[j][0] * v[j][0] + v[j][1] * v[j][1]) + (v[j][2] * v[j][2] + v[j][3] * v[j][3]);
;         const float rstd = rsqrtf(wave_sum(ss) * (1.0f / 1024.0f) + 1e-6f);
; #pragma unroll
;         for (int j = 0; j < 4; ++j) { const f32x4 o = (v[j] * rstd) * mul[j] + add[j]; v2u w; w.x = pk2(o[0], o[1]); w.y = pk2(o[2], o[3]);
;             *(v2u*)(U + (size_t)m * 1024 + 4 * lane + 256 * j) = w; }
	v_add_f32_e32 v82, v82, v83
	v_fmamk_f32 v82, v82, 0x3a800000, v81
	v_mul_f32_e32 v83, 0x4b800000, v82
	v_cmp_gt_f32_e32 vcc, s7, v82
	s_nop 1
	v_cndmask_b32_e32 v82, v82, v83, vcc
	v_rsq_f32_e32 v82, v82
	s_nop 0
	v_mul_f32_e32 v83, 0x45800000, v82
	v_cndmask_b32_e32 v82, v82, v83, vcc
	v_pk_mul_f32 v[164:165], v[164:165], v[82:83] op_sel_hi:[1,0]
	v_pk_mul_f32 v[160:161], v[160:161], v[82:83] op_sel_hi:[1,0]
	v_pk_mul_f32 v[156:157], v[156:157], v[82:83] op_sel_hi:[1,0]
	v_pk_mul_f32 v[152:153], v[152:153], v[82:83] op_sel_hi:[1,0]
	v_pk_mul_f32 v[166:167], v[166:167], v[82:83] op_sel_hi:[1,0]
	v_pk_mul_f32 v[162:163], v[162:163], v[82:83] op_sel_hi:[1,0]
	v_pk_fma_f32 v[164:165], v[48:49], v[164:165], v[28:29]
	v_pk_fma_f32 v[160:161], v[52:53], v[160:161], v[24:25]
	v_pk_mul_f32 v[158:159], v[158:159], v[82:83] op_sel_hi:[1,0]
	v_pk_fma_f32 v[156:157], v[56:57], v[156:157], v[20:21]
	v_pk_mul_f32 v[154:155], v[154:155], v[82:83] op_sel_hi:[1,0]
	v_pk_fma_f32 v[152:153], v[60:61], v[152:153], v[16:17]
	v_pk_fma_f32 v[166:167], v[50:51], v[166:167], v[30:31]
	v_pk_fma_f32 v[162:163], v[54:55], v[162:163], v[26:27]
	v_cvt_pk_bf16_f32 v164, v164, v165
	v_cvt_pk_bf16_f32 v165, v166, v167
	global_store_dwordx2 v[66:67], v[164:165], off
	v_cvt_pk_bf16_f32 v160, v160, v161
	v_cvt_pk_bf16_f32 v161, v162, v163
	global_store_dwordx2 v[66:67], v[160:161], off offset:512
	v_pk_fma_f32 v[158:159], v[58:59], v[158:159], v[22:23]
	v_cvt_pk_bf16_f32 v156, v156, v157
	v_pk_fma_f32 v[154:155], v[62:63], v[154:155], v[18:19]
	v_cvt_pk_bf16_f32 v157, v158, v159
	global_store_dwordx2 v[66:67], v[156:157], off offset:1024
	v_cvt_pk_bf16_f32 v152, v152, v153
	v_cvt_pk_bf16_f32 v153, v154, v155
	global_store_dwordx2 v[66:67], v[152:153], off offset:1536
	v_lshl_add_u64 v[66:67], v[66:67], 0, s[2:3]
	global_load_dwordx4 v[164:167], v[68:69], off
	global_load_dwordx4 v[160:163], v[68:69], off offset:1024
	global_load_dwordx4 v[156:159], v[68:69], off offset:2048
	global_load_dwordx4 v[152:155], v[68:69], off offset:3072
	v_lshl_add_u64 v[68:69], v[68:69], 0, s[0:1]
	s_waitcnt vmcnt(24)
	v_pk_mul_f32 v[82:83], v[176:177], v[176:177]
	v_pk_mul_f32 v[84:85], v[178:179], v[178:179]
	v_pk_mul_f32 v[86:87], v[180:181], v[180:181]
	v_pk_mul_f32 v[88:89], v[182:183], v[182:183]
	v_mov_b32_e32 v90, v86
	v_mov_b32_e32 v91, v89
	v_pk_mov_b32 v[86:87], v[86:87], v[88:89] op_sel:[1,0]
	v_mov_b32_e32 v88, v82
	v_mov_b32_e32 v89, v85
	v_pk_mov_b32 v[82:83], v[82:83], v[84:85] op_sel:[1,0]
	v_pk_add_f32 v[86:87], v[86:87], v[90:91]
	v_pk_add_f32 v[82:83], v[82:83], v[88:89]
	v_pk_add_f32 v[86:87], v[86:87], v[86:87] op_sel_hi:[0,1]
	v_pk_add_f32 v[82:83], v[82:83], v[82:83] op_sel_hi:[0,1]
	v_mul_f32_e32 v82, v172, v172
	v_pk_fma_f32 v[84:85], v[172:173], v[172:173], v[82:83] op_sel_hi:[1,1,0]
	v_mul_f32_e32 v82, v174, v174
	v_pk_fma_f32 v[88:89], v[174:175], v[174:175], v[82:83] op_sel_hi:[1,1,0]
	v_mul_f32_e32 v84, v168, v168
	v_mul_f32_e32 v88, v169, v169
	v_mul_f32_e32 v86, v170, v170
	v_mul_f32_e32 v82, v171, v171
	v_pk_add_f32 v[84:85], v[84:85], v[88:89]
	v_pk_add_f32 v[82:83], v[86:87], v[82:83]
	v_pk_add_f32 v[82:83], v[84:85], v[82:83]
	v_add_f32_e32 v82, v82, v83
	ds_bpermute_b32 v83, v71, v82
	s_waitcnt lgkmcnt(0)
	v_add_f32_e32 v82, v82, v83
	ds_bpermute_b32 v83, v72, v82
	s_waitcnt lgkmcnt(0)
	v_add_f32_e32 v82, v82, v83
	ds_bpermute_b32 v83, v73, v82
	s_waitcnt lgkmcnt(0)
	v_add_f32_e32 v82, v82, v83
	ds_bpermute_b32 v83, v74, v82
	s_waitcnt lgkmcnt(0)
	v_add_f32_e32 v82, v82, v83
	ds_bpermute_b32 v83, v75, v82
	s_waitcnt lgkmcnt(0)
	v_add_f32_e32 v82, v82, v83
	ds_bpermute_b32 v83, v76, v82
	s_waitcnt lgkmcnt(0)
	v_add_f32_e32 v82, v82, v83
	v_fmamk_f32 v82, v82, 0x3a800000, v81
	v_mul_f32_e32 v83, 0x4b800000, v82
	v_cmp_gt_f32_e32 vcc, s7, v82
	s_nop 1
	v_cndmask_b32_e32 v82, v82, v83, vcc
	v_rsq_f32_e32 v82, v82
	s_nop 0
	v_mul_f32_e32 v83, 0x45800000, v82
	v_cndmask_b32_e32 v82, v82, v83, vcc
	v_pk_mul_f32 v[180:181], v[180:181], v[82:83] op_sel_hi:[1,0]
	v_pk_mul_f32 v[176:177], v[176:177], v[82:83] op_sel_hi:[1,0]
	v_pk_mul_f32 v[172:173], v[172:173], v[82:83] op_sel_hi:[1,0]
	v_pk_mul_f32 v[168:169], v[168:169], v[82:83] op_sel_hi:[1,0]
	v_pk_mul_f32 v[182:183], v[182:183], v[82:83] op_sel_hi:[1,0]
	v_pk_mul_f32 v[178:179], v[178:179], v[82:83] op_sel_hi:[1,0]
	v_pk_fma_f32 v[180:181], v[48:49], v[180:181], v[28:29]
	v_pk_fma_f32 v[176:177], v[52:53], v[176:177], v[24:25]
	v_pk_mul_f32 v[174:175], v[174:175], v[82:83] op_sel_hi:[1,0]
	v_pk_fma_f32 v[172:173], v[56:57], v[172:173], v[20:21]
	v_pk_mul_f32 v[170:171], v[170:171], v[82:83] op_sel_hi:[1,0]
	v_pk_fma_f32 v[168:169], v[60:61], v[168:169], v[16:17]
	v_pk_fma_f32 v[182:183], v[50:51], v[182:183], v[30:31]
	v_pk_fma_f32 v[178:179], v[54:55], v[178:179], v[26:27]
	v_cvt_pk_bf16_f32 v180, v180, v181
	v_cvt_pk_bf16_f32 v181, v182, v183
	global_store_dwordx2 v[66:67], v[180:181], off
	v_cvt_pk_bf16_f32 v176, v176, v177
	v_cvt_pk_bf16_f32 v177, v178, v179
	global_store_dwordx2 v[66:67], v[176:177], off offset:512
	v_pk_fma_f32 v[174:175], v[58:59], v[174:175], v[22:23]
	v_cvt_pk_bf16_f32 v172, v172, v173
	v_pk_fma_f32 v[170:171], v[62:63], v[170:171], v[18:19]
	v_cvt_pk_bf16_f32 v173, v174, v175
	global_store_dwordx2 v[66:67], v[172:173], off offset:1024
	v_cvt_pk_bf16_f32 v168, v168, v169
	v_cvt_pk_bf16_f32 v169, v170, v171
	global_store_dwordx2 v[66:67], v[168:169], off offset:1536
	v_lshl_add_u64 v[66:67], v[66:67], 0, s[2:3]
	global_load_dwordx4 v[180:183], v[68:69], off
	global_load_dwordx4 v[176:179], v[68:69], off offset:1024
	global_load_dwordx4 v[172:175], v[68:69], off offset:2048
	global_load_dwordx4 v[168:171], v[68:69], off offset:3072
	v_lshl_add_u64 v[68:69], v[68:69], 0, s[0:1]
	s_waitcnt vmcnt(24)
; DI unsigned pk2(float lo, float hi) { return pg8::cvt_pk_bf16(lo, hi); }
; DI void prenorm_rows(const float* X, const float* gvec, const float* ada, int sh_off, int sc_off, bf16* U, int row_lo, int row_hi, int gw, int ngw, int lane) {
;     ...
;         f32x4 v[4]; float ss = 0.f;
; #pragma unroll
;         for (int j = 0; j < 4; ++j) v[j] = nx[j];
;         if (m + 1 < m1) {
; #pragma unroll
;             for (int j = 0; j < 4; ++j) nx[j] = *(const f32x4*)(X + (size_t)(m + 1) * 1024 + 4 * lane + 256 * j);
;         }
;         if (b != curb) { curb = b;
; #pragma unroll
;             for (int j = 0; j < 4; ++j) { const int col = 4 * lane + 256 * j; const f32x4 g = *(const f32x4*)(gvec + col), sc = *(const f32x4*)(ada + (size_t)b * 6144 + sc_off + col);
;                 mul[j] = g * (sc + 1.0f); add[j] = *(const f32x4*)(ada + (size_t)b * 6144 + sh_off + col); } }
; #pragma unroll
;         for (int j = 0; j < 4; ++j) ss += (v[j][0] * v[j][0] + v[j][1] * v[j][1]) + (v[j][2] * v[j][2] + v[j][3] * v[j][3]);
;         const float rstd = rsqrtf(wave_sum(ss) * (1.0f / 1024.0f) + 1e-6f);
; #pragma unroll
;         for (int j = 0; j < 4; ++j) { const f32x4 o = (v[j] * rstd) * mul[j] + add[j]; v2u w; w.x = pk2(o[0], o[1]); w.y = pk2(o[2], o[3]);
;             *(v2u*)(U + (size_t)m * 1024 + 4 * lane + 256 * j) = w; }
	v_pk_mul_f32 v[82:83], v[40:41], v[40:41]
	v_pk_mul_f32 v[84:85], v[42:43], v[42:43]
	v_pk_mul_f32 v[86:87], v[44:45], v[44:45]
	v_pk_mul_f32 v[88:89], v[46:47], v[46:47]
	v_mov_b32_e32 v90, v86
	v_mov_b32_e32 v91, v89
	v_pk_mov_b32 v[86:87], v[86:87], v[88:89] op_sel:[1,0]
	v_mov_b32_e32 v88, v82
	v_mov_b32_e32 v89, v85
	v_pk_mov_b32 v[82:83], v[82:83], v[84:85] op_sel:[1,0]
	v_pk_add_f32 v[86:87], v[86:87], v[90:91]
	v_pk_add_f32 v[82:83], v[82:83], v[88:89]
	v_pk_add_f32 v[86:87], v[86:87], v[86:87] op_sel_hi:[0,1]
	v_pk_add_f32 v[82:83], v[82:83], v[82:83] op_sel_hi:[0,1]
	v_mul_f32_e32 v82, v36, v36
	v_pk_fma_f32 v[84:85], v[36:37], v[36:37], v[82:83] op_sel_hi:[1,1,0]
	v_mul_f32_e32 v82, v38, v38
	v_pk_fma_f32 v[88:89], v[38:39], v[38:39], v[82:83] op_sel_hi:[1,1,0]
	v_mul_f32_e32 v84, v32, v32
	v_mul_f32_e32 v88, v33, v33
	v_mul_f32_e32 v86, v34, v34
	v_mul_f32_e32 v82, v35, v35
	v_pk_add_f32 v[84:85], v[84:85], v[88:89]
	v_pk_add_f32 v[82:83], v[86:87], v[82:83]
	v_pk_add_f32 v[82:83], v[84:85], v[82:83]
	v_add_f32_e32 v82, v82, v83
	ds_bpermute_b32 v83, v71, v82
	s_waitcnt lgkmcnt(0)
	v_add_f32_e32 v82, v82, v83
	ds_bpermute_b32 v83, v72, v82
	s_waitcnt lgkmcnt(0)
	v_add_f32_e32 v82, v82, v83
	ds_bpermute_b32 v83, v73, v82
	s_waitcnt lgkmcnt(0)
	v_add_f32_e32 v82, v82, v83
	ds_bpermute_b32 v83, v74, v82
	s_waitcnt lgkmcnt(0)
	v_add_f32_e32 v82, v82, v83
	ds_bpermute_b32 v83, v75, v82
	s_waitcnt lgkmcnt(0)
	v_add_f32_e32 v82, v82, v83
	ds_bpermute_b32 v83, v76, v82
	s_waitcnt lgkmcnt(0)
	v_add_f32_e32 v82, v82, v83
	v_fmamk_f32 v82, v82, 0x3a800000, v81
	v_mul_f32_e32 v83, 0x4b800000, v82
	v_cmp_gt_f32_e32 vcc, s7, v82
	s_nop 1
	v_cndmask_b32_e32 v82, v82, v83, vcc
	v_rsq_f32_e32 v82, v82
	s_nop 0
	v_mul_f32_e32 v83, 0x45800000, v82
	v_cndmask_b32_e32 v82, v82, v83, vcc
	v_pk_mul_f32 v[44:45], v[44:45], v[82:83] op_sel_hi:[1,0]
	v_pk_mul_f32 v[40:41], v[40:41], v[82:83] op_sel_hi:[1,0]
	v_pk_mul_f32 v[36:37], v[36:37], v[82:83] op_sel_hi:[1,0]
	v_pk_mul_f32 v[32:33], v[32:33], v[82:83] op_sel_hi:[1,0]
	v_pk_mul_f32 v[46:47], v[46:47], v[82:83] op_sel_hi:[1,0]
	v_pk_mul_f32 v[42:43], v[42:43], v[82:83] op_sel_hi:[1,0]
	v_pk_fma_f32 v[44:45], v[48:49], v[44:45], v[28:29]
	v_pk_fma_f32 v[40:41], v[52:53], v[40:41], v[24:25]
	v_pk_mul_f32 v[38:39], v[38:39], v[82:83] op_sel_hi:[1,0]
	v_pk_fma_f32 v[36:37], v[56:57], v[36:37], v[20:21]
	v_pk_mul_f32 v[34:35], v[34:35], v[82:83] op_sel_hi:[1,0]
	v_pk_fma_f32 v[32:33], v[60:61], v[32:33], v[16:17]
	v_pk_fma_f32 v[46:47], v[50:51], v[46:47], v[30:31]
	v_pk_fma_f32 v[42:43], v[54:55], v[42:43], v[26:27]
	v_cvt_pk_bf16_f32 v44, v44, v45
	v_cvt_pk_bf16_f32 v45, v46, v47
	global_store_dwordx2 v[66:67], v[44:45], off
	v_cvt_pk_bf16_f32 v40, v40, v41
	v_cvt_pk_bf16_f32 v41, v42, v43
	global_store_dwordx2 v[66:67], v[40:41], off offset:512
	v_pk_fma_f32 v[38:39], v[58:59], v[38:39], v[22:23]
	v_cvt_pk_bf16_f32 v36, v36, v37
	v_pk_fma_f32 v[34:35], v[62:63], v[34:35], v[18:19]
	v_cvt_pk_bf16_f32 v37, v38, v39
	global_store_dwordx2 v[66:67], v[36:37], off offset:1024
	v_cvt_pk_bf16_f32 v32, v32, v33
	v_cvt_pk_bf16_f32 v33, v34, v35
	global_store_dwordx2 v[66:67], v[32:33], off offset:1536
	v_lshl_add_u64 v[66:67], v[66:67], 0, s[2:3]
	global_load_dwordx4 v[44:47], v[68:69], off
	global_load_dwordx4 v[40:43], v[68:69], off offset:1024
	global_load_dwordx4 v[36:39], v[68:69], off offset:2048
	global_load_dwordx4 v[32:35], v[68:69], off offset:3072
	v_lshl_add_u64 v[68:69], v[68:69], 0, s[0:1]
	s_waitcnt vmcnt(24)
	v_pk_mul_f32 v[82:83], v[8:9], v[8:9]
	v_pk_mul_f32 v[84:85], v[10:11], v[10:11]
	v_pk_mul_f32 v[86:87], v[12:13], v[12:13]
	v_pk_mul_f32 v[88:89], v[14:15], v[14:15]
	v_mov_b32_e32 v90, v86
	v_mov_b32_e32 v91, v89
	v_pk_mov_b32 v[86:87], v[86:87], v[88:89] op_sel:[1,0]
	v_mov_b32_e32 v88, v82
	v_mov_b32_e32 v89, v85
	v_pk_mov_b32 v[82:83], v[82:83], v[84:85] op_sel:[1,0]
	v_pk_add_f32 v[86:87], v[86:87], v[90:91]
	v_pk_add_f32 v[82:83], v[82:83], v[88:89]
	v_pk_add_f32 v[86:87], v[86:87], v[86:87] op_sel_hi:[0,1]
	v_pk_add_f32 v[82:83], v[82:83], v[82:83] op_sel_hi:[0,1]
	v_mul_f32_e32 v82, v4, v4
	v_pk_fma_f32 v[84:85], v[4:5], v[4:5], v[82:83] op_sel_hi:[1,1,0]
	v_mul_f32_e32 v82, v6, v6
	v_pk_fma_f32 v[88:89], v[6:7], v[6:7], v[82:83] op_sel_hi:[1,1,0]
	v_mul_f32_e32 v84, v0, v0
	v_mul_f32_e32 v88, v1, v1
	v_mul_f32_e32 v86, v2, v2
	v_mul_f32_e32 v82, v3, v3
	v_pk_add_f32 v[84:85], v[84:85], v[88:89]
	v_pk_add_f32 v[82:83], v[86:87], v[82:83]
	v_pk_add_f32 v[82:83], v[84:85], v[82:83]
	v_add_f32_e32 v82, v82, v83
	ds_bpermute_b32 v83, v71, v82
	s_waitcnt lgkmcnt(0)
	v_add_f32_e32 v82, v82, v83
	ds_bpermute_b32 v83, v72, v82
	s_waitcnt lgkmcnt(0)
	v_add_f32_e32 v82, v82, v83
	ds_bpermute_b32 v83, v73, v82
	s_waitcnt lgkmcnt(0)
	v_add_f32_e32 v82, v82, v83
	ds_bpermute_b32 v83, v74, v82
	s_waitcnt lgkmcnt(0)
	v_add_f32_e32 v82, v82, v83
	ds_bpermute_b32 v83, v75, v82
	s_waitcnt lgkmcnt(0)
	v_add_f32_e32 v82, v82, v83
	ds_bpermute_b32 v83, v76, v82
	s_waitcnt lgkmcnt(0)
; DI unsigned pk2(float lo, float hi) { return pg8::cvt_pk_bf16(lo, hi); }
; DI void prenorm_rows(const float* X, const float* gvec, const float* ada, int sh_off, int sc_off, bf16* U, int row_lo, int row_hi, int gw, int ngw, int lane) {
;     ...
;         f32x4 v[4]; float ss = 0.f;
; #pragma unroll
;         for (int j = 0; j < 4; ++j) v[j] = nx[j];
;         if (m + 1 < m1) {
; #pragma unroll
;             for (int j = 0; j < 4; ++j) nx[j] = *(const f32x4*)(X + (size_t)(m + 1) * 1024 + 4 * lane + 256 * j);
;         }
;         if (b != curb) { curb = b;
; #pragma unroll
;             for (int j = 0; j < 4; ++j) { const int col = 4 * lane + 256 * j; const f32x4 g = *(const f32x4*)(gvec + col), sc = *(const f32x4*)(ada + (size_t)b * 6144 + sc_off + col);
;                 mul[j] = g * (sc + 1.0f); add[j] = *(const f32x4*)(ada + (size_t)b * 6144 + sh_off + col); } }
; #pragma unroll
;         for (int j = 0; j < 4; ++j) ss += (v[j][0] * v[j][0] + v[j][1] * v[j][1]) + (v[j][2] * v[j][2] + v[j][3] * v[j][3]);
;         const float rstd = rsqrtf(wave_sum(ss) * (1.0f / 1024.0f) + 1e-6f);
; #pragma unroll
;         for (int j = 0; j < 4; ++j) { const f32x4 o = (v[j] * rstd) * mul[j] + add[j]; v2u w; w.x = pk2(o[0], o[1]); w.y = pk2(o[2], o[3]);
;             *(v2u*)(U + (size_t)m * 1024 + 4 * lane + 256 * j) = w; }
	v_add_f32_e32 v82, v82, v83
	v_fmamk_f32 v82, v82, 0x3a800000, v81
	v_mul_f32_e32 v83, 0x4b800000, v82
	v_cmp_gt_f32_e32 vcc, s7, v82
	s_nop 1
	v_cndmask_b32_e32 v82, v82, v83, vcc
	v_rsq_f32_e32 v82, v82
	s_nop 0
	v_mul_f32_e32 v83, 0x45800000, v82
	v_cndmask_b32_e32 v82, v82, v83, vcc
	v_pk_mul_f32 v[12:13], v[12:13], v[82:83] op_sel_hi:[1,0]
	v_pk_mul_f32 v[8:9], v[8:9], v[82:83] op_sel_hi:[1,0]
	v_pk_mul_f32 v[4:5], v[4:5], v[82:83] op_sel_hi:[1,0]
	v_pk_mul_f32 v[0:1], v[0:1], v[82:83] op_sel_hi:[1,0]
	v_pk_mul_f32 v[14:15], v[14:15], v[82:83] op_sel_hi:[1,0]
	v_pk_mul_f32 v[10:11], v[10:11], v[82:83] op_sel_hi:[1,0]
	v_pk_fma_f32 v[12:13], v[48:49], v[12:13], v[28:29]
	v_pk_fma_f32 v[8:9], v[52:53], v[8:9], v[24:25]
	v_pk_mul_f32 v[6:7], v[6:7], v[82:83] op_sel_hi:[1,0]
	v_pk_fma_f32 v[4:5], v[56:57], v[4:5], v[20:21]
	v_pk_mul_f32 v[2:3], v[2:3], v[82:83] op_sel_hi:[1,0]
	v_pk_fma_f32 v[0:1], v[60:61], v[0:1], v[16:17]
	v_pk_fma_f32 v[14:15], v[50:51], v[14:15], v[30:31]
	v_pk_fma_f32 v[10:11], v[54:55], v[10:11], v[26:27]
	v_cvt_pk_bf16_f32 v12, v12, v13
	v_cvt_pk_bf16_f32 v13, v14, v15
	global_store_dwordx2 v[66:67], v[12:13], off
	v_cvt_pk_bf16_f32 v8, v8, v9
	v_cvt_pk_bf16_f32 v9, v10, v11
	global_store_dwordx2 v[66:67], v[8:9], off offset:512
	v_pk_fma_f32 v[6:7], v[58:59], v[6:7], v[22:23]
	v_cvt_pk_bf16_f32 v4, v4, v5
	v_pk_fma_f32 v[2:3], v[62:63], v[2:3], v[18:19]
	v_cvt_pk_bf16_f32 v5, v6, v7
	global_store_dwordx2 v[66:67], v[4:5], off offset:1024
	v_cvt_pk_bf16_f32 v0, v0, v1
	v_cvt_pk_bf16_f32 v1, v2, v3
	global_store_dwordx2 v[66:67], v[0:1], off offset:1536
	v_lshl_add_u64 v[66:67], v[66:67], 0, s[2:3]
	global_load_dwordx4 v[12:15], v[68:69], off
	global_load_dwordx4 v[8:11], v[68:69], off offset:1024
	global_load_dwordx4 v[4:7], v[68:69], off offset:2048
	global_load_dwordx4 v[0:3], v[68:69], off offset:3072
	v_lshl_add_u64 v[68:69], v[68:69], 0, s[0:1]
	s_waitcnt vmcnt(24)
	v_pk_mul_f32 v[82:83], v[160:161], v[160:161]
	v_pk_mul_f32 v[84:85], v[162:163], v[162:163]
	v_pk_mul_f32 v[86:87], v[164:165], v[164:165]
	v_pk_mul_f32 v[88:89], v[166:167], v[166:167]
	v_mov_b32_e32 v90, v86
	v_mov_b32_e32 v91, v89
	v_pk_mov_b32 v[86:87], v[86:87], v[88:89] op_sel:[1,0]
	v_mov_b32_e32 v88, v82
	v_mov_b32_e32 v89, v85
	v_pk_mov_b32 v[82:83], v[82:83], v[84:85] op_sel:[1,0]
	v_pk_add_f32 v[86:87], v[86:87], v[90:91]
	v_pk_add_f32 v[82:83], v[82:83], v[88:89]
	v_pk_add_f32 v[86:87], v[86:87], v[86:87] op_sel_hi:[0,1]
	v_pk_add_f32 v[82:83], v[82:83], v[82:83] op_sel_hi:[0,1]
	v_mul_f32_e32 v82, v156, v156
	v_pk_fma_f32 v[84:85], v[156:157], v[156:157], v[82:83] op_sel_hi:[1,1,0]
	v_mul_f32_e32 v82, v158, v158
	v_pk_fma_f32 v[88:89], v[158:159], v[158:159], v[82:83] op_sel_hi:[1,1,0]
	v_mul_f32_e32 v84, v152, v152
	v_mul_f32_e32 v88, v153, v153
	v_mul_f32_e32 v86, v154, v154
	v_mul_f32_e32 v82, v155, v155
	v_pk_add_f32 v[84:85], v[84:85], v[88:89]
	v_pk_add_f32 v[82:83], v[86:87], v[82:83]
	v_pk_add_f32 v[82:83], v[84:85], v[82:83]
	v_add_f32_e32 v82, v82, v83
	ds_bpermute_b32 v83, v71, v82
	s_waitcnt lgkmcnt(0)
	v_add_f32_e32 v82, v82, v83
	ds_bpermute_b32 v83, v72, v82
	s_waitcnt lgkmcnt(0)
	v_add_f32_e32 v82, v82, v83
	ds_bpermute_b32 v83, v73, v82
	s_waitcnt lgkmcnt(0)
	v_add_f32_e32 v82, v82, v83
	ds_bpermute_b32 v83, v74, v82
	s_waitcnt lgkmcnt(0)
	v_add_f32_e32 v82, v82, v83
	ds_bpermute_b32 v83, v75, v82
	s_waitcnt lgkmcnt(0)
	v_add_f32_e32 v82, v82, v83
	ds_bpermute_b32 v83, v76, v82
	s_waitcnt lgkmcnt(0)
	v_add_f32_e32 v82, v82, v83
	v_fmamk_f32 v82, v82, 0x3a800000, v81
	v_mul_f32_e32 v83, 0x4b800000, v82
	v_cmp_gt_f32_e32 vcc, s7, v82
	s_nop 1
	v_cndmask_b32_e32 v82, v82, v83, vcc
	v_rsq_f32_e32 v82, v82
	s_nop 0
	v_mul_f32_e32 v83, 0x45800000, v82
	v_cndmask_b32_e32 v82, v82, v83, vcc
	v_pk_mul_f32 v[164:165], v[164:165], v[82:83] op_sel_hi:[1,0]
	v_pk_mul_f32 v[160:161], v[160:161], v[82:83] op_sel_hi:[1,0]
	v_pk_mul_f32 v[156:157], v[156:157], v[82:83] op_sel_hi:[1,0]
	v_pk_mul_f32 v[152:153], v[152:153], v[82:83] op_sel_hi:[1,0]
	v_pk_mul_f32 v[166:167], v[166:167], v[82:83] op_sel_hi:[1,0]
	v_pk_mul_f32 v[162:163], v[162:163], v[82:83] op_sel_hi:[1,0]
	v_pk_fma_f32 v[164:165], v[48:49], v[164:165], v[28:29]
	v_pk_fma_f32 v[160:161], v[52:53], v[160:161], v[24:25]
	v_pk_mul_f32 v[158:159], v[158:159], v[82:83] op_sel_hi:[1,0]
	v_pk_fma_f32 v[156:157], v[56:57], v[156:157], v[20:21]
	v_pk_mul_f32 v[154:155], v[154:155], v[82:83] op_sel_hi:[1,0]
	v_pk_fma_f32 v[152:153], v[60:61], v[152:153], v[16:17]
	v_pk_fma_f32 v[166:167], v[50:51], v[166:167], v[30:31]
	v_pk_fma_f32 v[162:163], v[54:55], v[162:163], v[26:27]
	v_cvt_pk_bf16_f32 v164, v164, v165
	v_cvt_pk_bf16_f32 v165, v166, v167
	global_store_dwordx2 v[66:67], v[164:165], off
	v_cvt_pk_bf16_f32 v160, v160, v161
	v_cvt_pk_bf16_f32 v161, v162, v163
	global_store_dwordx2 v[66:67], v[160:161], off offset:512
	v_pk_fma_f32 v[158:159], v[58:59], v[158:159], v[22:23]
	v_cvt_pk_bf16_f32 v156, v156, v157
	v_pk_fma_f32 v[154:155], v[62:63], v[154:155], v[18:19]
	v_cvt_pk_bf16_f32 v157, v158, v159
	global_store_dwordx2 v[66:67], v[156:157], off offset:1024
	v_cvt_pk_bf16_f32 v152, v152, v153
	v_cvt_pk_bf16_f32 v153, v154, v155
	global_store_dwordx2 v[66:67], v[152:153], off offset:1536
	v_lshl_add_u64 v[66:67], v[66:67], 0, s[2:3]
	global_load_dwordx4 v[164:167], v[68:69], off
	global_load_dwordx4 v[160:163], v[68:69], off offset:1024
	global_load_dwordx4 v[156:159], v[68:69], off offset:2048
	global_load_dwordx4 v[152:155], v[68:69], off offset:3072
	v_lshl_add_u64 v[68:69], v[68:69], 0, s[0:1]
	s_waitcnt vmcnt(24)
; DI unsigned pk2(float lo, float hi) { return pg8::cvt_pk_bf16(lo, hi); }
; DI void prenorm_rows(const float* X, const float* gvec, const float* ada, int sh_off, int sc_off, bf16* U, int row_lo, int row_hi, int gw, int ngw, int lane) {
;     ...
;         f32x4 v[4]; float ss = 0.f;
; #pragma unroll
;         for (int j = 0; j < 4; ++j) v[j] = nx[j];
;         if (m + 1 < m1) {
; #pragma unroll
;             for (int j = 0; j < 4; ++j) nx[j] = *(const f32x4*)(X + (size_t)(m + 1) * 1024 + 4 * lane + 256 * j);
;         }
;         if (b != curb) { curb = b;
; #pragma unroll
;             for (int j = 0; j < 4; ++j) { const int col = 4 * lane + 256 * j; const f32x4 g = *(const f32x4*)(gvec + col), sc = *(const f32x4*)(ada + (size_t)b * 6144 + sc_off + col);
;                 mul[j] = g * (sc + 1.0f); add[j] = *(const f32x4*)(ada + (size_t)b * 6144 + sh_off + col); } }
; #pragma unroll
;         for (int j = 0; j < 4; ++j) ss += (v[j][0] * v[j][0] + v[j][1] * v[j][1]) + (v[j][2] * v[j][2] + v[j][3] * v[j][3]);
;         const float rstd = rsqrtf(wave_sum(ss) * (1.0f / 1024.0f) + 1e-6f);
; #pragma unroll
;         for (int j = 0; j < 4; ++j) { const f32x4 o = (v[j] * rstd) * mul[j] + add[j]; v2u w; w.x = pk2(o[0], o[1]); w.y = pk2(o[2], o[3]);
;             *(v2u*)(U + (size_t)m * 1024 + 4 * lane + 256 * j) = w; }
	v_pk_mul_f32 v[82:83], v[176:177], v[176:177]
	v_pk_mul_f32 v[84:85], v[178:179], v[178:179]
	v_pk_mul_f32 v[86:87], v[180:181], v[180:181]
	v_pk_mul_f32 v[88:89], v[182:183], v[182:183]
	v_mov_b32_e32 v90, v86
	v_mov_b32_e32 v91, v89
	v_pk_mov_b32 v[86:87], v[86:87], v[88:89] op_sel:[1,0]
	v_mov_b32_e32 v88, v82
	v_mov_b32_e32 v89, v85
	v_pk_mov_b32 v[82:83], v[82:83], v[84:85] op_sel:[1,0]
	v_pk_add_f32 v[86:87], v[86:87], v[90:91]
	v_pk_add_f32 v[82:83], v[82:83], v[88:89]
	v_pk_add_f32 v[86:87], v[86:87], v[86:87] op_sel_hi:[0,1]
	v_pk_add_f32 v[82:83], v[82:83], v[82:83] op_sel_hi:[0,1]
	v_mul_f32_e32 v82, v172, v172
	v_pk_fma_f32 v[84:85], v[172:173], v[172:173], v[82:83] op_sel_hi:[1,1,0]
	v_mul_f32_e32 v82, v174, v174
	v_pk_fma_f32 v[88:89], v[174:175], v[174:175], v[82:83] op_sel_hi:[1,1,0]
	v_mul_f32_e32 v84, v168, v168
	v_mul_f32_e32 v88, v169, v169
	v_mul_f32_e32 v86, v170, v170
	v_mul_f32_e32 v82, v171, v171
	v_pk_add_f32 v[84:85], v[84:85], v[88:89]
	v_pk_add_f32 v[82:83], v[86:87], v[82:83]
	v_pk_add_f32 v[82:83], v[84:85], v[82:83]
	v_add_f32_e32 v82, v82, v83
	ds_bpermute_b32 v83, v71, v82
	s_waitcnt lgkmcnt(0)
	v_add_f32_e32 v82, v82, v83
	ds_bpermute_b32 v83, v72, v82
	s_waitcnt lgkmcnt(0)
	v_add_f32_e32 v82, v82, v83
	ds_bpermute_b32 v83, v73, v82
	s_waitcnt lgkmcnt(0)
	v_add_f32_e32 v82, v82, v83
	ds_bpermute_b32 v83, v74, v82
	s_waitcnt lgkmcnt(0)
	v_add_f32_e32 v82, v82, v83
	ds_bpermute_b32 v83, v75, v82
	s_waitcnt lgkmcnt(0)
	v_add_f32_e32 v82, v82, v83
	ds_bpermute_b32 v83, v76, v82
	s_waitcnt lgkmcnt(0)
	v_add_f32_e32 v82, v82, v83
	v_fmamk_f32 v82, v82, 0x3a800000, v81
	v_mul_f32_e32 v83, 0x4b800000, v82
	v_cmp_gt_f32_e32 vcc, s7, v82
	s_nop 1
	v_cndmask_b32_e32 v82, v82, v83, vcc
	v_rsq_f32_e32 v82, v82
	s_nop 0
	v_mul_f32_e32 v83, 0x45800000, v82
	v_cndmask_b32_e32 v82, v82, v83, vcc
	v_pk_mul_f32 v[180:181], v[180:181], v[82:83] op_sel_hi:[1,0]
	v_pk_mul_f32 v[176:177], v[176:177], v[82:83] op_sel_hi:[1,0]
	v_pk_mul_f32 v[172:173], v[172:173], v[82:83] op_sel_hi:[1,0]
	v_pk_mul_f32 v[168:169], v[168:169], v[82:83] op_sel_hi:[1,0]
	v_pk_mul_f32 v[182:183], v[182:183], v[82:83] op_sel_hi:[1,0]
	v_pk_mul_f32 v[178:179], v[178:179], v[82:83] op_sel_hi:[1,0]
	v_pk_fma_f32 v[180:181], v[48:49], v[180:181], v[28:29]
	v_pk_fma_f32 v[176:177], v[52:53], v[176:177], v[24:25]
	v_pk_mul_f32 v[174:175], v[174:175], v[82:83] op_sel_hi:[1,0]
	v_pk_fma_f32 v[172:173], v[56:57], v[172:173], v[20:21]
	v_pk_mul_f32 v[170:171], v[170:171], v[82:83] op_sel_hi:[1,0]
	v_pk_fma_f32 v[168:169], v[60:61], v[168:169], v[16:17]
	v_pk_fma_f32 v[182:183], v[50:51], v[182:183], v[30:31]
	v_pk_fma_f32 v[178:179], v[54:55], v[178:179], v[26:27]
	v_cvt_pk_bf16_f32 v180, v180, v181
	v_cvt_pk_bf16_f32 v181, v182, v183
	global_store_dwordx2 v[66:67], v[180:181], off
	v_cvt_pk_bf16_f32 v176, v176, v177
	v_cvt_pk_bf16_f32 v177, v178, v179
	global_store_dwordx2 v[66:67], v[176:177], off offset:512
	v_pk_fma_f32 v[174:175], v[58:59], v[174:175], v[22:23]
	v_cvt_pk_bf16_f32 v172, v172, v173
	v_pk_fma_f32 v[170:171], v[62:63], v[170:171], v[18:19]
	v_cvt_pk_bf16_f32 v173, v174, v175
	global_store_dwordx2 v[66:67], v[172:173], off offset:1024
	v_cvt_pk_bf16_f32 v168, v168, v169
	v_cvt_pk_bf16_f32 v169, v170, v171
	global_store_dwordx2 v[66:67], v[168:169], off offset:1536
	v_lshl_add_u64 v[66:67], v[66:67], 0, s[2:3]
	global_load_dwordx4 v[180:183], v[68:69], off
	global_load_dwordx4 v[176:179], v[68:69], off offset:1024
	global_load_dwordx4 v[172:175], v[68:69], off offset:2048
	global_load_dwordx4 v[168:171], v[68:69], off offset:3072
	v_lshl_add_u64 v[68:69], v[68:69], 0, s[0:1]
	s_waitcnt vmcnt(24)
	v_pk_mul_f32 v[82:83], v[40:41], v[40:41]
	v_pk_mul_f32 v[84:85], v[42:43], v[42:43]
	v_pk_mul_f32 v[86:87], v[44:45], v[44:45]
	v_pk_mul_f32 v[88:89], v[46:47], v[46:47]
	v_mov_b32_e32 v90, v86
	v_mov_b32_e32 v91, v89
	v_pk_mov_b32 v[86:87], v[86:87], v[88:89] op_sel:[1,0]
	v_mov_b32_e32 v88, v82
	v_mov_b32_e32 v89, v85
	v_pk_mov_b32 v[82:83], v[82:83], v[84:85] op_sel:[1,0]
	v_pk_add_f32 v[86:87], v[86:87], v[90:91]
	v_pk_add_f32 v[82:83], v[82:83], v[88:89]
	v_pk_add_f32 v[86:87], v[86:87], v[86:87] op_sel_hi:[0,1]
	v_pk_add_f32 v[82:83], v[82:83], v[82:83] op_sel_hi:[0,1]
	v_mul_f32_e32 v82, v36, v36
	v_pk_fma_f32 v[84:85], v[36:37], v[36:37], v[82:83] op_sel_hi:[1,1,0]
	v_mul_f32_e32 v82, v38, v38
	v_pk_fma_f32 v[88:89], v[38:39], v[38:39], v[82:83] op_sel_hi:[1,1,0]
	v_mul_f32_e32 v84, v32, v32
	v_mul_f32_e32 v88, v33, v33
	v_mul_f32_e32 v86, v34, v34
	v_mul_f32_e32 v82, v35, v35
	v_pk_add_f32 v[84:85], v[84:85], v[88:89]
	v_pk_add_f32 v[82:83], v[86:87], v[82:83]
	v_pk_add_f32 v[82:83], v[84:85], v[82:83]
	v_add_f32_e32 v82, v82, v83
	ds_bpermute_b32 v83, v71, v82
	s_waitcnt lgkmcnt(0)
	v_add_f32_e32 v82, v82, v83
	ds_bpermute_b32 v83, v72, v82
	s_waitcnt lgkmcnt(0)
	v_add_f32_e32 v82, v82, v83
	ds_bpermute_b32 v83, v73, v82
	s_waitcnt lgkmcnt(0)
	v_add_f32_e32 v82, v82, v83
	ds_bpermute_b32 v83, v74, v82
	s_waitcnt lgkmcnt(0)
	v_add_f32_e32 v82, v82, v83
	ds_bpermute_b32 v83, v75, v82
	s_waitcnt lgkmcnt(0)
	v_add_f32_e32 v82, v82, v83
	ds_bpermute_b32 v83, v76, v82
	s_waitcnt lgkmcnt(0)
; DI unsigned pk2(float lo, float hi) { return pg8::cvt_pk_bf16(lo, hi); }
; DI void prenorm_rows(const float* X, const float* gvec, const float* ada, int sh_off, int sc_off, bf16* U, int row_lo, int row_hi, int gw, int ngw, int lane) {
;     ...
;         f32x4 v[4]; float ss = 0.f;
; #pragma unroll
;         for (int j = 0; j < 4; ++j) v[j] = nx[j];
;         if (m + 1 < m1) {
; #pragma unroll
;             for (int j = 0; j < 4; ++j) nx[j] = *(const f32x4*)(X + (size_t)(m + 1) * 1024 + 4 * lane + 256 * j);
;         }
;         if (b != curb) { curb = b;
; #pragma unroll
;             for (int j = 0; j < 4; ++j) { const int col = 4 * lane + 256 * j; const f32x4 g = *(const f32x4*)(gvec + col), sc = *(const f32x4*)(ada + (size_t)b * 6144 + sc_off + col);
;                 mul[j] = g * (sc + 1.0f); add[j] = *(const f32x4*)(ada + (size_t)b * 6144 + sh_off + col); } }
; #pragma unroll
;         for (int j = 0; j < 4; ++j) ss += (v[j][0] * v[j][0] + v[j][1] * v[j][1]) + (v[j][2] * v[j][2] + v[j][3] * v[j][3]);
;         const float rstd = rsqrtf(wave_sum(ss) * (1.0f / 1024.0f) + 1e-6f);
; #pragma unroll
;         for (int j = 0; j < 4; ++j) { const f32x4 o = (v[j] * rstd) * mul[j] + add[j]; v2u w; w.x = pk2(o[0], o[1]); w.y = pk2(o[2], o[3]);
;             *(v2u*)(U + (size_t)m * 1024 + 4 * lane + 256 * j) = w; }
	v_add_f32_e32 v82, v82, v83
	v_fmamk_f32 v82, v82, 0x3a800000, v81
	v_mul_f32_e32 v83, 0x4b800000, v82
	v_cmp_gt_f32_e32 vcc, s7, v82
	s_nop 1
	v_cndmask_b32_e32 v82, v82, v83, vcc
	v_rsq_f32_e32 v82, v82
	s_nop 0
	v_mul_f32_e32 v83, 0x45800000, v82
	v_cndmask_b32_e32 v82, v82, v83, vcc
	v_pk_mul_f32 v[44:45], v[44:45], v[82:83] op_sel_hi:[1,0]
	v_pk_mul_f32 v[40:41], v[40:41], v[82:83] op_sel_hi:[1,0]
	v_pk_mul_f32 v[36:37], v[36:37], v[82:83] op_sel_hi:[1,0]
	v_pk_mul_f32 v[32:33], v[32:33], v[82:83] op_sel_hi:[1,0]
	v_pk_mul_f32 v[46:47], v[46:47], v[82:83] op_sel_hi:[1,0]
	v_pk_mul_f32 v[42:43], v[42:43], v[82:83] op_sel_hi:[1,0]
	v_pk_fma_f32 v[44:45], v[48:49], v[44:45], v[28:29]
	v_pk_fma_f32 v[40:41], v[52:53], v[40:41], v[24:25]
	v_pk_mul_f32 v[38:39], v[38:39], v[82:83] op_sel_hi:[1,0]
	v_pk_fma_f32 v[36:37], v[56:57], v[36:37], v[20:21]
	v_pk_mul_f32 v[34:35], v[34:35], v[82:83] op_sel_hi:[1,0]
	v_pk_fma_f32 v[32:33], v[60:61], v[32:33], v[16:17]
	v_pk_fma_f32 v[46:47], v[50:51], v[46:47], v[30:31]
	v_pk_fma_f32 v[42:43], v[54:55], v[42:43], v[26:27]
	v_cvt_pk_bf16_f32 v44, v44, v45
	v_cvt_pk_bf16_f32 v45, v46, v47
	global_store_dwordx2 v[66:67], v[44:45], off
	v_cvt_pk_bf16_f32 v40, v40, v41
	v_cvt_pk_bf16_f32 v41, v42, v43
	global_store_dwordx2 v[66:67], v[40:41], off offset:512
	v_pk_fma_f32 v[38:39], v[58:59], v[38:39], v[22:23]
	v_cvt_pk_bf16_f32 v36, v36, v37
	v_pk_fma_f32 v[34:35], v[62:63], v[34:35], v[18:19]
	v_cvt_pk_bf16_f32 v37, v38, v39
	global_store_dwordx2 v[66:67], v[36:37], off offset:1024
	v_cvt_pk_bf16_f32 v32, v32, v33
	v_cvt_pk_bf16_f32 v33, v34, v35
	global_store_dwordx2 v[66:67], v[32:33], off offset:1536
	v_lshl_add_u64 v[66:67], v[66:67], 0, s[2:3]
	global_load_dwordx4 v[44:47], v[68:69], off
	global_load_dwordx4 v[40:43], v[68:69], off offset:1024
	global_load_dwordx4 v[36:39], v[68:69], off offset:2048
	global_load_dwordx4 v[32:35], v[68:69], off offset:3072
	v_lshl_add_u64 v[68:69], v[68:69], 0, s[0:1]
	s_waitcnt vmcnt(24)
	v_pk_mul_f32 v[82:83], v[8:9], v[8:9]
	v_pk_mul_f32 v[84:85], v[10:11], v[10:11]
	v_pk_mul_f32 v[86:87], v[12:13], v[12:13]
	v_pk_mul_f32 v[88:89], v[14:15], v[14:15]
	v_mov_b32_e32 v90, v86
	v_mov_b32_e32 v91, v89
	v_pk_mov_b32 v[86:87], v[86:87], v[88:89] op_sel:[1,0]
	v_mov_b32_e32 v88, v82
	v_mov_b32_e32 v89, v85
	v_pk_mov_b32 v[82:83], v[82:83], v[84:85] op_sel:[1,0]
	v_pk_add_f32 v[86:87], v[86:87], v[90:91]
	v_pk_add_f32 v[82:83], v[82:83], v[88:89]
	v_pk_add_f32 v[86:87], v[86:87], v[86:87] op_sel_hi:[0,1]
	v_pk_add_f32 v[82:83], v[82:83], v[82:83] op_sel_hi:[0,1]
	v_mul_f32_e32 v82, v4, v4
	v_pk_fma_f32 v[84:85], v[4:5], v[4:5], v[82:83] op_sel_hi:[1,1,0]
	v_mul_f32_e32 v82, v6, v6
	v_pk_fma_f32 v[88:89], v[6:7], v[6:7], v[82:83] op_sel_hi:[1,1,0]
	v_mul_f32_e32 v84, v0, v0
	v_mul_f32_e32 v88, v1, v1
	v_mul_f32_e32 v86, v2, v2
	v_mul_f32_e32 v82, v3, v3
	v_pk_add_f32 v[84:85], v[84:85], v[88:89]
	v_pk_add_f32 v[82:83], v[86:87], v[82:83]
	v_pk_add_f32 v[82:83], v[84:85], v[82:83]
	v_add_f32_e32 v82, v82, v83
	ds_bpermute_b32 v83, v71, v82
	s_waitcnt lgkmcnt(0)
	v_add_f32_e32 v82, v82, v83
	ds_bpermute_b32 v83, v72, v82
	s_waitcnt lgkmcnt(0)
	v_add_f32_e32 v82, v82, v83
	ds_bpermute_b32 v83, v73, v82
	s_waitcnt lgkmcnt(0)
	v_add_f32_e32 v82, v82, v83
	ds_bpermute_b32 v83, v74, v82
	s_waitcnt lgkmcnt(0)
	v_add_f32_e32 v82, v82, v83
	ds_bpermute_b32 v83, v75, v82
	s_waitcnt lgkmcnt(0)
	v_add_f32_e32 v82, v82, v83
	ds_bpermute_b32 v83, v76, v82
	s_waitcnt lgkmcnt(0)
	v_add_f32_e32 v82, v82, v83
	v_fmamk_f32 v82, v82, 0x3a800000, v81
	v_mul_f32_e32 v83, 0x4b800000, v82
	v_cmp_gt_f32_e32 vcc, s7, v82
	s_nop 1
	v_cndmask_b32_e32 v82, v82, v83, vcc
	v_rsq_f32_e32 v82, v82
	s_nop 0
	v_mul_f32_e32 v83, 0x45800000, v82
	v_cndmask_b32_e32 v82, v82, v83, vcc
	v_pk_mul_f32 v[12:13], v[12:13], v[82:83] op_sel_hi:[1,0]
	v_pk_mul_f32 v[8:9], v[8:9], v[82:83] op_sel_hi:[1,0]
	v_pk_mul_f32 v[4:5], v[4:5], v[82:83] op_sel_hi:[1,0]
	v_pk_mul_f32 v[0:1], v[0:1], v[82:83] op_sel_hi:[1,0]
	v_pk_mul_f32 v[14:15], v[14:15], v[82:83] op_sel_hi:[1,0]
	v_pk_mul_f32 v[10:11], v[10:11], v[82:83] op_sel_hi:[1,0]
	v_pk_fma_f32 v[12:13], v[48:49], v[12:13], v[28:29]
	v_pk_fma_f32 v[8:9], v[52:53], v[8:9], v[24:25]
	v_pk_mul_f32 v[6:7], v[6:7], v[82:83] op_sel_hi:[1,0]
	v_pk_fma_f32 v[4:5], v[56:57], v[4:5], v[20:21]
	v_pk_mul_f32 v[2:3], v[2:3], v[82:83] op_sel_hi:[1,0]
	v_pk_fma_f32 v[0:1], v[60:61], v[0:1], v[16:17]
	v_pk_fma_f32 v[14:15], v[50:51], v[14:15], v[30:31]
	v_pk_fma_f32 v[10:11], v[54:55], v[10:11], v[26:27]
	v_cvt_pk_bf16_f32 v12, v12, v13
	v_cvt_pk_bf16_f32 v13, v14, v15
	global_store_dwordx2 v[66:67], v[12:13], off
	v_cvt_pk_bf16_f32 v8, v8, v9
	v_cvt_pk_bf16_f32 v9, v10, v11
	global_store_dwordx2 v[66:67], v[8:9], off offset:512
	v_pk_fma_f32 v[6:7], v[58:59], v[6:7], v[22:23]
	v_cvt_pk_bf16_f32 v4, v4, v5
	v_pk_fma_f32 v[2:3], v[62:63], v[2:3], v[18:19]
	v_cvt_pk_bf16_f32 v5, v6, v7
	global_store_dwordx2 v[66:67], v[4:5], off offset:1024
	v_cvt_pk_bf16_f32 v0, v0, v1
	v_cvt_pk_bf16_f32 v1, v2, v3
	global_store_dwordx2 v[66:67], v[0:1], off offset:1536
	v_lshl_add_u64 v[66:67], v[66:67], 0, s[2:3]
	global_load_dwordx4 v[12:15], v[68:69], off
	global_load_dwordx4 v[8:11], v[68:69], off offset:1024
	global_load_dwordx4 v[4:7], v[68:69], off offset:2048
	global_load_dwordx4 v[0:3], v[68:69], off offset:3072
	v_lshl_add_u64 v[68:69], v[68:69], 0, s[0:1]
	s_waitcnt vmcnt(24)
; DI unsigned pk2(float lo, float hi) { return pg8::cvt_pk_bf16(lo, hi); }
; DI void prenorm_rows(const float* X, const float* gvec, const float* ada, int sh_off, int sc_off, bf16* U, int row_lo, int row_hi, int gw, int ngw, int lane) {
;     ...
;         f32x4 v[4]; float ss = 0.f;
; #pragma unroll
;         for (int j = 0; j < 4; ++j) v[j] = nx[j];
;         if (m + 1 < m1) {
; #pragma unroll
;             for (int j = 0; j < 4; ++j) nx[j] = *(const f32x4*)(X + (size_t)(m + 1) * 1024 + 4 * lane + 256 * j);
;         }
;         if (b != curb) { curb = b;
; #pragma unroll
;             for (int j = 0; j < 4; ++j) { const int col = 4 * lane + 256 * j; const f32x4 g = *(const f32x4*)(gvec + col), sc = *(const f32x4*)(ada + (size_t)b * 6144 + sc_off + col);
;                 mul[j] = g * (sc + 1.0f); add[j] = *(const f32x4*)(ada + (size_t)b * 6144 + sh_off + col); } }
; #pragma unroll
;         for (int j = 0; j < 4; ++j) ss += (v[j][0] * v[j][0] + v[j][1] * v[j][1]) + (v[j][2] * v[j][2] + v[j][3] * v[j][3]);
;         const float rstd = rsqrtf(wave_sum(ss) * (1.0f / 1024.0f) + 1e-6f);
; #pragma unroll
;         for (int j = 0; j < 4; ++j) { const f32x4 o = (v[j] * rstd) * mul[j] + add[j]; v2u w; w.x = pk2(o[0], o[1]); w.y = pk2(o[2], o[3]);
;             *(v2u*)(U + (size_t)m * 1024 + 4 * lane + 256 * j) = w; }
	v_pk_mul_f32 v[82:83], v[160:161], v[160:161]
	v_pk_mul_f32 v[84:85], v[162:163], v[162:163]
	v_pk_mul_f32 v[86:87], v[164:165], v[164:165]
	v_pk_mul_f32 v[88:89], v[166:167], v[166:167]
	v_mov_b32_e32 v90, v86
	v_mov_b32_e32 v91, v89
	v_pk_mov_b32 v[86:87], v[86:87], v[88:89] op_sel:[1,0]
	v_mov_b32_e32 v88, v82
	v_mov_b32_e32 v89, v85
	v_pk_mov_b32 v[82:83], v[82:83], v[84:85] op_sel:[1,0]
	v_pk_add_f32 v[86:87], v[86:87], v[90:91]
	v_pk_add_f32 v[82:83], v[82:83], v[88:89]
	v_pk_add_f32 v[86:87], v[86:87], v[86:87] op_sel_hi:[0,1]
	v_pk_add_f32 v[82:83], v[82:83], v[82:83] op_sel_hi:[0,1]
	v_mul_f32_e32 v82, v156, v156
	v_pk_fma_f32 v[84:85], v[156:157], v[156:157], v[82:83] op_sel_hi:[1,1,0]
	v_mul_f32_e32 v82, v158, v158
	v_pk_fma_f32 v[88:89], v[158:159], v[158:159], v[82:83] op_sel_hi:[1,1,0]
	v_mul_f32_e32 v84, v152, v152
	v_mul_f32_e32 v88, v153, v153
	v_mul_f32_e32 v86, v154, v154
	v_mul_f32_e32 v82, v155, v155
	v_pk_add_f32 v[84:85], v[84:85], v[88:89]
	v_pk_add_f32 v[82:83], v[86:87], v[82:83]
	v_pk_add_f32 v[82:83], v[84:85], v[82:83]
	v_add_f32_e32 v82, v82, v83
	ds_bpermute_b32 v83, v71, v82
	s_waitcnt lgkmcnt(0)
	v_add_f32_e32 v82, v82, v83
	ds_bpermute_b32 v83, v72, v82
	s_waitcnt lgkmcnt(0)
	v_add_f32_e32 v82, v82, v83
	ds_bpermute_b32 v83, v73, v82
	s_waitcnt lgkmcnt(0)
	v_add_f32_e32 v82, v82, v83
	ds_bpermute_b32 v83, v74, v82
	s_waitcnt lgkmcnt(0)
	v_add_f32_e32 v82, v82, v83
	ds_bpermute_b32 v83, v75, v82
	s_waitcnt lgkmcnt(0)
	v_add_f32_e32 v82, v82, v83
	ds_bpermute_b32 v83, v76, v82
	s_waitcnt lgkmcnt(0)
	v_add_f32_e32 v82, v82, v83
	v_fmamk_f32 v82, v82, 0x3a800000, v81
	v_mul_f32_e32 v83, 0x4b800000, v82
	v_cmp_gt_f32_e32 vcc, s7, v82
	s_nop 1
	v_cndmask_b32_e32 v82, v82, v83, vcc
	v_rsq_f32_e32 v82, v82
	s_nop 0
	v_mul_f32_e32 v83, 0x45800000, v82
	v_cndmask_b32_e32 v82, v82, v83, vcc
	v_pk_mul_f32 v[164:165], v[164:165], v[82:83] op_sel_hi:[1,0]
	v_pk_mul_f32 v[160:161], v[160:161], v[82:83] op_sel_hi:[1,0]
	v_pk_mul_f32 v[156:157], v[156:157], v[82:83] op_sel_hi:[1,0]
	v_pk_mul_f32 v[152:153], v[152:153], v[82:83] op_sel_hi:[1,0]
	v_pk_mul_f32 v[166:167], v[166:167], v[82:83] op_sel_hi:[1,0]
	v_pk_mul_f32 v[162:163], v[162:163], v[82:83] op_sel_hi:[1,0]
	v_pk_fma_f32 v[164:165], v[48:49], v[164:165], v[28:29]
	v_pk_fma_f32 v[160:161], v[52:53], v[160:161], v[24:25]
	v_pk_mul_f32 v[158:159], v[158:159], v[82:83] op_sel_hi:[1,0]
	v_pk_fma_f32 v[156:157], v[56:57], v[156:157], v[20:21]
	v_pk_mul_f32 v[154:155], v[154:155], v[82:83] op_sel_hi:[1,0]
	v_pk_fma_f32 v[152:153], v[60:61], v[152:153], v[16:17]
	v_pk_fma_f32 v[166:167], v[50:51], v[166:167], v[30:31]
	v_pk_fma_f32 v[162:163], v[54:55], v[162:163], v[26:27]
	v_cvt_pk_bf16_f32 v164, v164, v165
	v_cvt_pk_bf16_f32 v165, v166, v167
	global_store_dwordx2 v[66:67], v[164:165], off
	v_cvt_pk_bf16_f32 v160, v160, v161
	v_cvt_pk_bf16_f32 v161, v162, v163
	global_store_dwordx2 v[66:67], v[160:161], off offset:512
	v_pk_fma_f32 v[158:159], v[58:59], v[158:159], v[22:23]
	v_cvt_pk_bf16_f32 v156, v156, v157
	v_pk_fma_f32 v[154:155], v[62:63], v[154:155], v[18:19]
	v_cvt_pk_bf16_f32 v157, v158, v159
	global_store_dwordx2 v[66:67], v[156:157], off offset:1024
	v_cvt_pk_bf16_f32 v152, v152, v153
	v_cvt_pk_bf16_f32 v153, v154, v155
	global_store_dwordx2 v[66:67], v[152:153], off offset:1536
	v_lshl_add_u64 v[66:67], v[66:67], 0, s[2:3]
	global_load_dwordx4 v[164:167], v[68:69], off
	global_load_dwordx4 v[160:163], v[68:69], off offset:1024
	global_load_dwordx4 v[156:159], v[68:69], off offset:2048
	global_load_dwordx4 v[152:155], v[68:69], off offset:3072
	v_lshl_add_u64 v[68:69], v[68:69], 0, s[0:1]
	s_waitcnt vmcnt(24)
	v_pk_mul_f32 v[82:83], v[176:177], v[176:177]
	v_pk_mul_f32 v[84:85], v[178:179], v[178:179]
	v_pk_mul_f32 v[86:87], v[180:181], v[180:181]
	v_pk_mul_f32 v[88:89], v[182:183], v[182:183]
	v_mov_b32_e32 v90, v86
	v_mov_b32_e32 v91, v89
	v_pk_mov_b32 v[86:87], v[86:87], v[88:89] op_sel:[1,0]
	v_mov_b32_e32 v88, v82
	v_mov_b32_e32 v89, v85
	v_pk_mov_b32 v[82:83], v[82:83], v[84:85] op_sel:[1,0]
	v_pk_add_f32 v[86:87], v[86:87], v[90:91]
	v_pk_add_f32 v[82:83], v[82:83], v[88:89]
	v_pk_add_f32 v[86:87], v[86:87], v[86:87] op_sel_hi:[0,1]
	v_pk_add_f32 v[82:83], v[82:83], v[82:83] op_sel_hi:[0,1]
	v_mul_f32_e32 v82, v172, v172
	v_pk_fma_f32 v[84:85], v[172:173], v[172:173], v[82:83] op_sel_hi:[1,1,0]
	v_mul_f32_e32 v82, v174, v174
	v_pk_fma_f32 v[88:89], v[174:175], v[174:175], v[82:83] op_sel_hi:[1,1,0]
	v_mul_f32_e32 v84, v168, v168
	v_mul_f32_e32 v88, v169, v169
	v_mul_f32_e32 v86, v170, v170
	v_mul_f32_e32 v82, v171, v171
	v_pk_add_f32 v[84:85], v[84:85], v[88:89]
	v_pk_add_f32 v[82:83], v[86:87], v[82:83]
	v_pk_add_f32 v[82:83], v[84:85], v[82:83]
	v_add_f32_e32 v82, v82, v83
	ds_bpermute_b32 v83, v71, v82
	s_waitcnt lgkmcnt(0)
	v_add_f32_e32 v82, v82, v83
	ds_bpermute_b32 v83, v72, v82
	s_waitcnt lgkmcnt(0)
	v_add_f32_e32 v82, v82, v83
	ds_bpermute_b32 v83, v73, v82
	s_waitcnt lgkmcnt(0)
	v_add_f32_e32 v82, v82, v83
	ds_bpermute_b32 v83, v74, v82
	s_waitcnt lgkmcnt(0)
	v_add_f32_e32 v82, v82, v83
	ds_bpermute_b32 v83, v75, v82
	s_waitcnt lgkmcnt(0)
	v_add_f32_e32 v82, v82, v83
	ds_bpermute_b32 v83, v76, v82
	s_waitcnt lgkmcnt(0)
; DI unsigned pk2(float lo, float hi) { return pg8::cvt_pk_bf16(lo, hi); }
; DI void prenorm_rows(const float* X, const float* gvec, const float* ada, int sh_off, int sc_off, bf16* U, int row_lo, int row_hi, int gw, int ngw, int lane) {
;     ...
;         f32x4 v[4]; float ss = 0.f;
; #pragma unroll
;         for (int j = 0; j < 4; ++j) v[j] = nx[j];
;         if (m + 1 < m1) {
; #pragma unroll
;             for (int j = 0; j < 4; ++j) nx[j] = *(const f32x4*)(X + (size_t)(m + 1) * 1024 + 4 * lane + 256 * j);
;         }
;         if (b != curb) { curb = b;
; #pragma unroll
;             for (int j = 0; j < 4; ++j) { const int col = 4 * lane + 256 * j; const f32x4 g = *(const f32x4*)(gvec + col), sc = *(const f32x4*)(ada + (size_t)b * 6144 + sc_off + col);
;                 mul[j] = g * (sc + 1.0f); add[j] = *(const f32x4*)(ada + (size_t)b * 6144 + sh_off + col); } }
; #pragma unroll
;         for (int j = 0; j < 4; ++j) ss += (v[j][0] * v[j][0] + v[j][1] * v[j][1]) + (v[j][2] * v[j][2] + v[j][3] * v[j][3]);
;         const float rstd = rsqrtf(wave_sum(ss) * (1.0f / 1024.0f) + 1e-6f);
; #pragma unroll
;         for (int j = 0; j < 4; ++j) { const f32x4 o = (v[j] * rstd) * mul[j] + add[j]; v2u w; w.x = pk2(o[0], o[1]); w.y = pk2(o[2], o[3]);
;             *(v2u*)(U + (size_t)m * 1024 + 4 * lane + 256 * j) = w; }
	v_add_f32_e32 v82, v82, v83
	v_fmamk_f32 v82, v82, 0x3a800000, v81
	v_mul_f32_e32 v83, 0x4b800000, v82
	v_cmp_gt_f32_e32 vcc, s7, v82
	s_nop 1
	v_cndmask_b32_e32 v82, v82, v83, vcc
	v_rsq_f32_e32 v82, v82
	s_nop 0
	v_mul_f32_e32 v83, 0x45800000, v82
	v_cndmask_b32_e32 v82, v82, v83, vcc
	v_pk_mul_f32 v[180:181], v[180:181], v[82:83] op_sel_hi:[1,0]
	v_pk_mul_f32 v[176:177], v[176:177], v[82:83] op_sel_hi:[1,0]
	v_pk_mul_f32 v[172:173], v[172:173], v[82:83] op_sel_hi:[1,0]
	v_pk_mul_f32 v[168:169], v[168:169], v[82:83] op_sel_hi:[1,0]
	v_pk_mul_f32 v[182:183], v[182:183], v[82:83] op_sel_hi:[1,0]
	v_pk_mul_f32 v[178:179], v[178:179], v[82:83] op_sel_hi:[1,0]
	v_pk_fma_f32 v[180:181], v[48:49], v[180:181], v[28:29]
	v_pk_fma_f32 v[176:177], v[52:53], v[176:177], v[24:25]
	v_pk_mul_f32 v[174:175], v[174:175], v[82:83] op_sel_hi:[1,0]
	v_pk_fma_f32 v[172:173], v[56:57], v[172:173], v[20:21]
	v_pk_mul_f32 v[170:171], v[170:171], v[82:83] op_sel_hi:[1,0]
	v_pk_fma_f32 v[168:169], v[60:61], v[168:169], v[16:17]
	v_pk_fma_f32 v[182:183], v[50:51], v[182:183], v[30:31]
	v_pk_fma_f32 v[178:179], v[54:55], v[178:179], v[26:27]
	v_cvt_pk_bf16_f32 v180, v180, v181
	v_cvt_pk_bf16_f32 v181, v182, v183
	global_store_dwordx2 v[66:67], v[180:181], off
	v_cvt_pk_bf16_f32 v176, v176, v177
	v_cvt_pk_bf16_f32 v177, v178, v179
	global_store_dwordx2 v[66:67], v[176:177], off offset:512
	v_pk_fma_f32 v[174:175], v[58:59], v[174:175], v[22:23]
	v_cvt_pk_bf16_f32 v172, v172, v173
	v_pk_fma_f32 v[170:171], v[62:63], v[170:171], v[18:19]
	v_cvt_pk_bf16_f32 v173, v174, v175
	global_store_dwordx2 v[66:67], v[172:173], off offset:1024
	v_cvt_pk_bf16_f32 v168, v168, v169
	v_cvt_pk_bf16_f32 v169, v170, v171
	global_store_dwordx2 v[66:67], v[168:169], off offset:1536
	v_lshl_add_u64 v[66:67], v[66:67], 0, s[2:3]
	global_load_dwordx4 v[180:183], v[68:69], off
	global_load_dwordx4 v[176:179], v[68:69], off offset:1024
	global_load_dwordx4 v[172:175], v[68:69], off offset:2048
	global_load_dwordx4 v[168:171], v[68:69], off offset:3072
	v_lshl_add_u64 v[68:69], v[68:69], 0, s[0:1]
	s_waitcnt vmcnt(24)
	v_pk_mul_f32 v[82:83], v[40:41], v[40:41]
	v_pk_mul_f32 v[84:85], v[42:43], v[42:43]
	v_pk_mul_f32 v[86:87], v[44:45], v[44:45]
	v_pk_mul_f32 v[88:89], v[46:47], v[46:47]
	v_mov_b32_e32 v90, v86
	v_mov_b32_e32 v91, v89
	v_pk_mov_b32 v[86:87], v[86:87], v[88:89] op_sel:[1,0]
	v_mov_b32_e32 v88, v82
	v_mov_b32_e32 v89, v85
	v_pk_mov_b32 v[82:83], v[82:83], v[84:85] op_sel:[1,0]
	v_pk_add_f32 v[86:87], v[86:87], v[90:91]
	v_pk_add_f32 v[82:83], v[82:83], v[88:89]
	v_pk_add_f32 v[86:87], v[86:87], v[86:87] op_sel_hi:[0,1]
	v_pk_add_f32 v[82:83], v[82:83], v[82:83] op_sel_hi:[0,1]
	v_mul_f32_e32 v82, v36, v36
	v_pk_fma_f32 v[84:85], v[36:37], v[36:37], v[82:83] op_sel_hi:[1,1,0]
	v_mul_f32_e32 v82, v38, v38
	v_pk_fma_f32 v[88:89], v[38:39], v[38:39], v[82:83] op_sel_hi:[1,1,0]
	v_mul_f32_e32 v84, v32, v32
	v_mul_f32_e32 v88, v33, v33
	v_mul_f32_e32 v86, v34, v34
	v_mul_f32_e32 v82, v35, v35
	v_pk_add_f32 v[84:85], v[84:85], v[88:89]
	v_pk_add_f32 v[82:83], v[86:87], v[82:83]
	v_pk_add_f32 v[82:83], v[84:85], v[82:83]
	v_add_f32_e32 v82, v82, v83
	ds_bpermute_b32 v83, v71, v82
	s_waitcnt lgkmcnt(0)
	v_add_f32_e32 v82, v82, v83
	ds_bpermute_b32 v83, v72, v82
	s_waitcnt lgkmcnt(0)
	v_add_f32_e32 v82, v82, v83
	ds_bpermute_b32 v83, v73, v82
	s_waitcnt lgkmcnt(0)
	v_add_f32_e32 v82, v82, v83
	ds_bpermute_b32 v83, v74, v82
	s_waitcnt lgkmcnt(0)
	v_add_f32_e32 v82, v82, v83
	ds_bpermute_b32 v83, v75, v82
	s_waitcnt lgkmcnt(0)
	v_add_f32_e32 v82, v82, v83
	ds_bpermute_b32 v83, v76, v82
	s_waitcnt lgkmcnt(0)
	v_add_f32_e32 v82, v82, v83
	v_fmamk_f32 v82, v82, 0x3a800000, v81
	v_mul_f32_e32 v83, 0x4b800000, v82
	v_cmp_gt_f32_e32 vcc, s7, v82
	s_nop 1
	v_cndmask_b32_e32 v82, v82, v83, vcc
	v_rsq_f32_e32 v82, v82
	s_nop 0
	v_mul_f32_e32 v83, 0x45800000, v82
	v_cndmask_b32_e32 v82, v82, v83, vcc
	v_pk_mul_f32 v[44:45], v[44:45], v[82:83] op_sel_hi:[1,0]
	v_pk_mul_f32 v[40:41], v[40:41], v[82:83] op_sel_hi:[1,0]
	v_pk_mul_f32 v[36:37], v[36:37], v[82:83] op_sel_hi:[1,0]
	v_pk_mul_f32 v[32:33], v[32:33], v[82:83] op_sel_hi:[1,0]
	v_pk_mul_f32 v[46:47], v[46:47], v[82:83] op_sel_hi:[1,0]
	v_pk_mul_f32 v[42:43], v[42:43], v[82:83] op_sel_hi:[1,0]
	v_pk_fma_f32 v[44:45], v[48:49], v[44:45], v[28:29]
	v_pk_fma_f32 v[40:41], v[52:53], v[40:41], v[24:25]
	v_pk_mul_f32 v[38:39], v[38:39], v[82:83] op_sel_hi:[1,0]
	v_pk_fma_f32 v[36:37], v[56:57], v[36:37], v[20:21]
	v_pk_mul_f32 v[34:35], v[34:35], v[82:83] op_sel_hi:[1,0]
	v_pk_fma_f32 v[32:33], v[60:61], v[32:33], v[16:17]
	v_pk_fma_f32 v[46:47], v[50:51], v[46:47], v[30:31]
	v_pk_fma_f32 v[42:43], v[54:55], v[42:43], v[26:27]
	v_cvt_pk_bf16_f32 v44, v44, v45
	v_cvt_pk_bf16_f32 v45, v46, v47
	global_store_dwordx2 v[66:67], v[44:45], off
	v_cvt_pk_bf16_f32 v40, v40, v41
	v_cvt_pk_bf16_f32 v41, v42, v43
	global_store_dwordx2 v[66:67], v[40:41], off offset:512
	v_pk_fma_f32 v[38:39], v[58:59], v[38:39], v[22:23]
	v_cvt_pk_bf16_f32 v36, v36, v37
	v_pk_fma_f32 v[34:35], v[62:63], v[34:35], v[18:19]
	v_cvt_pk_bf16_f32 v37, v38, v39
	global_store_dwordx2 v[66:67], v[36:37], off offset:1024
	v_cvt_pk_bf16_f32 v32, v32, v33
	v_cvt_pk_bf16_f32 v33, v34, v35
	global_store_dwordx2 v[66:67], v[32:33], off offset:1536
	v_lshl_add_u64 v[66:67], v[66:67], 0, s[2:3]
	global_load_dwordx4 v[44:47], v[68:69], off
	global_load_dwordx4 v[40:43], v[68:69], off offset:1024
	global_load_dwordx4 v[36:39], v[68:69], off offset:2048
	global_load_dwordx4 v[32:35], v[68:69], off offset:3072
	v_lshl_add_u64 v[68:69], v[68:69], 0, s[0:1]
	s_waitcnt vmcnt(24)
; DI unsigned pk2(float lo, float hi) { return pg8::cvt_pk_bf16(lo, hi); }
; DI void prenorm_rows(const float* X, const float* gvec, const float* ada, int sh_off, int sc_off, bf16* U, int row_lo, int row_hi, int gw, int ngw, int lane) {
;     ...
;         f32x4 v[4]; float ss = 0.f;
; #pragma unroll
;         for (int j = 0; j < 4; ++j) v[j] = nx[j];
;         if (m + 1 < m1) {
; #pragma unroll
;             for (int j = 0; j < 4; ++j) nx[j] = *(const f32x4*)(X + (size_t)(m + 1) * 1024 + 4 * lane + 256 * j);
;         }
;         if (b != curb) { curb = b;
; #pragma unroll
;             for (int j = 0; j < 4; ++j) { const int col = 4 * lane + 256 * j; const f32x4 g = *(const f32x4*)(gvec + col), sc = *(const f32x4*)(ada + (size_t)b * 6144 + sc_off + col);
;                 mul[j] = g * (sc + 1.0f); add[j] = *(const f32x4*)(ada + (size_t)b * 6144 + sh_off + col); } }
; #pragma unroll
;         for (int j = 0; j < 4; ++j) ss += (v[j][0] * v[j][0] + v[j][1] * v[j][1]) + (v[j][2] * v[j][2] + v[j][3] * v[j][3]);
;         const float rstd = rsqrtf(wave_sum(ss) * (1.0f / 1024.0f) + 1e-6f);
; #pragma unroll
;         for (int j = 0; j < 4; ++j) { const f32x4 o = (v[j] * rstd) * mul[j] + add[j]; v2u w; w.x = pk2(o[0], o[1]); w.y = pk2(o[2], o[3]);
;             *(v2u*)(U + (size_t)m * 1024 + 4 * lane + 256 * j) = w; }
	v_pk_mul_f32 v[82:83], v[8:9], v[8:9]
	v_pk_mul_f32 v[84:85], v[10:11], v[10:11]
	v_pk_mul_f32 v[86:87], v[12:13], v[12:13]
	v_pk_mul_f32 v[88:89], v[14:15], v[14:15]
	v_mov_b32_e32 v90, v86
	v_mov_b32_e32 v91, v89
	v_pk_mov_b32 v[86:87], v[86:87], v[88:89] op_sel:[1,0]
	v_mov_b32_e32 v88, v82
	v_mov_b32_e32 v89, v85
	v_pk_mov_b32 v[82:83], v[82:83], v[84:85] op_sel:[1,0]
	v_pk_add_f32 v[86:87], v[86:87], v[90:91]
	v_pk_add_f32 v[82:83], v[82:83], v[88:89]
	v_pk_add_f32 v[86:87], v[86:87], v[86:87] op_sel_hi:[0,1]
	v_pk_add_f32 v[82:83], v[82:83], v[82:83] op_sel_hi:[0,1]
	v_mul_f32_e32 v82, v4, v4
	v_pk_fma_f32 v[84:85], v[4:5], v[4:5], v[82:83] op_sel_hi:[1,1,0]
	v_mul_f32_e32 v82, v6, v6
	v_pk_fma_f32 v[88:89], v[6:7], v[6:7], v[82:83] op_sel_hi:[1,1,0]
	v_mul_f32_e32 v84, v0, v0
	v_mul_f32_e32 v88, v1, v1
	v_mul_f32_e32 v86, v2, v2
	v_mul_f32_e32 v82, v3, v3
	v_pk_add_f32 v[84:85], v[84:85], v[88:89]
	v_pk_add_f32 v[82:83], v[86:87], v[82:83]
	v_pk_add_f32 v[82:83], v[84:85], v[82:83]
	v_add_f32_e32 v82, v82, v83
	ds_bpermute_b32 v83, v71, v82
	s_waitcnt lgkmcnt(0)
	v_add_f32_e32 v82, v82, v83
	ds_bpermute_b32 v83, v72, v82
	s_waitcnt lgkmcnt(0)
	v_add_f32_e32 v82, v82, v83
	ds_bpermute_b32 v83, v73, v82
	s_waitcnt lgkmcnt(0)
	v_add_f32_e32 v82, v82, v83
	ds_bpermute_b32 v83, v74, v82
	s_waitcnt lgkmcnt(0)
	v_add_f32_e32 v82, v82, v83
	ds_bpermute_b32 v83, v75, v82
	s_waitcnt lgkmcnt(0)
	v_add_f32_e32 v82, v82, v83
	ds_bpermute_b32 v83, v76, v82
	s_waitcnt lgkmcnt(0)
	v_add_f32_e32 v82, v82, v83
	v_fmamk_f32 v82, v82, 0x3a800000, v81
	v_mul_f32_e32 v83, 0x4b800000, v82
	v_cmp_gt_f32_e32 vcc, s7, v82
	s_nop 1
	v_cndmask_b32_e32 v82, v82, v83, vcc
	v_rsq_f32_e32 v82, v82
	s_nop 0
	v_mul_f32_e32 v83, 0x45800000, v82
	v_cndmask_b32_e32 v82, v82, v83, vcc
	v_pk_mul_f32 v[12:13], v[12:13], v[82:83] op_sel_hi:[1,0]
	v_pk_mul_f32 v[8:9], v[8:9], v[82:83] op_sel_hi:[1,0]
	v_pk_mul_f32 v[4:5], v[4:5], v[82:83] op_sel_hi:[1,0]
	v_pk_mul_f32 v[0:1], v[0:1], v[82:83] op_sel_hi:[1,0]
	v_pk_mul_f32 v[14:15], v[14:15], v[82:83] op_sel_hi:[1,0]
	v_pk_mul_f32 v[10:11], v[10:11], v[82:83] op_sel_hi:[1,0]
	v_pk_fma_f32 v[12:13], v[48:49], v[12:13], v[28:29]
	v_pk_fma_f32 v[8:9], v[52:53], v[8:9], v[24:25]
	v_pk_mul_f32 v[6:7], v[6:7], v[82:83] op_sel_hi:[1,0]
	v_pk_fma_f32 v[4:5], v[56:57], v[4:5], v[20:21]
	v_pk_mul_f32 v[2:3], v[2:3], v[82:83] op_sel_hi:[1,0]
	v_pk_fma_f32 v[0:1], v[60:61], v[0:1], v[16:17]
	v_pk_fma_f32 v[14:15], v[50:51], v[14:15], v[30:31]
	v_pk_fma_f32 v[10:11], v[54:55], v[10:11], v[26:27]
	v_cvt_pk_bf16_f32 v12, v12, v13
	v_cvt_pk_bf16_f32 v13, v14, v15
	global_store_dwordx2 v[66:67], v[12:13], off
	v_cvt_pk_bf16_f32 v8, v8, v9
	v_cvt_pk_bf16_f32 v9, v10, v11
	global_store_dwordx2 v[66:67], v[8:9], off offset:512
	v_pk_fma_f32 v[6:7], v[58:59], v[6:7], v[22:23]
	v_cvt_pk_bf16_f32 v4, v4, v5
	v_pk_fma_f32 v[2:3], v[62:63], v[2:3], v[18:19]
	v_cvt_pk_bf16_f32 v5, v6, v7
	global_store_dwordx2 v[66:67], v[4:5], off offset:1024
	v_cvt_pk_bf16_f32 v0, v0, v1
	v_cvt_pk_bf16_f32 v1, v2, v3
	global_store_dwordx2 v[66:67], v[0:1], off offset:1536
	v_lshl_add_u64 v[66:67], v[66:67], 0, s[2:3]
	global_load_dwordx4 v[12:15], v[68:69], off
	global_load_dwordx4 v[8:11], v[68:69], off offset:1024
	global_load_dwordx4 v[4:7], v[68:69], off offset:2048
	global_load_dwordx4 v[0:3], v[68:69], off offset:3072
	v_lshl_add_u64 v[68:69], v[68:69], 0, s[0:1]
	s_waitcnt vmcnt(24)
	v_pk_mul_f32 v[82:83], v[160:161], v[160:161]
	v_pk_mul_f32 v[84:85], v[162:163], v[162:163]
	v_pk_mul_f32 v[86:87], v[164:165], v[164:165]
	v_pk_mul_f32 v[88:89], v[166:167], v[166:167]
	v_mov_b32_e32 v90, v86
	v_mov_b32_e32 v91, v89
	v_pk_mov_b32 v[86:87], v[86:87], v[88:89] op_sel:[1,0]
	v_mov_b32_e32 v88, v82
	v_mov_b32_e32 v89, v85
	v_pk_mov_b32 v[82:83], v[82:83], v[84:85] op_sel:[1,0]
	v_pk_add_f32 v[86:87], v[86:87], v[90:91]
	v_pk_add_f32 v[82:83], v[82:83], v[88:89]
	v_pk_add_f32 v[86:87], v[86:87], v[86:87] op_sel_hi:[0,1]
	v_pk_add_f32 v[82:83], v[82:83], v[82:83] op_sel_hi:[0,1]
	v_mul_f32_e32 v82, v156, v156
	v_pk_fma_f32 v[84:85], v[156:157], v[156:157], v[82:83] op_sel_hi:[1,1,0]
	v_mul_f32_e32 v82, v158, v158
	v_pk_fma_f32 v[88:89], v[158:159], v[158:159], v[82:83] op_sel_hi:[1,1,0]
	v_mul_f32_e32 v84, v152, v152
	v_mul_f32_e32 v88, v153, v153
	v_mul_f32_e32 v86, v154, v154
	v_mul_f32_e32 v82, v155, v155
	v_pk_add_f32 v[84:85], v[84:85], v[88:89]
	v_pk_add_f32 v[82:83], v[86:87], v[82:83]
	v_pk_add_f32 v[82:83], v[84:85], v[82:83]
	v_add_f32_e32 v82, v82, v83
	ds_bpermute_b32 v83, v71, v82
	s_waitcnt lgkmcnt(0)
	v_add_f32_e32 v82, v82, v83
	ds_bpermute_b32 v83, v72, v82
	s_waitcnt lgkmcnt(0)
	v_add_f32_e32 v82, v82, v83
	ds_bpermute_b32 v83, v73, v82
	s_waitcnt lgkmcnt(0)
	v_add_f32_e32 v82, v82, v83
	ds_bpermute_b32 v83, v74, v82
	s_waitcnt lgkmcnt(0)
	v_add_f32_e32 v82, v82, v83
	ds_bpermute_b32 v83, v75, v82
	s_waitcnt lgkmcnt(0)
	v_add_f32_e32 v82, v82, v83
	ds_bpermute_b32 v83, v76, v82
	s_waitcnt lgkmcnt(0)
; DI unsigned pk2(float lo, float hi) { return pg8::cvt_pk_bf16(lo, hi); }
; DI void prenorm_rows(const float* X, const float* gvec, const float* ada, int sh_off, int sc_off, bf16* U, int row_lo, int row_hi, int gw, int ngw, int lane) {
;     ...
;         f32x4 v[4]; float ss = 0.f;
; #pragma unroll
;         for (int j = 0; j < 4; ++j) v[j] = nx[j];
;         if (m + 1 < m1) {
; #pragma unroll
;             for (int j = 0; j < 4; ++j) nx[j] = *(const f32x4*)(X + (size_t)(m + 1) * 1024 + 4 * lane + 256 * j);
;         }
;         if (b != curb) { curb = b;
; #pragma unroll
;             for (int j = 0; j < 4; ++j) { const int col = 4 * lane + 256 * j; const f32x4 g = *(const f32x4*)(gvec + col), sc = *(const f32x4*)(ada + (size_t)b * 6144 + sc_off + col);
;                 mul[j] = g * (sc + 1.0f); add[j] = *(const f32x4*)(ada + (size_t)b * 6144 + sh_off + col); } }
; #pragma unroll
;         for (int j = 0; j < 4; ++j) ss += (v[j][0] * v[j][0] + v[j][1] * v[j][1]) + (v[j][2] * v[j][2] + v[j][3] * v[j][3]);
;         const float rstd = rsqrtf(wave_sum(ss) * (1.0f / 1024.0f) + 1e-6f);
; #pragma unroll
;         for (int j = 0; j < 4; ++j) { const f32x4 o = (v[j] * rstd) * mul[j] + add[j]; v2u w; w.x = pk2(o[0], o[1]); w.y = pk2(o[2], o[3]);
;             *(v2u*)(U + (size_t)m * 1024 + 4 * lane + 256 * j) = w; }
	v_add_f32_e32 v82, v82, v83
	v_fmamk_f32 v82, v82, 0x3a800000, v81
	v_mul_f32_e32 v83, 0x4b800000, v82
	v_cmp_gt_f32_e32 vcc, s7, v82
	s_nop 1
	v_cndmask_b32_e32 v82, v82, v83, vcc
	v_rsq_f32_e32 v82, v82
	s_nop 0
	v_mul_f32_e32 v83, 0x45800000, v82
	v_cndmask_b32_e32 v82, v82, v83, vcc
	v_pk_mul_f32 v[164:165], v[164:165], v[82:83] op_sel_hi:[1,0]
	v_pk_mul_f32 v[160:161], v[160:161], v[82:83] op_sel_hi:[1,0]
	v_pk_mul_f32 v[156:157], v[156:157], v[82:83] op_sel_hi:[1,0]
	v_pk_mul_f32 v[152:153], v[152:153], v[82:83] op_sel_hi:[1,0]
	v_pk_mul_f32 v[166:167], v[166:167], v[82:83] op_sel_hi:[1,0]
	v_pk_mul_f32 v[162:163], v[162:163], v[82:83] op_sel_hi:[1,0]
	v_pk_fma_f32 v[164:165], v[48:49], v[164:165], v[28:29]
	v_pk_fma_f32 v[160:161], v[52:53], v[160:161], v[24:25]
	v_pk_mul_f32 v[158:159], v[158:159], v[82:83] op_sel_hi:[1,0]
	v_pk_fma_f32 v[156:157], v[56:57], v[156:157], v[20:21]
	v_pk_mul_f32 v[154:155], v[154:155], v[82:83] op_sel_hi:[1,0]
	v_pk_fma_f32 v[152:153], v[60:61], v[152:153], v[16:17]
	v_pk_fma_f32 v[166:167], v[50:51], v[166:167], v[30:31]
	v_pk_fma_f32 v[162:163], v[54:55], v[162:163], v[26:27]
	v_cvt_pk_bf16_f32 v164, v164, v165
	v_cvt_pk_bf16_f32 v165, v166, v167
	global_store_dwordx2 v[66:67], v[164:165], off
	v_cvt_pk_bf16_f32 v160, v160, v161
	v_cvt_pk_bf16_f32 v161, v162, v163
	global_store_dwordx2 v[66:67], v[160:161], off offset:512
	v_pk_fma_f32 v[158:159], v[58:59], v[158:159], v[22:23]
	v_cvt_pk_bf16_f32 v156, v156, v157
	v_pk_fma_f32 v[154:155], v[62:63], v[154:155], v[18:19]
	v_cvt_pk_bf16_f32 v157, v158, v159
	global_store_dwordx2 v[66:67], v[156:157], off offset:1024
	v_cvt_pk_bf16_f32 v152, v152, v153
	v_cvt_pk_bf16_f32 v153, v154, v155
	global_store_dwordx2 v[66:67], v[152:153], off offset:1536
	v_lshl_add_u64 v[66:67], v[66:67], 0, s[2:3]
	global_load_dwordx4 v[164:167], v[68:69], off
	global_load_dwordx4 v[160:163], v[68:69], off offset:1024
	global_load_dwordx4 v[156:159], v[68:69], off offset:2048
	global_load_dwordx4 v[152:155], v[68:69], off offset:3072
	v_lshl_add_u64 v[68:69], v[68:69], 0, s[0:1]
	s_waitcnt vmcnt(24)
	v_pk_mul_f32 v[82:83], v[176:177], v[176:177]
	v_pk_mul_f32 v[84:85], v[178:179], v[178:179]
	v_pk_mul_f32 v[86:87], v[180:181], v[180:181]
	v_pk_mul_f32 v[88:89], v[182:183], v[182:183]
	v_mov_b32_e32 v90, v86
	v_mov_b32_e32 v91, v89
	v_pk_mov_b32 v[86:87], v[86:87], v[88:89] op_sel:[1,0]
	v_mov_b32_e32 v88, v82
	v_mov_b32_e32 v89, v85
	v_pk_mov_b32 v[82:83], v[82:83], v[84:85] op_sel:[1,0]
	v_pk_add_f32 v[86:87], v[86:87], v[90:91]
	v_pk_add_f32 v[82:83], v[82:83], v[88:89]
	v_pk_add_f32 v[86:87], v[86:87], v[86:87] op_sel_hi:[0,1]
	v_pk_add_f32 v[82:83], v[82:83], v[82:83] op_sel_hi:[0,1]
	v_mul_f32_e32 v82, v172, v172
	v_pk_fma_f32 v[84:85], v[172:173], v[172:173], v[82:83] op_sel_hi:[1,1,0]
	v_mul_f32_e32 v82, v174, v174
	v_pk_fma_f32 v[88:89], v[174:175], v[174:175], v[82:83] op_sel_hi:[1,1,0]
	v_mul_f32_e32 v84, v168, v168
	v_mul_f32_e32 v88, v169, v169
	v_mul_f32_e32 v86, v170, v170
	v_mul_f32_e32 v82, v171, v171
	v_pk_add_f32 v[84:85], v[84:85], v[88:89]
	v_pk_add_f32 v[82:83], v[86:87], v[82:83]
	v_pk_add_f32 v[82:83], v[84:85], v[82:83]
	v_add_f32_e32 v82, v82, v83
	ds_bpermute_b32 v83, v71, v82
	s_waitcnt lgkmcnt(0)
	v_add_f32_e32 v82, v82, v83
	ds_bpermute_b32 v83, v72, v82
	s_waitcnt lgkmcnt(0)
	v_add_f32_e32 v82, v82, v83
	ds_bpermute_b32 v83, v73, v82
	s_waitcnt lgkmcnt(0)
	v_add_f32_e32 v82, v82, v83
	ds_bpermute_b32 v83, v74, v82
	s_waitcnt lgkmcnt(0)
	v_add_f32_e32 v82, v82, v83
	ds_bpermute_b32 v83, v75, v82
	s_waitcnt lgkmcnt(0)
	v_add_f32_e32 v82, v82, v83
	ds_bpermute_b32 v83, v76, v82
	s_waitcnt lgkmcnt(0)
	v_add_f32_e32 v82, v82, v83
	v_fmamk_f32 v82, v82, 0x3a800000, v81
	v_mul_f32_e32 v83, 0x4b800000, v82
	v_cmp_gt_f32_e32 vcc, s7, v82
	s_nop 1
	v_cndmask_b32_e32 v82, v82, v83, vcc
	v_rsq_f32_e32 v82, v82
	s_nop 0
	v_mul_f32_e32 v83, 0x45800000, v82
	v_cndmask_b32_e32 v82, v82, v83, vcc
	v_pk_mul_f32 v[180:181], v[180:181], v[82:83] op_sel_hi:[1,0]
	v_pk_mul_f32 v[176:177], v[176:177], v[82:83] op_sel_hi:[1,0]
	v_pk_mul_f32 v[172:173], v[172:173], v[82:83] op_sel_hi:[1,0]
	v_pk_mul_f32 v[168:169], v[168:169], v[82:83] op_sel_hi:[1,0]
	v_pk_mul_f32 v[182:183], v[182:183], v[82:83] op_sel_hi:[1,0]
	v_pk_mul_f32 v[178:179], v[178:179], v[82:83] op_sel_hi:[1,0]
	v_pk_fma_f32 v[180:181], v[48:49], v[180:181], v[28:29]
	v_pk_fma_f32 v[176:177], v[52:53], v[176:177], v[24:25]
	v_pk_mul_f32 v[174:175], v[174:175], v[82:83] op_sel_hi:[1,0]
	v_pk_fma_f32 v[172:173], v[56:57], v[172:173], v[20:21]
	v_pk_mul_f32 v[170:171], v[170:171], v[82:83] op_sel_hi:[1,0]
	v_pk_fma_f32 v[168:169], v[60:61], v[168:169], v[16:17]
	v_pk_fma_f32 v[182:183], v[50:51], v[182:183], v[30:31]
	v_pk_fma_f32 v[178:179], v[54:55], v[178:179], v[26:27]
	v_cvt_pk_bf16_f32 v180, v180, v181
	v_cvt_pk_bf16_f32 v181, v182, v183
	global_store_dwordx2 v[66:67], v[180:181], off
	v_cvt_pk_bf16_f32 v176, v176, v177
	v_cvt_pk_bf16_f32 v177, v178, v179
	global_store_dwordx2 v[66:67], v[176:177], off offset:512
	v_pk_fma_f32 v[174:175], v[58:59], v[174:175], v[22:23]
	v_cvt_pk_bf16_f32 v172, v172, v173
	v_pk_fma_f32 v[170:171], v[62:63], v[170:171], v[18:19]
	v_cvt_pk_bf16_f32 v173, v174, v175
	global_store_dwordx2 v[66:67], v[172:173], off offset:1024
	v_cvt_pk_bf16_f32 v168, v168, v169
	v_cvt_pk_bf16_f32 v169, v170, v171
	global_store_dwordx2 v[66:67], v[168:169], off offset:1536
	v_lshl_add_u64 v[66:67], v[66:67], 0, s[2:3]
	global_load_dwordx4 v[180:183], v[68:69], off
	global_load_dwordx4 v[176:179], v[68:69], off offset:1024
	global_load_dwordx4 v[172:175], v[68:69], off offset:2048
	global_load_dwordx4 v[168:171], v[68:69], off offset:3072
	v_lshl_add_u64 v[68:69], v[68:69], 0, s[0:1]
	s_waitcnt vmcnt(24)
; DI float wave_sum(float v) {
; #pragma unroll
;     for (int o = 1; o < 64; o <<= 1) v += __shfl_xor(v, o);
;     return v;
; DI void prenorm_rows(const float* X, const float* gvec, const float* ada, int sh_off, int sc_off, bf16* U, int row_lo, int row_hi, int gw, int ngw, int lane) {
;     ...
;         f32x4 v[4]; float ss = 0.f;
; #pragma unroll
;         for (int j = 0; j < 4; ++j) v[j] = nx[j];
;         if (m + 1 < m1) {
; #pragma unroll
;             for (int j = 0; j < 4; ++j) nx[j] = *(const f32x4*)(X + (size_t)(m + 1) * 1024 + 4 * lane + 256 * j);
;         }
;         if (b != curb) { curb = b;
; #pragma unroll
;             for (int j = 0; j < 4; ++j) { const int col = 4 * lane + 256 * j; const f32x4 g = *(const f32x4*)(gvec + col), sc = *(const f32x4*)(ada + (size_t)b * 6144 + sc_off + col);
;                 mul[j] = g * (sc + 1.0f); add[j] = *(const f32x4*)(ada + (size_t)b * 6144 + sh_off + col); } }
; #pragma unroll
;         for (int j = 0; j < 4; ++j) ss += (v[j][0] * v[j][0] + v[j][1] * v[j][1]) + (v[j][2] * v[j][2] + v[j][3] * v[j][3]);
;         const float rstd = rsqrtf(wave_sum(ss) * (1.0f / 1024.0f) + 1e-6f);
	v_pk_mul_f32 v[82:83], v[40:41], v[40:41]
	v_pk_mul_f32 v[84:85], v[42:43], v[42:43]
	v_pk_mul_f32 v[86:87], v[44:45], v[44:45]
	v_pk_mul_f32 v[88:89], v[46:47], v[46:47]
	v_mov_b32_e32 v90, v86
	v_mov_b32_e32 v91, v89
	v_pk_mov_b32 v[86:87], v[86:87], v[88:89] op_sel:[1,0]
	v_mov_b32_e32 v88, v82
	v_mov_b32_e32 v89, v85
	v_pk_mov_b32 v[82:83], v[82:83], v[84:85] op_sel:[1,0]
	v_pk_add_f32 v[86:87], v[86:87], v[90:91]
	v_pk_add_f32 v[82:83], v[82:83], v[88:89]
	v_pk_add_f32 v[86:87], v[86:87], v[86:87] op_sel_hi:[0,1]
	v_pk_add_f32 v[82:83], v[82:83], v[82:83] op_sel_hi:[0,1]
	v_mul_f32_e32 v82, v36, v36
	v_pk_fma_f32 v[84:85], v[36:37], v[36:37], v[82:83] op_sel_hi:[1,1,0]
	v_mul_f32_e32 v82, v38, v38
	v_pk_fma_f32 v[88:89], v[38:39], v[38:39], v[82:83] op_sel_hi:[1,1,0]
	v_mul_f32_e32 v84, v32, v32
	v_mul_f32_e32 v88, v33, v33
	v_mul_f32_e32 v86, v34, v34
	v_mul_f32_e32 v82, v35, v35
	v_pk_add_f32 v[84:85], v[84:85], v[88:89]
	v_pk_add_f32 v[82:83], v[86:87], v[82:83]
	v_pk_add_f32 v[82:83], v[84:85], v[82:83]
	v_add_f32_e32 v82, v82, v83
	ds_bpermute_b32 v83, v71, v82
	s_waitcnt lgkmcnt(0)
	v_add_f32_e32 v82, v82, v83
	ds_bpermute_b32 v83, v72, v82
	s_waitcnt lgkmcnt(0)
	v_add_f32_e32 v82, v82, v83
	ds_bpermute_b32 v83, v73, v82
	s_waitcnt lgkmcnt(0)
	v_add_f32_e32 v82, v82, v83
	ds_bpermute_b32 v83, v74, v82
	s_waitcnt lgkmcnt(0)
	v_add_f32_e32 v82, v82, v83
	ds_bpermute_b32 v83, v75, v82
	s_waitcnt lgkmcnt(0)
	v_add_f32_e32 v82, v82, v83
	ds_bpermute_b32 v83, v76, v82
	s_waitcnt lgkmcnt(0)
	v_add_f32_e32 v82, v82, v83
	v_fmamk_f32 v82, v82, 0x3a800000, v81
	v_mul_f32_e32 v83, 0x4b800000, v82
	v_cmp_gt_f32_e32 vcc, s7, v82
	s_nop 1
	v_cndmask_b32_e32 v82, v82, v83, vcc
	v_rsq_f32_e32 v82, v82
	s_nop 0
	v_mul_f32_e32 v83, 0x45800000, v82
	v_cndmask_b32_e32 v82, v82, v83, vcc
	v_pk_mul_f32 v[44:45], v[44:45], v[82:83] op_sel_hi:[1,0]
	v_pk_mul_f32 v[40:41], v[40:41], v[82:83] op_sel_hi:[1,0]
	v_pk_mul_f32 v[36:37], v[36:37], v[82:83] op_sel_hi:[1,0]
	v_pk_mul_f32 v[32:33], v[32:33], v[82:83] op_sel_hi:[1,0]
	v_pk_mul_f32 v[46:47], v[46:47], v[82:83] op_sel_hi:[1,0]
	v_pk_mul_f32 v[42:43], v[42:43], v[82:83] op_sel_hi:[1,0]
	v_pk_fma_f32 v[44:45], v[48:49], v[44:45], v[28:29]
	v_pk_fma_f32 v[40:41], v[52:53], v[40:41], v[24:25]
	v_pk_mul_f32 v[38:39], v[38:39], v[82:83] op_sel_hi:[1,0]
	v_pk_fma_f32 v[36:37], v[56:57], v[36:37], v[20:21]
	v_pk_mul_f32 v[34:35], v[34:35], v[82:83] op_sel_hi:[1,0]
	v_pk_fma_f32 v[32:33], v[60:61], v[32:33], v[16:17]
	v_pk_fma_f32 v[46:47], v[50:51], v[46:47], v[30:31]
	v_pk_fma_f32 v[42:43], v[54:55], v[42:43], v[26:27]
	v_cvt_pk_bf16_f32 v44, v44, v45
	v_cvt_pk_bf16_f32 v45, v46, v47
	global_store_dwordx2 v[66:67], v[44:45], off
	v_cvt_pk_bf16_f32 v40, v40, v41
	v_cvt_pk_bf16_f32 v41, v42, v43
	global_store_dwordx2 v[66:67], v[40:41], off offset:512
	v_pk_fma_f32 v[38:39], v[58:59], v[38:39], v[22:23]
	v_cvt_pk_bf16_f32 v36, v36, v37
	v_pk_fma_f32 v[34:35], v[62:63], v[34:35], v[18:19]
	v_cvt_pk_bf16_f32 v37, v38, v39
	global_store_dwordx2 v[66:67], v[36:37], off offset:1024
	v_cvt_pk_bf16_f32 v32, v32, v33
	v_cvt_pk_bf16_f32 v33, v34, v35
	global_store_dwordx2 v[66:67], v[32:33], off offset:1536
	v_lshl_add_u64 v[66:67], v[66:67], 0, s[2:3]
	global_load_dwordx4 v[44:47], v[68:69], off
	global_load_dwordx4 v[40:43], v[68:69], off offset:1024
	global_load_dwordx4 v[36:39], v[68:69], off offset:2048
	global_load_dwordx4 v[32:35], v[68:69], off offset:3072
	v_lshl_add_u64 v[68:69], v[68:69], 0, s[0:1]
	s_waitcnt vmcnt(24)
	v_pk_mul_f32 v[82:83], v[8:9], v[8:9]
	v_pk_mul_f32 v[84:85], v[10:11], v[10:11]
	v_pk_mul_f32 v[86:87], v[12:13], v[12:13]
	v_pk_mul_f32 v[88:89], v[14:15], v[14:15]
	v_mov_b32_e32 v90, v86
	v_mov_b32_e32 v91, v89
	v_pk_mov_b32 v[86:87], v[86:87], v[88:89] op_sel:[1,0]
	v_mov_b32_e32 v88, v82
	v_mov_b32_e32 v89, v85
	v_pk_mov_b32 v[82:83], v[82:83], v[84:85] op_sel:[1,0]
	v_pk_add_f32 v[86:87], v[86:87], v[90:91]
	v_pk_add_f32 v[82:83], v[82:83], v[88:89]
	v_pk_add_f32 v[86:87], v[86:87], v[86:87] op_sel_hi:[0,1]
	v_pk_add_f32 v[82:83], v[82:83], v[82:83] op_sel_hi:[0,1]
	v_mul_f32_e32 v82, v4, v4
	v_pk_fma_f32 v[84:85], v[4:5], v[4:5], v[82:83] op_sel_hi:[1,1,0]
	v_mul_f32_e32 v82, v6, v6
	v_pk_fma_f32 v[88:89], v[6:7], v[6:7], v[82:83] op_sel_hi:[1,1,0]
	v_mul_f32_e32 v84, v0, v0
	v_mul_f32_e32 v88, v1, v1
	v_mul_f32_e32 v86, v2, v2
	v_mul_f32_e32 v82, v3, v3
	v_pk_add_f32 v[84:85], v[84:85], v[88:89]
	v_pk_add_f32 v[82:83], v[86:87], v[82:83]
	v_pk_add_f32 v[82:83], v[84:85], v[82:83]
	v_add_f32_e32 v82, v82, v83
	ds_bpermute_b32 v83, v71, v82
	s_waitcnt lgkmcnt(0)
	v_add_f32_e32 v82, v82, v83
	ds_bpermute_b32 v83, v72, v82
	s_waitcnt lgkmcnt(0)
	v_add_f32_e32 v82, v82, v83
	ds_bpermute_b32 v83, v73, v82
	s_waitcnt lgkmcnt(0)
	v_add_f32_e32 v82, v82, v83
	ds_bpermute_b32 v83, v74, v82
	s_waitcnt lgkmcnt(0)
	v_add_f32_e32 v82, v82, v83
	ds_bpermute_b32 v83, v75, v82
	s_waitcnt lgkmcnt(0)
	v_add_f32_e32 v82, v82, v83
	ds_bpermute_b32 v83, v76, v82
	s_waitcnt lgkmcnt(0)
; DI unsigned pk2(float lo, float hi) { return pg8::cvt_pk_bf16(lo, hi); }
; DI void prenorm_rows(const float* X, const float* gvec, const float* ada, int sh_off, int sc_off, bf16* U, int row_lo, int row_hi, int gw, int ngw, int lane) {
;     ...
;         const float rstd = rsqrtf(wave_sum(ss) * (1.0f / 1024.0f) + 1e-6f);
; #pragma unroll
;         for (int j = 0; j < 4; ++j) { const f32x4 o = (v[j] * rstd) * mul[j] + add[j]; v2u w; w.x = pk2(o[0], o[1]); w.y = pk2(o[2], o[3]);
;             *(v2u*)(U + (size_t)m * 1024 + 4 * lane + 256 * j) = w; }
	v_add_f32_e32 v82, v82, v83
	v_fmamk_f32 v82, v82, 0x3a800000, v81
	v_mul_f32_e32 v83, 0x4b800000, v82
	v_cmp_gt_f32_e32 vcc, s7, v82
	s_nop 1
	v_cndmask_b32_e32 v82, v82, v83, vcc
	v_rsq_f32_e32 v82, v82
	s_nop 0
	v_mul_f32_e32 v83, 0x45800000, v82
	v_cndmask_b32_e32 v82, v82, v83, vcc
	v_pk_mul_f32 v[12:13], v[12:13], v[82:83] op_sel_hi:[1,0]
	v_pk_mul_f32 v[8:9], v[8:9], v[82:83] op_sel_hi:[1,0]
	v_pk_mul_f32 v[4:5], v[4:5], v[82:83] op_sel_hi:[1,0]
	v_pk_mul_f32 v[0:1], v[0:1], v[82:83] op_sel_hi:[1,0]
	v_pk_mul_f32 v[14:15], v[14:15], v[82:83] op_sel_hi:[1,0]
	v_pk_mul_f32 v[10:11], v[10:11], v[82:83] op_sel_hi:[1,0]
	v_pk_fma_f32 v[12:13], v[48:49], v[12:13], v[28:29]
	v_pk_fma_f32 v[8:9], v[52:53], v[8:9], v[24:25]
	v_pk_mul_f32 v[6:7], v[6:7], v[82:83] op_sel_hi:[1,0]
	v_pk_fma_f32 v[4:5], v[56:57], v[4:5], v[20:21]
	v_pk_mul_f32 v[2:3], v[2:3], v[82:83] op_sel_hi:[1,0]
	v_pk_fma_f32 v[0:1], v[60:61], v[0:1], v[16:17]
	v_pk_fma_f32 v[14:15], v[50:51], v[14:15], v[30:31]
	v_pk_fma_f32 v[10:11], v[54:55], v[10:11], v[26:27]
	v_cvt_pk_bf16_f32 v12, v12, v13
	v_cvt_pk_bf16_f32 v13, v14, v15
	global_store_dwordx2 v[66:67], v[12:13], off
	v_cvt_pk_bf16_f32 v8, v8, v9
	v_cvt_pk_bf16_f32 v9, v10, v11
	global_store_dwordx2 v[66:67], v[8:9], off offset:512
	v_pk_fma_f32 v[6:7], v[58:59], v[6:7], v[22:23]
	v_cvt_pk_bf16_f32 v4, v4, v5
	v_pk_fma_f32 v[2:3], v[62:63], v[2:3], v[18:19]
	v_cvt_pk_bf16_f32 v5, v6, v7
	global_store_dwordx2 v[66:67], v[4:5], off offset:1024
	v_cvt_pk_bf16_f32 v0, v0, v1
	v_cvt_pk_bf16_f32 v1, v2, v3
	global_store_dwordx2 v[66:67], v[0:1], off offset:1536
	v_lshl_add_u64 v[66:67], v[66:67], 0, s[2:3]
	global_load_dwordx4 v[12:15], v[68:69], off
	global_load_dwordx4 v[8:11], v[68:69], off offset:1024
	global_load_dwordx4 v[4:7], v[68:69], off offset:2048
	global_load_dwordx4 v[0:3], v[68:69], off offset:3072
	v_lshl_add_u64 v[68:69], v[68:69], 0, s[0:1]
	s_waitcnt vmcnt(24)
	v_pk_mul_f32 v[82:83], v[160:161], v[160:161]
	v_pk_mul_f32 v[84:85], v[162:163], v[162:163]
	v_pk_mul_f32 v[86:87], v[164:165], v[164:165]
	v_pk_mul_f32 v[88:89], v[166:167], v[166:167]
	v_mov_b32_e32 v90, v86
	v_mov_b32_e32 v91, v89
	v_pk_mov_b32 v[86:87], v[86:87], v[88:89] op_sel:[1,0]
	v_mov_b32_e32 v88, v82
	v_mov_b32_e32 v89, v85
	v_pk_mov_b32 v[82:83], v[82:83], v[84:85] op_sel:[1,0]
	v_pk_add_f32 v[86:87], v[86:87], v[90:91]
	v_pk_add_f32 v[82:83], v[82:83], v[88:89]
	v_pk_add_f32 v[86:87], v[86:87], v[86:87] op_sel_hi:[0,1]
	v_pk_add_f32 v[82:83], v[82:83], v[82:83] op_sel_hi:[0,1]
	v_mul_f32_e32 v82, v156, v156
	v_pk_fma_f32 v[84:85], v[156:157], v[156:157], v[82:83] op_sel_hi:[1,1,0]
	v_mul_f32_e32 v82, v158, v158
	v_pk_fma_f32 v[88:89], v[158:159], v[158:159], v[82:83] op_sel_hi:[1,1,0]
	v_mul_f32_e32 v84, v152, v152
	v_mul_f32_e32 v88, v153, v153
	v_mul_f32_e32 v86, v154, v154
	v_mul_f32_e32 v82, v155, v155
	v_pk_add_f32 v[84:85], v[84:85], v[88:89]
	v_pk_add_f32 v[82:83], v[86:87], v[82:83]
	v_pk_add_f32 v[82:83], v[84:85], v[82:83]
	v_add_f32_e32 v82, v82, v83
	ds_bpermute_b32 v83, v71, v82
	s_waitcnt lgkmcnt(0)
	v_add_f32_e32 v82, v82, v83
	ds_bpermute_b32 v83, v72, v82
	s_waitcnt lgkmcnt(0)
	v_add_f32_e32 v82, v82, v83
	ds_bpermute_b32 v83, v73, v82
	s_waitcnt lgkmcnt(0)
	v_add_f32_e32 v82, v82, v83
	ds_bpermute_b32 v83, v74, v82
	s_waitcnt lgkmcnt(0)
	v_add_f32_e32 v82, v82, v83
	ds_bpermute_b32 v83, v75, v82
	s_waitcnt lgkmcnt(0)
	v_add_f32_e32 v82, v82, v83
	ds_bpermute_b32 v83, v76, v82
	s_waitcnt lgkmcnt(0)
	v_add_f32_e32 v82, v82, v83
	v_fmamk_f32 v82, v82, 0x3a800000, v81
	v_mul_f32_e32 v83, 0x4b800000, v82
	v_cmp_gt_f32_e32 vcc, s7, v82
	s_nop 1
	v_cndmask_b32_e32 v82, v82, v83, vcc
	v_rsq_f32_e32 v82, v82
	s_nop 0
	v_mul_f32_e32 v83, 0x45800000, v82
	v_cndmask_b32_e32 v82, v82, v83, vcc
	v_pk_mul_f32 v[164:165], v[164:165], v[82:83] op_sel_hi:[1,0]
	v_pk_mul_f32 v[160:161], v[160:161], v[82:83] op_sel_hi:[1,0]
	v_pk_mul_f32 v[156:157], v[156:157], v[82:83] op_sel_hi:[1,0]
	v_pk_mul_f32 v[152:153], v[152:153], v[82:83] op_sel_hi:[1,0]
	v_pk_mul_f32 v[166:167], v[166:167], v[82:83] op_sel_hi:[1,0]
	v_pk_mul_f32 v[162:163], v[162:163], v[82:83] op_sel_hi:[1,0]
	v_pk_fma_f32 v[164:165], v[48:49], v[164:165], v[28:29]
	v_pk_fma_f32 v[160:161], v[52:53], v[160:161], v[24:25]
	v_pk_mul_f32 v[158:159], v[158:159], v[82:83] op_sel_hi:[1,0]
	v_pk_fma_f32 v[156:157], v[56:57], v[156:157], v[20:21]
	v_pk_mul_f32 v[154:155], v[154:155], v[82:83] op_sel_hi:[1,0]
	v_pk_fma_f32 v[152:153], v[60:61], v[152:153], v[16:17]
	v_pk_fma_f32 v[166:167], v[50:51], v[166:167], v[30:31]
	v_pk_fma_f32 v[162:163], v[54:55], v[162:163], v[26:27]
	v_cvt_pk_bf16_f32 v164, v164, v165
	v_cvt_pk_bf16_f32 v165, v166, v167
	global_store_dwordx2 v[66:67], v[164:165], off
	v_cvt_pk_bf16_f32 v160, v160, v161
	v_cvt_pk_bf16_f32 v161, v162, v163
	global_store_dwordx2 v[66:67], v[160:161], off offset:512
	v_pk_fma_f32 v[158:159], v[58:59], v[158:159], v[22:23]
	v_cvt_pk_bf16_f32 v156, v156, v157
	v_pk_fma_f32 v[154:155], v[62:63], v[154:155], v[18:19]
	v_cvt_pk_bf16_f32 v157, v158, v159
	global_store_dwordx2 v[66:67], v[156:157], off offset:1024
	v_cvt_pk_bf16_f32 v152, v152, v153
	v_cvt_pk_bf16_f32 v153, v154, v155
	global_store_dwordx2 v[66:67], v[152:153], off offset:1536
	v_lshl_add_u64 v[66:67], v[66:67], 0, s[2:3]
	global_load_dwordx4 v[164:167], v[68:69], off
	global_load_dwordx4 v[160:163], v[68:69], off offset:1024
	global_load_dwordx4 v[156:159], v[68:69], off offset:2048
	global_load_dwordx4 v[152:155], v[68:69], off offset:3072
	v_lshl_add_u64 v[68:69], v[68:69], 0, s[0:1]
	s_waitcnt vmcnt(24)
; DI unsigned pk2(float lo, float hi) { return pg8::cvt_pk_bf16(lo, hi); }
; DI void prenorm_rows(const float* X, const float* gvec, const float* ada, int sh_off, int sc_off, bf16* U, int row_lo, int row_hi, int gw, int ngw, int lane) {
;     ...
;             for (int j = 0; j < 4; ++j) { const int col = 4 * lane + 256 * j; const f32x4 g = *(const f32x4*)(gvec + col), sc = *(const f32x4*)(ada + (size_t)b * 6144 + sc_off + col);
;                 mul[j] = g * (sc + 1.0f); add[j] = *(const f32x4*)(ada + (size_t)b * 6144 + sh_off + col); } }
; #pragma unroll
;         for (int j = 0; j < 4; ++j) ss += (v[j][0] * v[j][0] + v[j][1] * v[j][1]) + (v[j][2] * v[j][2] + v[j][3] * v[j][3]);
;         const float rstd = rsqrtf(wave_sum(ss) * (1.0f / 1024.0f) + 1e-6f);
; #pragma unroll
;         for (int j = 0; j < 4; ++j) { const f32x4 o = (v[j] * rstd) * mul[j] + add[j]; v2u w; w.x = pk2(o[0], o[1]); w.y = pk2(o[2], o[3]);
;             *(v2u*)(U + (size_t)m * 1024 + 4 * lane + 256 * j) = w; }
	v_pk_mul_f32 v[82:83], v[176:177], v[176:177]
	v_pk_mul_f32 v[84:85], v[178:179], v[178:179]
	v_pk_mul_f32 v[86:87], v[180:181], v[180:181]
	v_pk_mul_f32 v[88:89], v[182:183], v[182:183]
	v_mov_b32_e32 v90, v86
	v_mov_b32_e32 v91, v89
	v_pk_mov_b32 v[86:87], v[86:87], v[88:89] op_sel:[1,0]
	v_mov_b32_e32 v88, v82
	v_mov_b32_e32 v89, v85
	v_pk_mov_b32 v[82:83], v[82:83], v[84:85] op_sel:[1,0]
	v_pk_add_f32 v[86:87], v[86:87], v[90:91]
	v_pk_add_f32 v[82:83], v[82:83], v[88:89]
	v_pk_add_f32 v[86:87], v[86:87], v[86:87] op_sel_hi:[0,1]
	v_pk_add_f32 v[82:83], v[82:83], v[82:83] op_sel_hi:[0,1]
	v_mul_f32_e32 v82, v172, v172
	v_pk_fma_f32 v[84:85], v[172:173], v[172:173], v[82:83] op_sel_hi:[1,1,0]
	v_mul_f32_e32 v82, v174, v174
	v_pk_fma_f32 v[88:89], v[174:175], v[174:175], v[82:83] op_sel_hi:[1,1,0]
	v_mul_f32_e32 v84, v168, v168
	v_mul_f32_e32 v88, v169, v169
	v_mul_f32_e32 v86, v170, v170
	v_mul_f32_e32 v82, v171, v171
	v_pk_add_f32 v[84:85], v[84:85], v[88:89]
	v_pk_add_f32 v[82:83], v[86:87], v[82:83]
	v_pk_add_f32 v[82:83], v[84:85], v[82:83]
	v_add_f32_e32 v82, v82, v83
	ds_bpermute_b32 v83, v71, v82
	s_waitcnt lgkmcnt(0)
	v_add_f32_e32 v82, v82, v83
	ds_bpermute_b32 v83, v72, v82
	s_waitcnt lgkmcnt(0)
	v_add_f32_e32 v82, v82, v83
	ds_bpermute_b32 v83, v73, v82
	s_waitcnt lgkmcnt(0)
	v_add_f32_e32 v82, v82, v83
	ds_bpermute_b32 v83, v74, v82
	s_waitcnt lgkmcnt(0)
	v_add_f32_e32 v82, v82, v83
	ds_bpermute_b32 v83, v75, v82
	s_waitcnt lgkmcnt(0)
	v_add_f32_e32 v82, v82, v83
	ds_bpermute_b32 v83, v76, v82
	s_waitcnt lgkmcnt(0)
	v_add_f32_e32 v82, v82, v83
	v_fmamk_f32 v82, v82, 0x3a800000, v81
	v_mul_f32_e32 v83, 0x4b800000, v82
	v_cmp_gt_f32_e32 vcc, s7, v82
	s_nop 1
	v_cndmask_b32_e32 v82, v82, v83, vcc
	v_rsq_f32_e32 v82, v82
	s_nop 0
	v_mul_f32_e32 v83, 0x45800000, v82
	v_cndmask_b32_e32 v82, v82, v83, vcc
	v_pk_mul_f32 v[180:181], v[180:181], v[82:83] op_sel_hi:[1,0]
	v_pk_mul_f32 v[176:177], v[176:177], v[82:83] op_sel_hi:[1,0]
	v_pk_mul_f32 v[172:173], v[172:173], v[82:83] op_sel_hi:[1,0]
	v_pk_mul_f32 v[168:169], v[168:169], v[82:83] op_sel_hi:[1,0]
	v_pk_mul_f32 v[182:183], v[182:183], v[82:83] op_sel_hi:[1,0]
	v_pk_mul_f32 v[178:179], v[178:179], v[82:83] op_sel_hi:[1,0]
	v_pk_fma_f32 v[180:181], v[48:49], v[180:181], v[28:29]
	v_pk_fma_f32 v[176:177], v[52:53], v[176:177], v[24:25]
	v_pk_mul_f32 v[174:175], v[174:175], v[82:83] op_sel_hi:[1,0]
	v_pk_fma_f32 v[172:173], v[56:57], v[172:173], v[20:21]
	v_pk_mul_f32 v[170:171], v[170:171], v[82:83] op_sel_hi:[1,0]
	v_pk_fma_f32 v[168:169], v[60:61], v[168:169], v[16:17]
	v_pk_fma_f32 v[182:183], v[50:51], v[182:183], v[30:31]
	v_pk_fma_f32 v[178:179], v[54:55], v[178:179], v[26:27]
	v_cvt_pk_bf16_f32 v180, v180, v181
	v_cvt_pk_bf16_f32 v181, v182, v183
	global_store_dwordx2 v[66:67], v[180:181], off
	v_cvt_pk_bf16_f32 v176, v176, v177
	v_cvt_pk_bf16_f32 v177, v178, v179
	global_store_dwordx2 v[66:67], v[176:177], off offset:512
	v_pk_fma_f32 v[174:175], v[58:59], v[174:175], v[22:23]
	v_cvt_pk_bf16_f32 v172, v172, v173
	v_pk_fma_f32 v[170:171], v[62:63], v[170:171], v[18:19]
	v_cvt_pk_bf16_f32 v173, v174, v175
	global_store_dwordx2 v[66:67], v[172:173], off offset:1024
	v_cvt_pk_bf16_f32 v168, v168, v169
	v_cvt_pk_bf16_f32 v169, v170, v171
	global_store_dwordx2 v[66:67], v[168:169], off offset:1536
	v_lshl_add_u64 v[66:67], v[66:67], 0, s[2:3]
	global_load_dwordx4 v[180:183], v[68:69], off
	global_load_dwordx4 v[176:179], v[68:69], off offset:1024
	global_load_dwordx4 v[172:175], v[68:69], off offset:2048
	global_load_dwordx4 v[168:171], v[68:69], off offset:3072
	v_lshl_add_u64 v[68:69], v[68:69], 0, s[0:1]
	s_waitcnt vmcnt(24)
	v_pk_mul_f32 v[82:83], v[40:41], v[40:41]
	v_pk_mul_f32 v[84:85], v[42:43], v[42:43]
	v_pk_mul_f32 v[86:87], v[44:45], v[44:45]
	v_pk_mul_f32 v[88:89], v[46:47], v[46:47]
	v_mov_b32_e32 v90, v86
	v_mov_b32_e32 v91, v89
	v_pk_mov_b32 v[86:87], v[86:87], v[88:89] op_sel:[1,0]
	v_mov_b32_e32 v88, v82
	v_mov_b32_e32 v89, v85
	v_pk_mov_b32 v[82:83], v[82:83], v[84:85] op_sel:[1,0]
	v_pk_add_f32 v[86:87], v[86:87], v[90:91]
	v_pk_add_f32 v[82:83], v[82:83], v[88:89]
	v_pk_add_f32 v[86:87], v[86:87], v[86:87] op_sel_hi:[0,1]
	v_pk_add_f32 v[82:83], v[82:83], v[82:83] op_sel_hi:[0,1]
	v_mul_f32_e32 v82, v36, v36
	v_pk_fma_f32 v[84:85], v[36:37], v[36:37], v[82:83] op_sel_hi:[1,1,0]
	v_mul_f32_e32 v82, v38, v38
	v_pk_fma_f32 v[88:89], v[38:39], v[38:39], v[82:83] op_sel_hi:[1,1,0]
	v_mul_f32_e32 v84, v32, v32
	v_mul_f32_e32 v88, v33, v33
	v_mul_f32_e32 v86, v34, v34
	v_mul_f32_e32 v82, v35, v35
	v_pk_add_f32 v[84:85], v[84:85], v[88:89]
	v_pk_add_f32 v[82:83], v[86:87], v[82:83]
	v_pk_add_f32 v[82:83], v[84:85], v[82:83]
	v_add_f32_e32 v82, v82, v83
	ds_bpermute_b32 v83, v71, v82
	s_waitcnt lgkmcnt(0)
	v_add_f32_e32 v82, v82, v83
	ds_bpermute_b32 v83, v72, v82
	s_waitcnt lgkmcnt(0)
	v_add_f32_e32 v82, v82, v83
	ds_bpermute_b32 v83, v73, v82
	s_waitcnt lgkmcnt(0)
	v_add_f32_e32 v82, v82, v83
	ds_bpermute_b32 v83, v74, v82
	s_waitcnt lgkmcnt(0)
	v_add_f32_e32 v82, v82, v83
	ds_bpermute_b32 v83, v75, v82
	s_waitcnt lgkmcnt(0)
	v_add_f32_e32 v82, v82, v83
	ds_bpermute_b32 v83, v76, v82
	s_waitcnt lgkmcnt(0)
; DI unsigned pk2(float lo, float hi) { return pg8::cvt_pk_bf16(lo, hi); }
; DI void prenorm_rows(const float* X, const float* gvec, const float* ada, int sh_off, int sc_off, bf16* U, int row_lo, int row_hi, int gw, int ngw, int lane) {
;     ...
;         f32x4 v[4]; float ss = 0.f;
; #pragma unroll
;         for (int j = 0; j < 4; ++j) v[j] = nx[j];
;         if (m + 1 < m1) {
; #pragma unroll
;             for (int j = 0; j < 4; ++j) nx[j] = *(const f32x4*)(X + (size_t)(m + 1) * 1024 + 4 * lane + 256 * j);
;         }
;         if (b != curb) { curb = b;
; #pragma unroll
;             for (int j = 0; j < 4; ++j) { const int col = 4 * lane + 256 * j; const f32x4 g = *(const f32x4*)(gvec + col), sc = *(const f32x4*)(ada + (size_t)b * 6144 + sc_off + col);
;                 mul[j] = g * (sc + 1.0f); add[j] = *(const f32x4*)(ada + (size_t)b * 6144 + sh_off + col); } }
; #pragma unroll
;         for (int j = 0; j < 4; ++j) ss += (v[j][0] * v[j][0] + v[j][1] * v[j][1]) + (v[j][2] * v[j][2] + v[j][3] * v[j][3]);
;         const float rstd = rsqrtf(wave_sum(ss) * (1.0f / 1024.0f) + 1e-6f);
; #pragma unroll
;         for (int j = 0; j < 4; ++j) { const f32x4 o = (v[j] * rstd) * mul[j] + add[j]; v2u w; w.x = pk2(o[0], o[1]); w.y = pk2(o[2], o[3]);
;             *(v2u*)(U + (size_t)m * 1024 + 4 * lane + 256 * j) = w; }
	v_add_f32_e32 v82, v82, v83
	v_fmamk_f32 v82, v82, 0x3a800000, v81
	v_mul_f32_e32 v83, 0x4b800000, v82
	v_cmp_gt_f32_e32 vcc, s7, v82
	s_nop 1
	v_cndmask_b32_e32 v82, v82, v83, vcc
	v_rsq_f32_e32 v82, v82
	s_nop 0
	v_mul_f32_e32 v83, 0x45800000, v82
	v_cndmask_b32_e32 v82, v82, v83, vcc
	v_pk_mul_f32 v[44:45], v[44:45], v[82:83] op_sel_hi:[1,0]
	v_pk_mul_f32 v[40:41], v[40:41], v[82:83] op_sel_hi:[1,0]
	v_pk_mul_f32 v[36:37], v[36:37], v[82:83] op_sel_hi:[1,0]
	v_pk_mul_f32 v[32:33], v[32:33], v[82:83] op_sel_hi:[1,0]
	v_pk_mul_f32 v[46:47], v[46:47], v[82:83] op_sel_hi:[1,0]
	v_pk_mul_f32 v[42:43], v[42:43], v[82:83] op_sel_hi:[1,0]
	v_pk_fma_f32 v[44:45], v[48:49], v[44:45], v[28:29]
	v_pk_fma_f32 v[40:41], v[52:53], v[40:41], v[24:25]
	v_pk_mul_f32 v[38:39], v[38:39], v[82:83] op_sel_hi:[1,0]
	v_pk_fma_f32 v[36:37], v[56:57], v[36:37], v[20:21]
	v_pk_mul_f32 v[34:35], v[34:35], v[82:83] op_sel_hi:[1,0]
	v_pk_fma_f32 v[32:33], v[60:61], v[32:33], v[16:17]
	v_pk_fma_f32 v[46:47], v[50:51], v[46:47], v[30:31]
	v_pk_fma_f32 v[42:43], v[54:55], v[42:43], v[26:27]
	v_cvt_pk_bf16_f32 v44, v44, v45
	v_cvt_pk_bf16_f32 v45, v46, v47
	global_store_dwordx2 v[66:67], v[44:45], off
	v_cvt_pk_bf16_f32 v40, v40, v41
	v_cvt_pk_bf16_f32 v41, v42, v43
	global_store_dwordx2 v[66:67], v[40:41], off offset:512
	v_pk_fma_f32 v[38:39], v[58:59], v[38:39], v[22:23]
	v_cvt_pk_bf16_f32 v36, v36, v37
	v_pk_fma_f32 v[34:35], v[62:63], v[34:35], v[18:19]
	v_cvt_pk_bf16_f32 v37, v38, v39
	global_store_dwordx2 v[66:67], v[36:37], off offset:1024
	v_cvt_pk_bf16_f32 v32, v32, v33
	v_cvt_pk_bf16_f32 v33, v34, v35
	global_store_dwordx2 v[66:67], v[32:33], off offset:1536
	v_lshl_add_u64 v[66:67], v[66:67], 0, s[2:3]
	global_load_dwordx4 v[44:47], v[68:69], off
	global_load_dwordx4 v[40:43], v[68:69], off offset:1024
	global_load_dwordx4 v[36:39], v[68:69], off offset:2048
	global_load_dwordx4 v[32:35], v[68:69], off offset:3072
	v_lshl_add_u64 v[68:69], v[68:69], 0, s[0:1]
	s_waitcnt vmcnt(24)
	v_pk_mul_f32 v[82:83], v[8:9], v[8:9]
	v_pk_mul_f32 v[84:85], v[10:11], v[10:11]
	v_pk_mul_f32 v[86:87], v[12:13], v[12:13]
	v_pk_mul_f32 v[88:89], v[14:15], v[14:15]
	v_mov_b32_e32 v90, v86
	v_mov_b32_e32 v91, v89
	v_pk_mov_b32 v[86:87], v[86:87], v[88:89] op_sel:[1,0]
	v_mov_b32_e32 v88, v82
	v_mov_b32_e32 v89, v85
	v_pk_mov_b32 v[82:83], v[82:83], v[84:85] op_sel:[1,0]
	v_pk_add_f32 v[86:87], v[86:87], v[90:91]
	v_pk_add_f32 v[82:83], v[82:83], v[88:89]
	v_pk_add_f32 v[86:87], v[86:87], v[86:87] op_sel_hi:[0,1]
	v_pk_add_f32 v[82:83], v[82:83], v[82:83] op_sel_hi:[0,1]
	v_mul_f32_e32 v82, v4, v4
	v_pk_fma_f32 v[84:85], v[4:5], v[4:5], v[82:83] op_sel_hi:[1,1,0]
	v_mul_f32_e32 v82, v6, v6
	v_pk_fma_f32 v[88:89], v[6:7], v[6:7], v[82:83] op_sel_hi:[1,1,0]
	v_mul_f32_e32 v84, v0, v0
	v_mul_f32_e32 v88, v1, v1
	v_mul_f32_e32 v86, v2, v2
	v_mul_f32_e32 v82, v3, v3
	v_pk_add_f32 v[84:85], v[84:85], v[88:89]
	v_pk_add_f32 v[82:83], v[86:87], v[82:83]
	v_pk_add_f32 v[82:83], v[84:85], v[82:83]
	v_add_f32_e32 v82, v82, v83
	ds_bpermute_b32 v83, v71, v82
	s_waitcnt lgkmcnt(0)
	v_add_f32_e32 v82, v82, v83
	ds_bpermute_b32 v83, v72, v82
	s_waitcnt lgkmcnt(0)
	v_add_f32_e32 v82, v82, v83
	ds_bpermute_b32 v83, v73, v82
	s_waitcnt lgkmcnt(0)
	v_add_f32_e32 v82, v82, v83
	ds_bpermute_b32 v83, v74, v82
	s_waitcnt lgkmcnt(0)
	v_add_f32_e32 v82, v82, v83
	ds_bpermute_b32 v83, v75, v82
	s_waitcnt lgkmcnt(0)
	v_add_f32_e32 v82, v82, v83
	ds_bpermute_b32 v83, v76, v82
	s_waitcnt lgkmcnt(0)
	v_add_f32_e32 v82, v82, v83
	v_fmamk_f32 v82, v82, 0x3a800000, v81
	v_mul_f32_e32 v83, 0x4b800000, v82
	v_cmp_gt_f32_e32 vcc, s7, v82
	s_nop 1
	v_cndmask_b32_e32 v82, v82, v83, vcc
	v_rsq_f32_e32 v82, v82
	s_nop 0
	v_mul_f32_e32 v83, 0x45800000, v82
	v_cndmask_b32_e32 v82, v82, v83, vcc
	v_pk_mul_f32 v[12:13], v[12:13], v[82:83] op_sel_hi:[1,0]
	v_pk_mul_f32 v[8:9], v[8:9], v[82:83] op_sel_hi:[1,0]
	v_pk_mul_f32 v[4:5], v[4:5], v[82:83] op_sel_hi:[1,0]
	v_pk_mul_f32 v[0:1], v[0:1], v[82:83] op_sel_hi:[1,0]
	v_pk_mul_f32 v[14:15], v[14:15], v[82:83] op_sel_hi:[1,0]
	v_pk_mul_f32 v[10:11], v[10:11], v[82:83] op_sel_hi:[1,0]
	v_pk_fma_f32 v[12:13], v[48:49], v[12:13], v[28:29]
	v_pk_fma_f32 v[8:9], v[52:53], v[8:9], v[24:25]
	v_pk_mul_f32 v[6:7], v[6:7], v[82:83] op_sel_hi:[1,0]
	v_pk_fma_f32 v[4:5], v[56:57], v[4:5], v[20:21]
	v_pk_mul_f32 v[2:3], v[2:3], v[82:83] op_sel_hi:[1,0]
	v_pk_fma_f32 v[0:1], v[60:61], v[0:1], v[16:17]
	v_pk_fma_f32 v[14:15], v[50:51], v[14:15], v[30:31]
	v_pk_fma_f32 v[10:11], v[54:55], v[10:11], v[26:27]
	v_cvt_pk_bf16_f32 v12, v12, v13
	v_cvt_pk_bf16_f32 v13, v14, v15
	global_store_dwordx2 v[66:67], v[12:13], off
	v_cvt_pk_bf16_f32 v8, v8, v9
	v_cvt_pk_bf16_f32 v9, v10, v11
	global_store_dwordx2 v[66:67], v[8:9], off offset:512
	v_pk_fma_f32 v[6:7], v[58:59], v[6:7], v[22:23]
	v_cvt_pk_bf16_f32 v4, v4, v5
	v_pk_fma_f32 v[2:3], v[62:63], v[2:3], v[18:19]
	v_cvt_pk_bf16_f32 v5, v6, v7
	global_store_dwordx2 v[66:67], v[4:5], off offset:1024
	v_cvt_pk_bf16_f32 v0, v0, v1
	v_cvt_pk_bf16_f32 v1, v2, v3
	global_store_dwordx2 v[66:67], v[0:1], off offset:1536
	v_lshl_add_u64 v[66:67], v[66:67], 0, s[2:3]
	global_load_dwordx4 v[12:15], v[68:69], off
	global_load_dwordx4 v[8:11], v[68:69], off offset:1024
	global_load_dwordx4 v[4:7], v[68:69], off offset:2048
	global_load_dwordx4 v[0:3], v[68:69], off offset:3072
	v_lshl_add_u64 v[68:69], v[68:69], 0, s[0:1]
	s_waitcnt vmcnt(24)
; DI unsigned pk2(float lo, float hi) { return pg8::cvt_pk_bf16(lo, hi); }
; DI void prenorm_rows(const float* X, const float* gvec, const float* ada, int sh_off, int sc_off, bf16* U, int row_lo, int row_hi, int gw, int ngw, int lane) {
;     ...
;         f32x4 v[4]; float ss = 0.f;
; #pragma unroll
;         for (int j = 0; j < 4; ++j) v[j] = nx[j];
;         if (m + 1 < m1) {
; #pragma unroll
;             for (int j = 0; j < 4; ++j) nx[j] = *(const f32x4*)(X + (size_t)(m + 1) * 1024 + 4 * lane + 256 * j);
;         }
;         if (b != curb) { curb = b;
; #pragma unroll
;             for (int j = 0; j < 4; ++j) { const int col = 4 * lane + 256 * j; const f32x4 g = *(const f32x4*)(gvec + col), sc = *(const f32x4*)(ada + (size_t)b * 6144 + sc_off + col);
;                 mul[j] = g * (sc + 1.0f); add[j] = *(const f32x4*)(ada + (size_t)b * 6144 + sh_off + col); } }
; #pragma unroll
;         for (int j = 0; j < 4; ++j) ss += (v[j][0] * v[j][0] + v[j][1] * v[j][1]) + (v[j][2] * v[j][2] + v[j][3] * v[j][3]);
;         const float rstd = rsqrtf(wave_sum(ss) * (1.0f / 1024.0f) + 1e-6f);
; #pragma unroll
;         for (int j = 0; j < 4; ++j) { const f32x4 o = (v[j] * rstd) * mul[j] + add[j]; v2u w; w.x = pk2(o[0], o[1]); w.y = pk2(o[2], o[3]);
;             *(v2u*)(U + (size_t)m * 1024 + 4 * lane + 256 * j) = w; }
	v_pk_mul_f32 v[82:83], v[160:161], v[160:161]
	v_pk_mul_f32 v[84:85], v[162:163], v[162:163]
	v_pk_mul_f32 v[86:87], v[164:165], v[164:165]
	v_pk_mul_f32 v[88:89], v[166:167], v[166:167]
	v_mov_b32_e32 v90, v86
	v_mov_b32_e32 v91, v89
	v_pk_mov_b32 v[86:87], v[86:87], v[88:89] op_sel:[1,0]
	v_mov_b32_e32 v88, v82
	v_mov_b32_e32 v89, v85
	v_pk_mov_b32 v[82:83], v[82:83], v[84:85] op_sel:[1,0]
	v_pk_add_f32 v[86:87], v[86:87], v[90:91]
	v_pk_add_f32 v[82:83], v[82:83], v[88:89]
	v_pk_add_f32 v[86:87], v[86:87], v[86:87] op_sel_hi:[0,1]
	v_pk_add_f32 v[82:83], v[82:83], v[82:83] op_sel_hi:[0,1]
	v_mul_f32_e32 v82, v156, v156
	v_pk_fma_f32 v[84:85], v[156:157], v[156:157], v[82:83] op_sel_hi:[1,1,0]
	v_mul_f32_e32 v82, v158, v158
	v_pk_fma_f32 v[88:89], v[158:159], v[158:159], v[82:83] op_sel_hi:[1,1,0]
	v_mul_f32_e32 v84, v152, v152
	v_mul_f32_e32 v88, v153, v153
	v_mul_f32_e32 v86, v154, v154
	v_mul_f32_e32 v82, v155, v155
	v_pk_add_f32 v[84:85], v[84:85], v[88:89]
	v_pk_add_f32 v[82:83], v[86:87], v[82:83]
	v_pk_add_f32 v[82:83], v[84:85], v[82:83]
	v_add_f32_e32 v82, v82, v83
	ds_bpermute_b32 v83, v71, v82
	s_waitcnt lgkmcnt(0)
	v_add_f32_e32 v82, v82, v83
	ds_bpermute_b32 v83, v72, v82
	s_waitcnt lgkmcnt(0)
	v_add_f32_e32 v82, v82, v83
	ds_bpermute_b32 v83, v73, v82
	s_waitcnt lgkmcnt(0)
	v_add_f32_e32 v82, v82, v83
	ds_bpermute_b32 v83, v74, v82
	s_waitcnt lgkmcnt(0)
	v_add_f32_e32 v82, v82, v83
	ds_bpermute_b32 v83, v75, v82
	s_waitcnt lgkmcnt(0)
	v_add_f32_e32 v82, v82, v83
	ds_bpermute_b32 v83, v76, v82
	s_waitcnt lgkmcnt(0)
	v_add_f32_e32 v82, v82, v83
	v_fmamk_f32 v82, v82, 0x3a800000, v81
	v_mul_f32_e32 v83, 0x4b800000, v82
	v_cmp_gt_f32_e32 vcc, s7, v82
	s_nop 1
	v_cndmask_b32_e32 v82, v82, v83, vcc
	v_rsq_f32_e32 v82, v82
	s_nop 0
	v_mul_f32_e32 v83, 0x45800000, v82
	v_cndmask_b32_e32 v82, v82, v83, vcc
	v_pk_mul_f32 v[164:165], v[164:165], v[82:83] op_sel_hi:[1,0]
	v_pk_mul_f32 v[160:161], v[160:161], v[82:83] op_sel_hi:[1,0]
	v_pk_mul_f32 v[156:157], v[156:157], v[82:83] op_sel_hi:[1,0]
	v_pk_mul_f32 v[152:153], v[152:153], v[82:83] op_sel_hi:[1,0]
	v_pk_mul_f32 v[166:167], v[166:167], v[82:83] op_sel_hi:[1,0]
	v_pk_mul_f32 v[162:163], v[162:163], v[82:83] op_sel_hi:[1,0]
	v_pk_fma_f32 v[164:165], v[48:49], v[164:165], v[28:29]
	v_pk_fma_f32 v[160:161], v[52:53], v[160:161], v[24:25]
	v_pk_mul_f32 v[158:159], v[158:159], v[82:83] op_sel_hi:[1,0]
	v_pk_fma_f32 v[156:157], v[56:57], v[156:157], v[20:21]
	v_pk_mul_f32 v[154:155], v[154:155], v[82:83] op_sel_hi:[1,0]
	v_pk_fma_f32 v[152:153], v[60:61], v[152:153], v[16:17]
	v_pk_fma_f32 v[166:167], v[50:51], v[166:167], v[30:31]
	v_pk_fma_f32 v[162:163], v[54:55], v[162:163], v[26:27]
	v_cvt_pk_bf16_f32 v164, v164, v165
	v_cvt_pk_bf16_f32 v165, v166, v167
	global_store_dwordx2 v[66:67], v[164:165], off
	v_cvt_pk_bf16_f32 v160, v160, v161
	v_cvt_pk_bf16_f32 v161, v162, v163
	global_store_dwordx2 v[66:67], v[160:161], off offset:512
	v_pk_fma_f32 v[158:159], v[58:59], v[158:159], v[22:23]
	v_cvt_pk_bf16_f32 v156, v156, v157
	v_pk_fma_f32 v[154:155], v[62:63], v[154:155], v[18:19]
	v_cvt_pk_bf16_f32 v157, v158, v159
	global_store_dwordx2 v[66:67], v[156:157], off offset:1024
	v_cvt_pk_bf16_f32 v152, v152, v153
	v_cvt_pk_bf16_f32 v153, v154, v155
	global_store_dwordx2 v[66:67], v[152:153], off offset:1536
	v_lshl_add_u64 v[66:67], v[66:67], 0, s[2:3]
	global_load_dwordx4 v[164:167], v[68:69], off
	global_load_dwordx4 v[160:163], v[68:69], off offset:1024
	global_load_dwordx4 v[156:159], v[68:69], off offset:2048
	global_load_dwordx4 v[152:155], v[68:69], off offset:3072
	v_lshl_add_u64 v[68:69], v[68:69], 0, s[0:1]
	s_waitcnt vmcnt(24)
	v_pk_mul_f32 v[82:83], v[176:177], v[176:177]
	v_pk_mul_f32 v[84:85], v[178:179], v[178:179]
	v_pk_mul_f32 v[86:87], v[180:181], v[180:181]
	v_pk_mul_f32 v[88:89], v[182:183], v[182:183]
	v_mov_b32_e32 v90, v86
	v_mov_b32_e32 v91, v89
	v_pk_mov_b32 v[86:87], v[86:87], v[88:89] op_sel:[1,0]
	v_mov_b32_e32 v88, v82
	v_mov_b32_e32 v89, v85
	v_pk_mov_b32 v[82:83], v[82:83], v[84:85] op_sel:[1,0]
	v_pk_add_f32 v[86:87], v[86:87], v[90:91]
	v_pk_add_f32 v[82:83], v[82:83], v[88:89]
	v_pk_add_f32 v[86:87], v[86:87], v[86:87] op_sel_hi:[0,1]
	v_pk_add_f32 v[82:83], v[82:83], v[82:83] op_sel_hi:[0,1]
	v_mul_f32_e32 v82, v172, v172
	v_pk_fma_f32 v[84:85], v[172:173], v[172:173], v[82:83] op_sel_hi:[1,1,0]
	v_mul_f32_e32 v82, v174, v174
	v_pk_fma_f32 v[88:89], v[174:175], v[174:175], v[82:83] op_sel_hi:[1,1,0]
	v_mul_f32_e32 v84, v168, v168
	v_mul_f32_e32 v88, v169, v169
	v_mul_f32_e32 v86, v170, v170
	v_mul_f32_e32 v82, v171, v171
	v_pk_add_f32 v[84:85], v[84:85], v[88:89]
	v_pk_add_f32 v[82:83], v[86:87], v[82:83]
	v_pk_add_f32 v[82:83], v[84:85], v[82:83]
	v_add_f32_e32 v82, v82, v83
	ds_bpermute_b32 v83, v71, v82
	s_waitcnt lgkmcnt(0)
	v_add_f32_e32 v82, v82, v83
	ds_bpermute_b32 v83, v72, v82
	s_waitcnt lgkmcnt(0)
	v_add_f32_e32 v82, v82, v83
	ds_bpermute_b32 v83, v73, v82
	s_waitcnt lgkmcnt(0)
	v_add_f32_e32 v82, v82, v83
	ds_bpermute_b32 v83, v74, v82
	s_waitcnt lgkmcnt(0)
	v_add_f32_e32 v82, v82, v83
	ds_bpermute_b32 v83, v75, v82
	s_waitcnt lgkmcnt(0)
	v_add_f32_e32 v82, v82, v83
	ds_bpermute_b32 v83, v76, v82
	s_waitcnt lgkmcnt(0)
; DI unsigned pk2(float lo, float hi) { return pg8::cvt_pk_bf16(lo, hi); }
; DI void prenorm_rows(const float* X, const float* gvec, const float* ada, int sh_off, int sc_off, bf16* U, int row_lo, int row_hi, int gw, int ngw, int lane) {
;     ...
;         f32x4 v[4]; float ss = 0.f;
; #pragma unroll
;         for (int j = 0; j < 4; ++j) v[j] = nx[j];
;         if (m + 1 < m1) {
; #pragma unroll
;             for (int j = 0; j < 4; ++j) nx[j] = *(const f32x4*)(X + (size_t)(m + 1) * 1024 + 4 * lane + 256 * j);
;         }
;         if (b != curb) { curb = b;
; #pragma unroll
;             for (int j = 0; j < 4; ++j) { const int col = 4 * lane + 256 * j; const f32x4 g = *(const f32x4*)(gvec + col), sc = *(const f32x4*)(ada + (size_t)b * 6144 + sc_off + col);
;                 mul[j] = g * (sc + 1.0f); add[j] = *(const f32x4*)(ada + (size_t)b * 6144 + sh_off + col); } }
; #pragma unroll
;         for (int j = 0; j < 4; ++j) ss += (v[j][0] * v[j][0] + v[j][1] * v[j][1]) + (v[j][2] * v[j][2] + v[j][3] * v[j][3]);
;         const float rstd = rsqrtf(wave_sum(ss) * (1.0f / 1024.0f) + 1e-6f);
; #pragma unroll
;         for (int j = 0; j < 4; ++j) { const f32x4 o = (v[j] * rstd) * mul[j] + add[j]; v2u w; w.x = pk2(o[0], o[1]); w.y = pk2(o[2], o[3]);
;             *(v2u*)(U + (size_t)m * 1024 + 4 * lane + 256 * j) = w; }
	v_add_f32_e32 v82, v82, v83
	v_fmamk_f32 v82, v82, 0x3a800000, v81
	v_mul_f32_e32 v83, 0x4b800000, v82
	v_cmp_gt_f32_e32 vcc, s7, v82
	s_nop 1
	v_cndmask_b32_e32 v82, v82, v83, vcc
	v_rsq_f32_e32 v82, v82
	s_nop 0
	v_mul_f32_e32 v83, 0x45800000, v82
	v_cndmask_b32_e32 v82, v82, v83, vcc
	v_pk_mul_f32 v[180:181], v[180:181], v[82:83] op_sel_hi:[1,0]
	v_pk_mul_f32 v[176:177], v[176:177], v[82:83] op_sel_hi:[1,0]
	v_pk_mul_f32 v[172:173], v[172:173], v[82:83] op_sel_hi:[1,0]
	v_pk_mul_f32 v[168:169], v[168:169], v[82:83] op_sel_hi:[1,0]
	v_pk_mul_f32 v[182:183], v[182:183], v[82:83] op_sel_hi:[1,0]
	v_pk_mul_f32 v[178:179], v[178:179], v[82:83] op_sel_hi:[1,0]
	v_pk_fma_f32 v[180:181], v[48:49], v[180:181], v[28:29]
	v_pk_fma_f32 v[176:177], v[52:53], v[176:177], v[24:25]
	v_pk_mul_f32 v[174:175], v[174:175], v[82:83] op_sel_hi:[1,0]
	v_pk_fma_f32 v[172:173], v[56:57], v[172:173], v[20:21]
	v_pk_mul_f32 v[170:171], v[170:171], v[82:83] op_sel_hi:[1,0]
	v_pk_fma_f32 v[168:169], v[60:61], v[168:169], v[16:17]
	v_pk_fma_f32 v[182:183], v[50:51], v[182:183], v[30:31]
	v_pk_fma_f32 v[178:179], v[54:55], v[178:179], v[26:27]
	v_cvt_pk_bf16_f32 v180, v180, v181
	v_cvt_pk_bf16_f32 v181, v182, v183
	global_store_dwordx2 v[66:67], v[180:181], off
	v_cvt_pk_bf16_f32 v176, v176, v177
	v_cvt_pk_bf16_f32 v177, v178, v179
	global_store_dwordx2 v[66:67], v[176:177], off offset:512
	v_pk_fma_f32 v[174:175], v[58:59], v[174:175], v[22:23]
	v_cvt_pk_bf16_f32 v172, v172, v173
	v_pk_fma_f32 v[170:171], v[62:63], v[170:171], v[18:19]
	v_cvt_pk_bf16_f32 v173, v174, v175
	global_store_dwordx2 v[66:67], v[172:173], off offset:1024
	v_cvt_pk_bf16_f32 v168, v168, v169
	v_cvt_pk_bf16_f32 v169, v170, v171
	global_store_dwordx2 v[66:67], v[168:169], off offset:1536
	v_lshl_add_u64 v[66:67], v[66:67], 0, s[2:3]
	global_load_dwordx4 v[180:183], v[68:69], off
	global_load_dwordx4 v[176:179], v[68:69], off offset:1024
	global_load_dwordx4 v[172:175], v[68:69], off offset:2048
	global_load_dwordx4 v[168:171], v[68:69], off offset:3072
	v_lshl_add_u64 v[68:69], v[68:69], 0, s[0:1]
	s_waitcnt vmcnt(24)
	v_pk_mul_f32 v[82:83], v[40:41], v[40:41]
	v_pk_mul_f32 v[84:85], v[42:43], v[42:43]
	v_pk_mul_f32 v[86:87], v[44:45], v[44:45]
	v_pk_mul_f32 v[88:89], v[46:47], v[46:47]
	v_mov_b32_e32 v90, v86
	v_mov_b32_e32 v91, v89
	v_pk_mov_b32 v[86:87], v[86:87], v[88:89] op_sel:[1,0]
	v_mov_b32_e32 v88, v82
	v_mov_b32_e32 v89, v85
	v_pk_mov_b32 v[82:83], v[82:83], v[84:85] op_sel:[1,0]
	v_pk_add_f32 v[86:87], v[86:87], v[90:91]
	v_pk_add_f32 v[82:83], v[82:83], v[88:89]
	v_pk_add_f32 v[86:87], v[86:87], v[86:87] op_sel_hi:[0,1]
	v_pk_add_f32 v[82:83], v[82:83], v[82:83] op_sel_hi:[0,1]
	v_mul_f32_e32 v82, v36, v36
	v_pk_fma_f32 v[84:85], v[36:37], v[36:37], v[82:83] op_sel_hi:[1,1,0]
	v_mul_f32_e32 v82, v38, v38
	v_pk_fma_f32 v[88:89], v[38:39], v[38:39], v[82:83] op_sel_hi:[1,1,0]
	v_mul_f32_e32 v84, v32, v32
	v_mul_f32_e32 v88, v33, v33
	v_mul_f32_e32 v86, v34, v34
	v_mul_f32_e32 v82, v35, v35
	v_pk_add_f32 v[84:85], v[84:85], v[88:89]
	v_pk_add_f32 v[82:83], v[86:87], v[82:83]
	v_pk_add_f32 v[82:83], v[84:85], v[82:83]
	v_add_f32_e32 v82, v82, v83
	ds_bpermute_b32 v83, v71, v82
	s_waitcnt lgkmcnt(0)
	v_add_f32_e32 v82, v82, v83
	ds_bpermute_b32 v83, v72, v82
	s_waitcnt lgkmcnt(0)
	v_add_f32_e32 v82, v82, v83
	ds_bpermute_b32 v83, v73, v82
	s_waitcnt lgkmcnt(0)
	v_add_f32_e32 v82, v82, v83
	ds_bpermute_b32 v83, v74, v82
	s_waitcnt lgkmcnt(0)
	v_add_f32_e32 v82, v82, v83
	ds_bpermute_b32 v83, v75, v82
	s_waitcnt lgkmcnt(0)
	v_add_f32_e32 v82, v82, v83
	ds_bpermute_b32 v83, v76, v82
	s_waitcnt lgkmcnt(0)
	v_add_f32_e32 v82, v82, v83
	v_fmamk_f32 v82, v82, 0x3a800000, v81
	v_mul_f32_e32 v83, 0x4b800000, v82
	v_cmp_gt_f32_e32 vcc, s7, v82
	s_nop 1
	v_cndmask_b32_e32 v82, v82, v83, vcc
	v_rsq_f32_e32 v82, v82
	s_nop 0
	v_mul_f32_e32 v83, 0x45800000, v82
	v_cndmask_b32_e32 v82, v82, v83, vcc
	v_pk_mul_f32 v[44:45], v[44:45], v[82:83] op_sel_hi:[1,0]
	v_pk_mul_f32 v[40:41], v[40:41], v[82:83] op_sel_hi:[1,0]
	v_pk_mul_f32 v[36:37], v[36:37], v[82:83] op_sel_hi:[1,0]
	v_pk_mul_f32 v[32:33], v[32:33], v[82:83] op_sel_hi:[1,0]
	v_pk_mul_f32 v[46:47], v[46:47], v[82:83] op_sel_hi:[1,0]
	v_pk_mul_f32 v[42:43], v[42:43], v[82:83] op_sel_hi:[1,0]
	v_pk_fma_f32 v[44:45], v[48:49], v[44:45], v[28:29]
	v_pk_fma_f32 v[40:41], v[52:53], v[40:41], v[24:25]
	v_pk_mul_f32 v[38:39], v[38:39], v[82:83] op_sel_hi:[1,0]
	v_pk_fma_f32 v[36:37], v[56:57], v[36:37], v[20:21]
	v_pk_mul_f32 v[34:35], v[34:35], v[82:83] op_sel_hi:[1,0]
	v_pk_fma_f32 v[32:33], v[60:61], v[32:33], v[16:17]
	v_pk_fma_f32 v[46:47], v[50:51], v[46:47], v[30:31]
	v_pk_fma_f32 v[42:43], v[54:55], v[42:43], v[26:27]
	v_cvt_pk_bf16_f32 v44, v44, v45
	v_cvt_pk_bf16_f32 v45, v46, v47
	global_store_dwordx2 v[66:67], v[44:45], off
	v_cvt_pk_bf16_f32 v40, v40, v41
	v_cvt_pk_bf16_f32 v41, v42, v43
	global_store_dwordx2 v[66:67], v[40:41], off offset:512
	v_pk_fma_f32 v[38:39], v[58:59], v[38:39], v[22:23]
	v_cvt_pk_bf16_f32 v36, v36, v37
	v_pk_fma_f32 v[34:35], v[62:63], v[34:35], v[18:19]
	v_cvt_pk_bf16_f32 v37, v38, v39
	global_store_dwordx2 v[66:67], v[36:37], off offset:1024
	v_cvt_pk_bf16_f32 v32, v32, v33
	v_cvt_pk_bf16_f32 v33, v34, v35
	global_store_dwordx2 v[66:67], v[32:33], off offset:1536
	v_lshl_add_u64 v[66:67], v[66:67], 0, s[2:3]
	global_load_dwordx4 v[44:47], v[68:69], off
	global_load_dwordx4 v[40:43], v[68:69], off offset:1024
	global_load_dwordx4 v[36:39], v[68:69], off offset:2048
	global_load_dwordx4 v[32:35], v[68:69], off offset:3072
	v_lshl_add_u64 v[68:69], v[68:69], 0, s[0:1]
	s_waitcnt vmcnt(24)
; DI unsigned pk2(float lo, float hi) { return pg8::cvt_pk_bf16(lo, hi); }
; DI void prenorm_rows(const float* X, const float* gvec, const float* ada, int sh_off, int sc_off, bf16* U, int row_lo, int row_hi, int gw, int ngw, int lane) {
;     ...
;         f32x4 v[4]; float ss = 0.f;
; #pragma unroll
;         for (int j = 0; j < 4; ++j) v[j] = nx[j];
;         if (m + 1 < m1) {
; #pragma unroll
;             for (int j = 0; j < 4; ++j) nx[j] = *(const f32x4*)(X + (size_t)(m + 1) * 1024 + 4 * lane + 256 * j);
;         }
;         if (b != curb) { curb = b;
; #pragma unroll
;             for (int j = 0; j < 4; ++j) { const int col = 4 * lane + 256 * j; const f32x4 g = *(const f32x4*)(gvec + col), sc = *(const f32x4*)(ada + (size_t)b * 6144 + sc_off + col);
;                 mul[j] = g * (sc + 1.0f); add[j] = *(const f32x4*)(ada + (size_t)b * 6144 + sh_off + col); } }
; #pragma unroll
;         for (int j = 0; j < 4; ++j) ss += (v[j][0] * v[j][0] + v[j][1] * v[j][1]) + (v[j][2] * v[j][2] + v[j][3] * v[j][3]);
;         const float rstd = rsqrtf(wave_sum(ss) * (1.0f / 1024.0f) + 1e-6f);
; #pragma unroll
;         for (int j = 0; j < 4; ++j) { const f32x4 o = (v[j] * rstd) * mul[j] + add[j]; v2u w; w.x = pk2(o[0], o[1]); w.y = pk2(o[2], o[3]);
;             *(v2u*)(U + (size_t)m * 1024 + 4 * lane + 256 * j) = w; }
	v_pk_mul_f32 v[82:83], v[8:9], v[8:9]
	v_pk_mul_f32 v[84:85], v[10:11], v[10:11]
	v_pk_mul_f32 v[86:87], v[12:13], v[12:13]
	v_pk_mul_f32 v[88:89], v[14:15], v[14:15]
	v_mov_b32_e32 v90, v86
	v_mov_b32_e32 v91, v89
	v_pk_mov_b32 v[86:87], v[86:87], v[88:89] op_sel:[1,0]
	v_mov_b32_e32 v88, v82
	v_mov_b32_e32 v89, v85
	v_pk_mov_b32 v[82:83], v[82:83], v[84:85] op_sel:[1,0]
	v_pk_add_f32 v[86:87], v[86:87], v[90:91]
	v_pk_add_f32 v[82:83], v[82:83], v[88:89]
	v_pk_add_f32 v[86:87], v[86:87], v[86:87] op_sel_hi:[0,1]
	v_pk_add_f32 v[82:83], v[82:83], v[82:83] op_sel_hi:[0,1]
	v_mul_f32_e32 v82, v4, v4
	v_pk_fma_f32 v[84:85], v[4:5], v[4:5], v[82:83] op_sel_hi:[1,1,0]
	v_mul_f32_e32 v82, v6, v6
	v_pk_fma_f32 v[88:89], v[6:7], v[6:7], v[82:83] op_sel_hi:[1,1,0]
	v_mul_f32_e32 v84, v0, v0
	v_mul_f32_e32 v88, v1, v1
	v_mul_f32_e32 v86, v2, v2
	v_mul_f32_e32 v82, v3, v3
	v_pk_add_f32 v[84:85], v[84:85], v[88:89]
	v_pk_add_f32 v[82:83], v[86:87], v[82:83]
	v_pk_add_f32 v[82:83], v[84:85], v[82:83]
	v_add_f32_e32 v82, v82, v83
	ds_bpermute_b32 v83, v71, v82
	s_waitcnt lgkmcnt(0)
	v_add_f32_e32 v82, v82, v83
	ds_bpermute_b32 v83, v72, v82
	s_waitcnt lgkmcnt(0)
	v_add_f32_e32 v82, v82, v83
	ds_bpermute_b32 v83, v73, v82
	s_waitcnt lgkmcnt(0)
	v_add_f32_e32 v82, v82, v83
	ds_bpermute_b32 v83, v74, v82
	s_waitcnt lgkmcnt(0)
	v_add_f32_e32 v82, v82, v83
	ds_bpermute_b32 v83, v75, v82
	s_waitcnt lgkmcnt(0)
	v_add_f32_e32 v82, v82, v83
	ds_bpermute_b32 v83, v76, v82
	s_waitcnt lgkmcnt(0)
	v_add_f32_e32 v82, v82, v83
	v_fmamk_f32 v82, v82, 0x3a800000, v81
	v_mul_f32_e32 v83, 0x4b800000, v82
	v_cmp_gt_f32_e32 vcc, s7, v82
	s_nop 1
	v_cndmask_b32_e32 v82, v82, v83, vcc
	v_rsq_f32_e32 v82, v82
	s_nop 0
	v_mul_f32_e32 v83, 0x45800000, v82
	v_cndmask_b32_e32 v82, v82, v83, vcc
	v_pk_mul_f32 v[12:13], v[12:13], v[82:83] op_sel_hi:[1,0]
	v_pk_mul_f32 v[8:9], v[8:9], v[82:83] op_sel_hi:[1,0]
	v_pk_mul_f32 v[4:5], v[4:5], v[82:83] op_sel_hi:[1,0]
	v_pk_mul_f32 v[0:1], v[0:1], v[82:83] op_sel_hi:[1,0]
	v_pk_mul_f32 v[14:15], v[14:15], v[82:83] op_sel_hi:[1,0]
	v_pk_mul_f32 v[10:11], v[10:11], v[82:83] op_sel_hi:[1,0]
	v_pk_fma_f32 v[12:13], v[48:49], v[12:13], v[28:29]
	v_pk_fma_f32 v[8:9], v[52:53], v[8:9], v[24:25]
	v_pk_mul_f32 v[6:7], v[6:7], v[82:83] op_sel_hi:[1,0]
	v_pk_fma_f32 v[4:5], v[56:57], v[4:5], v[20:21]
	v_pk_mul_f32 v[2:3], v[2:3], v[82:83] op_sel_hi:[1,0]
	v_pk_fma_f32 v[0:1], v[60:61], v[0:1], v[16:17]
	v_pk_fma_f32 v[14:15], v[50:51], v[14:15], v[30:31]
	v_pk_fma_f32 v[10:11], v[54:55], v[10:11], v[26:27]
	v_cvt_pk_bf16_f32 v12, v12, v13
	v_cvt_pk_bf16_f32 v13, v14, v15
	global_store_dwordx2 v[66:67], v[12:13], off
	v_cvt_pk_bf16_f32 v8, v8, v9
	v_cvt_pk_bf16_f32 v9, v10, v11
	global_store_dwordx2 v[66:67], v[8:9], off offset:512
	v_pk_fma_f32 v[6:7], v[58:59], v[6:7], v[22:23]
	v_cvt_pk_bf16_f32 v4, v4, v5
	v_pk_fma_f32 v[2:3], v[62:63], v[2:3], v[18:19]
	v_cvt_pk_bf16_f32 v5, v6, v7
	global_store_dwordx2 v[66:67], v[4:5], off offset:1024
	v_cvt_pk_bf16_f32 v0, v0, v1
	v_cvt_pk_bf16_f32 v1, v2, v3
	global_store_dwordx2 v[66:67], v[0:1], off offset:1536
	v_lshl_add_u64 v[66:67], v[66:67], 0, s[2:3]
	s_waitcnt vmcnt(20)
	v_pk_mul_f32 v[82:83], v[160:161], v[160:161]
	v_pk_mul_f32 v[84:85], v[162:163], v[162:163]
	v_pk_mul_f32 v[86:87], v[164:165], v[164:165]
	v_pk_mul_f32 v[88:89], v[166:167], v[166:167]
	v_mov_b32_e32 v90, v86
	v_mov_b32_e32 v91, v89
	v_pk_mov_b32 v[86:87], v[86:87], v[88:89] op_sel:[1,0]
	v_mov_b32_e32 v88, v82
	v_mov_b32_e32 v89, v85
	v_pk_mov_b32 v[82:83], v[82:83], v[84:85] op_sel:[1,0]
	v_pk_add_f32 v[86:87], v[86:87], v[90:91]
	v_pk_add_f32 v[82:83], v[82:83], v[88:89]
	v_pk_add_f32 v[86:87], v[86:87], v[86:87] op_sel_hi:[0,1]
	v_pk_add_f32 v[82:83], v[82:83], v[82:83] op_sel_hi:[0,1]
	v_mul_f32_e32 v82, v156, v156
	v_pk_fma_f32 v[84:85], v[156:157], v[156:157], v[82:83] op_sel_hi:[1,1,0]
	v_mul_f32_e32 v82, v158, v158
	v_pk_fma_f32 v[88:89], v[158:159], v[158:159], v[82:83] op_sel_hi:[1,1,0]
	v_mul_f32_e32 v84, v152, v152
	v_mul_f32_e32 v88, v153, v153
	v_mul_f32_e32 v86, v154, v154
	v_mul_f32_e32 v82, v155, v155
	v_pk_add_f32 v[84:85], v[84:85], v[88:89]
	v_pk_add_f32 v[82:83], v[86:87], v[82:83]
	v_pk_add_f32 v[82:83], v[84:85], v[82:83]
	v_add_f32_e32 v82, v82, v83
	ds_bpermute_b32 v83, v71, v82
	s_waitcnt lgkmcnt(0)
	v_add_f32_e32 v82, v82, v83
	ds_bpermute_b32 v83, v72, v82
	s_waitcnt lgkmcnt(0)
	v_add_f32_e32 v82, v82, v83
	ds_bpermute_b32 v83, v73, v82
	s_waitcnt lgkmcnt(0)
	v_add_f32_e32 v82, v82, v83
	ds_bpermute_b32 v83, v74, v82
	s_waitcnt lgkmcnt(0)
	v_add_f32_e32 v82, v82, v83
	ds_bpermute_b32 v83, v75, v82
	s_waitcnt lgkmcnt(0)
	v_add_f32_e32 v82, v82, v83
	ds_bpermute_b32 v83, v76, v82
	s_waitcnt lgkmcnt(0)
; DI unsigned pk2(float lo, float hi) { return pg8::cvt_pk_bf16(lo, hi); }
; DI void prenorm_rows(const float* X, const float* gvec, const float* ada, int sh_off, int sc_off, bf16* U, int row_lo, int row_hi, int gw, int ngw, int lane) {
;     ...
;         f32x4 v[4]; float ss = 0.f;
; #pragma unroll
;         for (int j = 0; j < 4; ++j) v[j] = nx[j];
;         if (m + 1 < m1) {
; #pragma unroll
;             for (int j = 0; j < 4; ++j) nx[j] = *(const f32x4*)(X + (size_t)(m + 1) * 1024 + 4 * lane + 256 * j);
;         }
;         if (b != curb) { curb = b;
; #pragma unroll
;             for (int j = 0; j < 4; ++j) { const int col = 4 * lane + 256 * j; const f32x4 g = *(const f32x4*)(gvec + col), sc = *(const f32x4*)(ada + (size_t)b * 6144 + sc_off + col);
;                 mul[j] = g * (sc + 1.0f); add[j] = *(const f32x4*)(ada + (size_t)b * 6144 + sh_off + col); } }
; #pragma unroll
;         for (int j = 0; j < 4; ++j) ss += (v[j][0] * v[j][0] + v[j][1] * v[j][1]) + (v[j][2] * v[j][2] + v[j][3] * v[j][3]);
;         const float rstd = rsqrtf(wave_sum(ss) * (1.0f / 1024.0f) + 1e-6f);
; #pragma unroll
;         for (int j = 0; j < 4; ++j) { const f32x4 o = (v[j] * rstd) * mul[j] + add[j]; v2u w; w.x = pk2(o[0], o[1]); w.y = pk2(o[2], o[3]);
;             *(v2u*)(U + (size_t)m * 1024 + 4 * lane + 256 * j) = w; }
	v_add_f32_e32 v82, v82, v83
	v_fmamk_f32 v82, v82, 0x3a800000, v81
	v_mul_f32_e32 v83, 0x4b800000, v82
	v_cmp_gt_f32_e32 vcc, s7, v82
	s_nop 1
	v_cndmask_b32_e32 v82, v82, v83, vcc
	v_rsq_f32_e32 v82, v82
	s_nop 0
	v_mul_f32_e32 v83, 0x45800000, v82
	v_cndmask_b32_e32 v82, v82, v83, vcc
	v_pk_mul_f32 v[164:165], v[164:165], v[82:83] op_sel_hi:[1,0]
	v_pk_mul_f32 v[160:161], v[160:161], v[82:83] op_sel_hi:[1,0]
	v_pk_mul_f32 v[156:157], v[156:157], v[82:83] op_sel_hi:[1,0]
	v_pk_mul_f32 v[152:153], v[152:153], v[82:83] op_sel_hi:[1,0]
	v_pk_mul_f32 v[166:167], v[166:167], v[82:83] op_sel_hi:[1,0]
	v_pk_mul_f32 v[162:163], v[162:163], v[82:83] op_sel_hi:[1,0]
	v_pk_fma_f32 v[164:165], v[48:49], v[164:165], v[28:29]
	v_pk_fma_f32 v[160:161], v[52:53], v[160:161], v[24:25]
	v_pk_mul_f32 v[158:159], v[158:159], v[82:83] op_sel_hi:[1,0]
	v_pk_fma_f32 v[156:157], v[56:57], v[156:157], v[20:21]
	v_pk_mul_f32 v[154:155], v[154:155], v[82:83] op_sel_hi:[1,0]
	v_pk_fma_f32 v[152:153], v[60:61], v[152:153], v[16:17]
	v_pk_fma_f32 v[166:167], v[50:51], v[166:167], v[30:31]
	v_pk_fma_f32 v[162:163], v[54:55], v[162:163], v[26:27]
	v_cvt_pk_bf16_f32 v164, v164, v165
	v_cvt_pk_bf16_f32 v165, v166, v167
	global_store_dwordx2 v[66:67], v[164:165], off
	v_cvt_pk_bf16_f32 v160, v160, v161
	v_cvt_pk_bf16_f32 v161, v162, v163
	global_store_dwordx2 v[66:67], v[160:161], off offset:512
	v_pk_fma_f32 v[158:159], v[58:59], v[158:159], v[22:23]
	v_cvt_pk_bf16_f32 v156, v156, v157
	v_pk_fma_f32 v[154:155], v[62:63], v[154:155], v[18:19]
	v_cvt_pk_bf16_f32 v157, v158, v159
	global_store_dwordx2 v[66:67], v[156:157], off offset:1024
	v_cvt_pk_bf16_f32 v152, v152, v153
	v_cvt_pk_bf16_f32 v153, v154, v155
	global_store_dwordx2 v[66:67], v[152:153], off offset:1536
	v_lshl_add_u64 v[66:67], v[66:67], 0, s[2:3]
	s_waitcnt vmcnt(16)
	v_pk_mul_f32 v[82:83], v[176:177], v[176:177]
	v_pk_mul_f32 v[84:85], v[178:179], v[178:179]
	v_pk_mul_f32 v[86:87], v[180:181], v[180:181]
	v_pk_mul_f32 v[88:89], v[182:183], v[182:183]
	v_mov_b32_e32 v90, v86
	v_mov_b32_e32 v91, v89
	v_pk_mov_b32 v[86:87], v[86:87], v[88:89] op_sel:[1,0]
	v_mov_b32_e32 v88, v82
	v_mov_b32_e32 v89, v85
	v_pk_mov_b32 v[82:83], v[82:83], v[84:85] op_sel:[1,0]
	v_pk_add_f32 v[86:87], v[86:87], v[90:91]
	v_pk_add_f32 v[82:83], v[82:83], v[88:89]
	v_pk_add_f32 v[86:87], v[86:87], v[86:87] op_sel_hi:[0,1]
	v_pk_add_f32 v[82:83], v[82:83], v[82:83] op_sel_hi:[0,1]
	v_mul_f32_e32 v82, v172, v172
	v_pk_fma_f32 v[84:85], v[172:173], v[172:173], v[82:83] op_sel_hi:[1,1,0]
	v_mul_f32_e32 v82, v174, v174
	v_pk_fma_f32 v[88:89], v[174:175], v[174:175], v[82:83] op_sel_hi:[1,1,0]
	v_mul_f32_e32 v84, v168, v168
	v_mul_f32_e32 v88, v169, v169
	v_mul_f32_e32 v86, v170, v170
	v_mul_f32_e32 v82, v171, v171
	v_pk_add_f32 v[84:85], v[84:85], v[88:89]
	v_pk_add_f32 v[82:83], v[86:87], v[82:83]
	v_pk_add_f32 v[82:83], v[84:85], v[82:83]
	v_add_f32_e32 v82, v82, v83
	ds_bpermute_b32 v83, v71, v82
	s_waitcnt lgkmcnt(0)
	v_add_f32_e32 v82, v82, v83
	ds_bpermute_b32 v83, v72, v82
	s_waitcnt lgkmcnt(0)
	v_add_f32_e32 v82, v82, v83
	ds_bpermute_b32 v83, v73, v82
	s_waitcnt lgkmcnt(0)
	v_add_f32_e32 v82, v82, v83
	ds_bpermute_b32 v83, v74, v82
	s_waitcnt lgkmcnt(0)
	v_add_f32_e32 v82, v82, v83
	ds_bpermute_b32 v83, v75, v82
	s_waitcnt lgkmcnt(0)
	v_add_f32_e32 v82, v82, v83
	ds_bpermute_b32 v83, v76, v82
	s_waitcnt lgkmcnt(0)
; DI unsigned pk2(float lo, float hi) { return pg8::cvt_pk_bf16(lo, hi); }
; DI void prenorm_rows(const float* X, const float* gvec, const float* ada, int sh_off, int sc_off, bf16* U, int row_lo, int row_hi, int gw, int ngw, int lane) {
;     ...
;         f32x4 v[4]; float ss = 0.f;
; #pragma unroll
;         for (int j = 0; j < 4; ++j) v[j] = nx[j];
;         if (m + 1 < m1) {
; #pragma unroll
;             for (int j = 0; j < 4; ++j) nx[j] = *(const f32x4*)(X + (size_t)(m + 1) * 1024 + 4 * lane + 256 * j);
;         }
;         if (b != curb) { curb = b;
; #pragma unroll
;             for (int j = 0; j < 4; ++j) { const int col = 4 * lane + 256 * j; const f32x4 g = *(const f32x4*)(gvec + col), sc = *(const f32x4*)(ada + (size_t)b * 6144 + sc_off + col);
;                 mul[j] = g * (sc + 1.0f); add[j] = *(const f32x4*)(ada + (size_t)b * 6144 + sh_off + col); } }
; #pragma unroll
;         for (int j = 0; j < 4; ++j) ss += (v[j][0] * v[j][0] + v[j][1] * v[j][1]) + (v[j][2] * v[j][2] + v[j][3] * v[j][3]);
;         const float rstd = rsqrtf(wave_sum(ss) * (1.0f / 1024.0f) + 1e-6f);
; #pragma unroll
;         for (int j = 0; j < 4; ++j) { const f32x4 o = (v[j] * rstd) * mul[j] + add[j]; v2u w; w.x = pk2(o[0], o[1]); w.y = pk2(o[2], o[3]);
;             *(v2u*)(U + (size_t)m * 1024 + 4 * lane + 256 * j) = w; }
	v_add_f32_e32 v82, v82, v83
	v_fmamk_f32 v82, v82, 0x3a800000, v81
	v_mul_f32_e32 v83, 0x4b800000, v82
	v_cmp_gt_f32_e32 vcc, s7, v82
	s_nop 1
	v_cndmask_b32_e32 v82, v82, v83, vcc
	v_rsq_f32_e32 v82, v82
	s_nop 0
	v_mul_f32_e32 v83, 0x45800000, v82
	v_cndmask_b32_e32 v82, v82, v83, vcc
	v_pk_mul_f32 v[180:181], v[180:181], v[82:83] op_sel_hi:[1,0]
	v_pk_mul_f32 v[176:177], v[176:177], v[82:83] op_sel_hi:[1,0]
	v_pk_mul_f32 v[172:173], v[172:173], v[82:83] op_sel_hi:[1,0]
	v_pk_mul_f32 v[168:169], v[168:169], v[82:83] op_sel_hi:[1,0]
	v_pk_mul_f32 v[182:183], v[182:183], v[82:83] op_sel_hi:[1,0]
	v_pk_mul_f32 v[178:179], v[178:179], v[82:83] op_sel_hi:[1,0]
	v_pk_fma_f32 v[180:181], v[48:49], v[180:181], v[28:29]
	v_pk_fma_f32 v[176:177], v[52:53], v[176:177], v[24:25]
	v_pk_mul_f32 v[174:175], v[174:175], v[82:83] op_sel_hi:[1,0]
	v_pk_fma_f32 v[172:173], v[56:57], v[172:173], v[20:21]
	v_pk_mul_f32 v[170:171], v[170:171], v[82:83] op_sel_hi:[1,0]
	v_pk_fma_f32 v[168:169], v[60:61], v[168:169], v[16:17]
	v_pk_fma_f32 v[182:183], v[50:51], v[182:183], v[30:31]
	v_pk_fma_f32 v[178:179], v[54:55], v[178:179], v[26:27]
	v_cvt_pk_bf16_f32 v180, v180, v181
	v_cvt_pk_bf16_f32 v181, v182, v183
	global_store_dwordx2 v[66:67], v[180:181], off
	v_cvt_pk_bf16_f32 v176, v176, v177
	v_cvt_pk_bf16_f32 v177, v178, v179
	global_store_dwordx2 v[66:67], v[176:177], off offset:512
	v_pk_fma_f32 v[174:175], v[58:59], v[174:175], v[22:23]
	v_cvt_pk_bf16_f32 v172, v172, v173
	v_pk_fma_f32 v[170:171], v[62:63], v[170:171], v[18:19]
	v_cvt_pk_bf16_f32 v173, v174, v175
	global_store_dwordx2 v[66:67], v[172:173], off offset:1024
	v_cvt_pk_bf16_f32 v168, v168, v169
	v_cvt_pk_bf16_f32 v169, v170, v171
	global_store_dwordx2 v[66:67], v[168:169], off offset:1536
	v_lshl_add_u64 v[66:67], v[66:67], 0, s[2:3]
	s_waitcnt vmcnt(12)
	v_pk_mul_f32 v[82:83], v[40:41], v[40:41]
	v_pk_mul_f32 v[84:85], v[42:43], v[42:43]
	v_pk_mul_f32 v[86:87], v[44:45], v[44:45]
	v_pk_mul_f32 v[88:89], v[46:47], v[46:47]
	v_mov_b32_e32 v90, v86
	v_mov_b32_e32 v91, v89
	v_pk_mov_b32 v[86:87], v[86:87], v[88:89] op_sel:[1,0]
	v_mov_b32_e32 v88, v82
	v_mov_b32_e32 v89, v85
	v_pk_mov_b32 v[82:83], v[82:83], v[84:85] op_sel:[1,0]
	v_pk_add_f32 v[86:87], v[86:87], v[90:91]
	v_pk_add_f32 v[82:83], v[82:83], v[88:89]
	v_pk_add_f32 v[86:87], v[86:87], v[86:87] op_sel_hi:[0,1]
	v_pk_add_f32 v[82:83], v[82:83], v[82:83] op_sel_hi:[0,1]
	v_mul_f32_e32 v82, v36, v36
	v_pk_fma_f32 v[84:85], v[36:37], v[36:37], v[82:83] op_sel_hi:[1,1,0]
	v_mul_f32_e32 v82, v38, v38
	v_pk_fma_f32 v[88:89], v[38:39], v[38:39], v[82:83] op_sel_hi:[1,1,0]
	v_mul_f32_e32 v84, v32, v32
	v_mul_f32_e32 v88, v33, v33
	v_mul_f32_e32 v86, v34, v34
	v_mul_f32_e32 v82, v35, v35
	v_pk_add_f32 v[84:85], v[84:85], v[88:89]
	v_pk_add_f32 v[82:83], v[86:87], v[82:83]
	v_pk_add_f32 v[82:83], v[84:85], v[82:83]
	v_add_f32_e32 v82, v82, v83
	ds_bpermute_b32 v83, v71, v82
	s_waitcnt lgkmcnt(0)
	v_add_f32_e32 v82, v82, v83
	ds_bpermute_b32 v83, v72, v82
	s_waitcnt lgkmcnt(0)
	v_add_f32_e32 v82, v82, v83
	ds_bpermute_b32 v83, v73, v82
	s_waitcnt lgkmcnt(0)
	v_add_f32_e32 v82, v82, v83
	ds_bpermute_b32 v83, v74, v82
	s_waitcnt lgkmcnt(0)
	v_add_f32_e32 v82, v82, v83
	ds_bpermute_b32 v83, v75, v82
	s_waitcnt lgkmcnt(0)
	v_add_f32_e32 v82, v82, v83
	ds_bpermute_b32 v83, v76, v82
	s_waitcnt lgkmcnt(0)
	v_add_f32_e32 v82, v82, v83
	v_fmamk_f32 v82, v82, 0x3a800000, v81
	v_mul_f32_e32 v83, 0x4b800000, v82
	v_cmp_gt_f32_e32 vcc, s7, v82
	s_nop 1
	v_cndmask_b32_e32 v82, v82, v83, vcc
	v_rsq_f32_e32 v82, v82
	s_nop 0
	v_mul_f32_e32 v83, 0x45800000, v82
	v_cndmask_b32_e32 v82, v82, v83, vcc
	v_pk_mul_f32 v[44:45], v[44:45], v[82:83] op_sel_hi:[1,0]
	v_pk_mul_f32 v[40:41], v[40:41], v[82:83] op_sel_hi:[1,0]
	v_pk_mul_f32 v[36:37], v[36:37], v[82:83] op_sel_hi:[1,0]
	v_pk_mul_f32 v[32:33], v[32:33], v[82:83] op_sel_hi:[1,0]
	v_pk_mul_f32 v[46:47], v[46:47], v[82:83] op_sel_hi:[1,0]
	v_pk_mul_f32 v[42:43], v[42:43], v[82:83] op_sel_hi:[1,0]
	v_pk_fma_f32 v[44:45], v[48:49], v[44:45], v[28:29]
	v_pk_fma_f32 v[40:41], v[52:53], v[40:41], v[24:25]
	v_pk_mul_f32 v[38:39], v[38:39], v[82:83] op_sel_hi:[1,0]
	v_pk_fma_f32 v[36:37], v[56:57], v[36:37], v[20:21]
	v_pk_mul_f32 v[34:35], v[34:35], v[82:83] op_sel_hi:[1,0]
	v_pk_fma_f32 v[32:33], v[60:61], v[32:33], v[16:17]
	v_pk_fma_f32 v[46:47], v[50:51], v[46:47], v[30:31]
	v_pk_fma_f32 v[42:43], v[54:55], v[42:43], v[26:27]
	v_cvt_pk_bf16_f32 v44, v44, v45
	v_cvt_pk_bf16_f32 v45, v46, v47
	global_store_dwordx2 v[66:67], v[44:45], off
	v_cvt_pk_bf16_f32 v40, v40, v41
	v_cvt_pk_bf16_f32 v41, v42, v43
	global_store_dwordx2 v[66:67], v[40:41], off offset:512
	v_pk_fma_f32 v[38:39], v[58:59], v[38:39], v[22:23]
	v_cvt_pk_bf16_f32 v36, v36, v37
	v_pk_fma_f32 v[34:35], v[62:63], v[34:35], v[18:19]
	v_cvt_pk_bf16_f32 v37, v38, v39
	global_store_dwordx2 v[66:67], v[36:37], off offset:1024
	v_cvt_pk_bf16_f32 v32, v32, v33
	v_cvt_pk_bf16_f32 v33, v34, v35
	global_store_dwordx2 v[66:67], v[32:33], off offset:1536
	v_lshl_add_u64 v[66:67], v[66:67], 0, s[2:3]
